# w_out/w_up f32->bf16 conversion moved from phase 0 into idle waves of the scan/attention phase (work queue, 2 tiles of loads in flight), w_down conversion into idle blocks of the up-projection tail; p
# speedup vs baseline: 1.0235x; 1.0235x over previous
.LBB0_239:
	s_branch .Ldc8_entry

.Ldc4_entry:
	s_mov_b64 exec, -1
	v_readlane_b32 s0, v250, 0
	v_readlane_b32 s1, v250, 1
	v_mbcnt_lo_u32_b32 v3, -1, 0
	v_mbcnt_hi_u32_b32 v3, -1, v3
	s_sub_u32 s0, s0, 0x120
	s_subb_u32 s1, s1, 0
	s_load_dwordx4 s[80:83], s[0:1], 0xe0
	s_load_dwordx2 s[64:65], s[0:1], 0x68
	s_add_u32 s70, s24, 0x5016740
	s_addc_u32 s71, s25, 0
	v_readfirstlane_b32 s84, v159
	v_mov_b32_e32 v9, 1
	v_lshrrev_b32_e32 v7, 5, v3
	v_and_b32_e32 v8, 31, v3
	s_lshr_b32 s84, s84, 6
	s_mul_i32 s72, s84, 0x4800
	s_cmp_gt_u32 s84, 5
	s_cselect_b32 s85, 0xffffc0c0, 0
	s_add_i32 s72, s72, s85
	v_lshlrev_b32_e32 v8, 2, v8
	v_lshrrev_b32_e32 v10, 3, v3
	v_and_b32_e32 v11, 7, v3
	v_mul_u32_u24_e32 v5, 0x84, v7
	v_add3_u32 v5, v5, v8, s72
	v_mul_u32_u24_e32 v6, 0x420, v11
	v_lshl_add_u32 v6, v10, 2, v6
	v_add_u32_e32 v6, s72, v6
	v_lshlrev_b32_e32 v11, 4, v11
	s_mov_b32 s58, 0
	s_mov_b32 s59, 0
	s_waitcnt lgkmcnt(0)
	s_mov_b64 exec, 1
	global_atomic_add v2, v1, v9, s[70:71] sc0
	s_mov_b64 exec, -1
	s_waitcnt vmcnt(0)
	s_cmp_lt_u32 s58, s59
	s_cbranch_scc1 .Ldc4_n0
	v_readfirstlane_b32 s58, v2
	s_lshl_b32 s58, s58, 3
	s_cmp_ge_u32 s58, 0x3400
	s_cbranch_scc1 .Ldc4_done
	s_add_u32 s59, s58, 8
	s_mov_b64 exec, 1
	global_atomic_add v2, v1, v9, s[70:71] sc0
	s_mov_b64 exec, -1
.Ldc4_n0:
	s_mov_b32 s73, s58
	s_add_u32 s58, s58, 1
	s_cmp_lt_u32 s73, 0x800
	s_cbranch_scc0 .Ldc4_i1_r1
	s_mov_b64 s[74:75], s[80:81]
	s_mov_b64 s[76:77], s[24:25]
	s_mov_b32 s78, 0x2000
	s_mov_b32 s79, 0x1000
	s_lshr_b32 s84, s73, 6
	s_and_b32 s85, s73, 63
	s_branch .Ldc4_i1_d
.Ldc4_i1_r1:
	s_mov_b64 s[74:75], s[82:83]
	s_add_u32 s76, s24, 0x800000
	s_addc_u32 s77, s25, 0
	s_mov_b32 s78, 0xb000
	s_mov_b32 s79, 0x1000
	s_sub_u32 s86, s73, 0x800
	s_mul_hi_u32 s84, s86, 0xba2e8c
	s_mul_i32 s85, s84, 0x160
	s_sub_u32 s85, s86, s85
.Ldc4_i1_d:
	s_lshl_b32 s84, s84, 6
	s_lshl_b32 s85, s85, 5
	s_mul_i32 s86, s84, s78
	s_lshl_b32 s36, s85, 2
	s_add_u32 s86, s86, s36
	s_add_u32 s74, s74, s86
	s_addc_u32 s75, s75, 0
	s_mul_i32 s86, s85, s79
	s_lshl_b32 s36, s84, 1
	s_add_u32 s86, s86, s36
	s_add_u32 s40, s76, s86
	s_addc_u32 s41, s77, 0
	s_lshl_b32 s39, s79, 3
	v_mad_u32_u24 v12, v10, s79, v11
	v_mad_u32_u24 v4, v7, s78, v8
	s_lshl_b32 s36, s78, 1
	global_load_dword v16, v4, s[74:75] nt
	v_add_u32_e32 v4, s36, v4
	global_load_dword v17, v4, s[74:75] nt
	v_add_u32_e32 v4, s36, v4
	global_load_dword v18, v4, s[74:75] nt
	v_add_u32_e32 v4, s36, v4
	global_load_dword v19, v4, s[74:75] nt
	v_add_u32_e32 v4, s36, v4
	global_load_dword v20, v4, s[74:75] nt
	v_add_u32_e32 v4, s36, v4
	global_load_dword v21, v4, s[74:75] nt
	v_add_u32_e32 v4, s36, v4
	global_load_dword v22, v4, s[74:75] nt
	v_add_u32_e32 v4, s36, v4
	global_load_dword v23, v4, s[74:75] nt
	v_add_u32_e32 v4, s36, v4
	global_load_dword v24, v4, s[74:75] nt
	v_add_u32_e32 v4, s36, v4
	global_load_dword v25, v4, s[74:75] nt
	v_add_u32_e32 v4, s36, v4
	global_load_dword v26, v4, s[74:75] nt
	v_add_u32_e32 v4, s36, v4
	global_load_dword v27, v4, s[74:75] nt
	v_add_u32_e32 v4, s36, v4
	global_load_dword v28, v4, s[74:75] nt
	v_add_u32_e32 v4, s36, v4
	global_load_dword v29, v4, s[74:75] nt
	v_add_u32_e32 v4, s36, v4
	global_load_dword v30, v4, s[74:75] nt
	v_add_u32_e32 v4, s36, v4
	global_load_dword v31, v4, s[74:75] nt
	v_add_u32_e32 v4, s36, v4
	s_waitcnt vmcnt(46)
	global_load_dword v32, v4, s[74:75] nt
	v_add_u32_e32 v4, s36, v4
	global_load_dword v33, v4, s[74:75] nt
	v_add_u32_e32 v4, s36, v4
	global_load_dword v34, v4, s[74:75] nt
	v_add_u32_e32 v4, s36, v4
	global_load_dword v35, v4, s[74:75] nt
	v_add_u32_e32 v4, s36, v4
	global_load_dword v36, v4, s[74:75] nt
	v_add_u32_e32 v4, s36, v4
	global_load_dword v37, v4, s[74:75] nt
	v_add_u32_e32 v4, s36, v4
	global_load_dword v38, v4, s[74:75] nt
	v_add_u32_e32 v4, s36, v4
	global_load_dword v39, v4, s[74:75] nt
	v_add_u32_e32 v4, s36, v4
	global_load_dword v40, v4, s[74:75] nt
	v_add_u32_e32 v4, s36, v4
	global_load_dword v41, v4, s[74:75] nt
	v_add_u32_e32 v4, s36, v4
	global_load_dword v42, v4, s[74:75] nt
	v_add_u32_e32 v4, s36, v4
	global_load_dword v43, v4, s[74:75] nt
	v_add_u32_e32 v4, s36, v4
	global_load_dword v44, v4, s[74:75] nt
	v_add_u32_e32 v4, s36, v4
	global_load_dword v45, v4, s[74:75] nt
	v_add_u32_e32 v4, s36, v4
	global_load_dword v46, v4, s[74:75] nt
	v_add_u32_e32 v4, s36, v4
	global_load_dword v47, v4, s[74:75] nt
	s_cmp_lt_u32 s58, s59
	s_cbranch_scc1 .Ldc4_n2
	v_readfirstlane_b32 s58, v2
	s_lshl_b32 s58, s58, 3
	s_cmp_ge_u32 s58, 0x3400
	s_cbranch_scc1 .Ldc4_fin0
	s_add_u32 s59, s58, 8
	s_mov_b64 exec, 1
	global_atomic_add v2, v1, v9, s[70:71] sc0
	s_mov_b64 exec, -1

.Ldc4_i3_d:
	s_lshl_b32 s84, s84, 6
	s_lshl_b32 s85, s85, 5
	s_mul_i32 s86, s84, s78
	s_lshl_b32 s36, s85, 2
	s_add_u32 s86, s86, s36
	s_add_u32 s74, s74, s86
	s_addc_u32 s75, s75, 0
	s_mul_i32 s86, s85, s79
	s_lshl_b32 s36, s84, 1
	s_add_u32 s86, s86, s36
	s_add_u32 s54, s76, s86
	s_addc_u32 s55, s77, 0
	s_lshl_b32 s57, s79, 3
	v_mad_u32_u24 v13, v10, s79, v11
	v_mad_u32_u24 v4, v7, s78, v8
	s_lshl_b32 s36, s78, 1
	global_load_dword v48, v4, s[74:75] nt
	v_add_u32_e32 v4, s36, v4
	global_load_dword v49, v4, s[74:75] nt
	v_add_u32_e32 v4, s36, v4
	global_load_dword v50, v4, s[74:75] nt
	v_add_u32_e32 v4, s36, v4
	global_load_dword v51, v4, s[74:75] nt
	v_add_u32_e32 v4, s36, v4
	global_load_dword v52, v4, s[74:75] nt
	v_add_u32_e32 v4, s36, v4
	global_load_dword v53, v4, s[74:75] nt
	v_add_u32_e32 v4, s36, v4
	global_load_dword v54, v4, s[74:75] nt
	v_add_u32_e32 v4, s36, v4
	global_load_dword v55, v4, s[74:75] nt
	v_add_u32_e32 v4, s36, v4
	global_load_dword v56, v4, s[74:75] nt
	v_add_u32_e32 v4, s36, v4
	global_load_dword v57, v4, s[74:75] nt
	v_add_u32_e32 v4, s36, v4
	global_load_dword v58, v4, s[74:75] nt
	v_add_u32_e32 v4, s36, v4
	global_load_dword v59, v4, s[74:75] nt
	v_add_u32_e32 v4, s36, v4
	global_load_dword v60, v4, s[74:75] nt
	v_add_u32_e32 v4, s36, v4
	global_load_dword v61, v4, s[74:75] nt
	v_add_u32_e32 v4, s36, v4
	global_load_dword v62, v4, s[74:75] nt
	v_add_u32_e32 v4, s36, v4
	global_load_dword v63, v4, s[74:75] nt
	v_add_u32_e32 v4, s36, v4
	s_waitcnt vmcnt(46)
	global_load_dword v64, v4, s[74:75] nt
	v_add_u32_e32 v4, s36, v4
	global_load_dword v65, v4, s[74:75] nt
	v_add_u32_e32 v4, s36, v4
	global_load_dword v66, v4, s[74:75] nt
	v_add_u32_e32 v4, s36, v4
	global_load_dword v67, v4, s[74:75] nt
	v_add_u32_e32 v4, s36, v4
	global_load_dword v68, v4, s[74:75] nt
	v_add_u32_e32 v4, s36, v4
	global_load_dword v69, v4, s[74:75] nt
	v_add_u32_e32 v4, s36, v4
	global_load_dword v70, v4, s[74:75] nt
	v_add_u32_e32 v4, s36, v4
	global_load_dword v71, v4, s[74:75] nt
	v_add_u32_e32 v4, s36, v4
	global_load_dword v72, v4, s[74:75] nt
	v_add_u32_e32 v4, s36, v4
	global_load_dword v73, v4, s[74:75] nt
	v_add_u32_e32 v4, s36, v4
	global_load_dword v74, v4, s[74:75] nt
	v_add_u32_e32 v4, s36, v4
	global_load_dword v75, v4, s[74:75] nt
	v_add_u32_e32 v4, s36, v4
	global_load_dword v76, v4, s[74:75] nt
	v_add_u32_e32 v4, s36, v4
	global_load_dword v77, v4, s[74:75] nt
	v_add_u32_e32 v4, s36, v4
	global_load_dword v78, v4, s[74:75] nt
	v_add_u32_e32 v4, s36, v4
	global_load_dword v79, v4, s[74:75] nt
	s_waitcnt vmcnt(32)
	ds_write_b32 v5, v16 offset:0
	ds_write_b32 v5, v17 offset:264
	ds_write_b32 v5, v18 offset:528
	ds_write_b32 v5, v19 offset:792
	ds_write_b32 v5, v20 offset:1056
	ds_write_b32 v5, v21 offset:1320
	ds_write_b32 v5, v22 offset:1584
	ds_write_b32 v5, v23 offset:1848
	ds_write_b32 v5, v24 offset:2112
	ds_write_b32 v5, v25 offset:2376
	ds_write_b32 v5, v26 offset:2640
	ds_write_b32 v5, v27 offset:2904
	ds_write_b32 v5, v28 offset:3168
	ds_write_b32 v5, v29 offset:3432
	ds_write_b32 v5, v30 offset:3696
	ds_write_b32 v5, v31 offset:3960
	ds_write_b32 v5, v32 offset:4224
	ds_write_b32 v5, v33 offset:4488
	ds_write_b32 v5, v34 offset:4752
	ds_write_b32 v5, v35 offset:5016
	ds_write_b32 v5, v36 offset:5280
	ds_write_b32 v5, v37 offset:5544
	ds_write_b32 v5, v38 offset:5808
	ds_write_b32 v5, v39 offset:6072
	ds_write_b32 v5, v40 offset:6336
	ds_write_b32 v5, v41 offset:6600
	ds_write_b32 v5, v42 offset:6864
	ds_write_b32 v5, v43 offset:7128
	ds_write_b32 v5, v44 offset:7392
	ds_write_b32 v5, v45 offset:7656
	ds_write_b32 v5, v46 offset:7920
	ds_write_b32 v5, v47 offset:8184
	s_waitcnt lgkmcnt(0)
	ds_read2_b32 v[80:81], v6 offset0:0 offset1:33
	ds_read2_b32 v[82:83], v6 offset0:66 offset1:99
	ds_read2_b32 v[84:85], v6 offset0:132 offset1:165
	ds_read2_b32 v[86:87], v6 offset0:198 offset1:231
	ds_read2_b32 v[88:89], v6 offset0:8 offset1:41
	ds_read2_b32 v[90:91], v6 offset0:74 offset1:107
	ds_read2_b32 v[92:93], v6 offset0:140 offset1:173
	ds_read2_b32 v[94:95], v6 offset0:206 offset1:239
	ds_read2_b32 v[136:137], v6 offset0:16 offset1:49
	ds_read2_b32 v[138:139], v6 offset0:82 offset1:115
	ds_read2_b32 v[140:141], v6 offset0:148 offset1:181
	ds_read2_b32 v[142:143], v6 offset0:214 offset1:247
	ds_read2_b32 v[144:145], v6 offset0:24 offset1:57
	ds_read2_b32 v[146:147], v6 offset0:90 offset1:123
	ds_read2_b32 v[148:149], v6 offset0:156 offset1:189
	ds_read2_b32 v[150:151], v6 offset0:222 offset1:255
	s_waitcnt lgkmcnt(12)
	v_cvt_pk_bf16_f32 v96, v80, v81
	v_cvt_pk_bf16_f32 v97, v82, v83
	v_cvt_pk_bf16_f32 v98, v84, v85
	v_cvt_pk_bf16_f32 v99, v86, v87
	global_store_dwordx4 v12, v[96:99], s[40:41]
	v_add_u32_e32 v12, s39, v12
	s_waitcnt lgkmcnt(8)
	v_cvt_pk_bf16_f32 v100, v88, v89
	v_cvt_pk_bf16_f32 v101, v90, v91
	v_cvt_pk_bf16_f32 v102, v92, v93
	v_cvt_pk_bf16_f32 v103, v94, v95
	global_store_dwordx4 v12, v[100:103], s[40:41]
	v_add_u32_e32 v12, s39, v12
	s_waitcnt lgkmcnt(4)
	v_cvt_pk_bf16_f32 v104, v136, v137
	v_cvt_pk_bf16_f32 v105, v138, v139
	v_cvt_pk_bf16_f32 v106, v140, v141
	v_cvt_pk_bf16_f32 v107, v142, v143
	global_store_dwordx4 v12, v[104:107], s[40:41]
	v_add_u32_e32 v12, s39, v12
	s_waitcnt lgkmcnt(0)
	v_cvt_pk_bf16_f32 v108, v144, v145
	v_cvt_pk_bf16_f32 v109, v146, v147
	v_cvt_pk_bf16_f32 v110, v148, v149
	v_cvt_pk_bf16_f32 v111, v150, v151
	global_store_dwordx4 v12, v[108:111], s[40:41]
	s_cmp_lt_u32 s58, s59
	s_cbranch_scc1 .Ldc4_n4
	v_readfirstlane_b32 s58, v2
	s_lshl_b32 s58, s58, 3
	s_cmp_ge_u32 s58, 0x3400
	s_cbranch_scc1 .Ldc4_fin1
	s_add_u32 s59, s58, 8
	s_mov_b64 exec, 1
	global_atomic_add v2, v1, v9, s[70:71] sc0
	s_mov_b64 exec, -1
.Ldc4_n4:
	s_mov_b32 s73, s58
	s_add_u32 s58, s58, 1
.Ldc4_loop:
	s_cmp_lt_u32 s73, 0x800
	s_cbranch_scc0 .Ldc4_i5_r1
	s_mov_b64 s[74:75], s[80:81]
	s_mov_b64 s[76:77], s[24:25]
	s_mov_b32 s78, 0x2000
	s_mov_b32 s79, 0x1000
	s_lshr_b32 s84, s73, 6
	s_and_b32 s85, s73, 63
	s_branch .Ldc4_i5_d

.Ldc4_i5_d:
	s_lshl_b32 s84, s84, 6
	s_lshl_b32 s85, s85, 5
	s_mul_i32 s86, s84, s78
	s_lshl_b32 s36, s85, 2
	s_add_u32 s86, s86, s36
	s_add_u32 s74, s74, s86
	s_addc_u32 s75, s75, 0
	s_mul_i32 s86, s85, s79
	s_lshl_b32 s36, s84, 1
	s_add_u32 s86, s86, s36
	s_add_u32 s40, s76, s86
	s_addc_u32 s41, s77, 0
	s_lshl_b32 s39, s79, 3
	v_mad_u32_u24 v12, v10, s79, v11
	v_mad_u32_u24 v4, v7, s78, v8
	s_lshl_b32 s36, s78, 1
	global_load_dword v16, v4, s[74:75] nt
	v_add_u32_e32 v4, s36, v4
	global_load_dword v17, v4, s[74:75] nt
	v_add_u32_e32 v4, s36, v4
	global_load_dword v18, v4, s[74:75] nt
	v_add_u32_e32 v4, s36, v4
	global_load_dword v19, v4, s[74:75] nt
	v_add_u32_e32 v4, s36, v4
	global_load_dword v20, v4, s[74:75] nt
	v_add_u32_e32 v4, s36, v4
	global_load_dword v21, v4, s[74:75] nt
	v_add_u32_e32 v4, s36, v4
	global_load_dword v22, v4, s[74:75] nt
	v_add_u32_e32 v4, s36, v4
	global_load_dword v23, v4, s[74:75] nt
	v_add_u32_e32 v4, s36, v4
	global_load_dword v24, v4, s[74:75] nt
	v_add_u32_e32 v4, s36, v4
	global_load_dword v25, v4, s[74:75] nt
	v_add_u32_e32 v4, s36, v4
	global_load_dword v26, v4, s[74:75] nt
	v_add_u32_e32 v4, s36, v4
	global_load_dword v27, v4, s[74:75] nt
	v_add_u32_e32 v4, s36, v4
	global_load_dword v28, v4, s[74:75] nt
	v_add_u32_e32 v4, s36, v4
	global_load_dword v29, v4, s[74:75] nt
	v_add_u32_e32 v4, s36, v4
	global_load_dword v30, v4, s[74:75] nt
	v_add_u32_e32 v4, s36, v4
	global_load_dword v31, v4, s[74:75] nt
	v_add_u32_e32 v4, s36, v4
	s_waitcnt vmcnt(46)
	global_load_dword v32, v4, s[74:75] nt
	v_add_u32_e32 v4, s36, v4
	global_load_dword v33, v4, s[74:75] nt
	v_add_u32_e32 v4, s36, v4
	global_load_dword v34, v4, s[74:75] nt
	v_add_u32_e32 v4, s36, v4
	global_load_dword v35, v4, s[74:75] nt
	v_add_u32_e32 v4, s36, v4
	global_load_dword v36, v4, s[74:75] nt
	v_add_u32_e32 v4, s36, v4
	global_load_dword v37, v4, s[74:75] nt
	v_add_u32_e32 v4, s36, v4
	global_load_dword v38, v4, s[74:75] nt
	v_add_u32_e32 v4, s36, v4
	global_load_dword v39, v4, s[74:75] nt
	v_add_u32_e32 v4, s36, v4
	global_load_dword v40, v4, s[74:75] nt
	v_add_u32_e32 v4, s36, v4
	global_load_dword v41, v4, s[74:75] nt
	v_add_u32_e32 v4, s36, v4
	global_load_dword v42, v4, s[74:75] nt
	v_add_u32_e32 v4, s36, v4
	global_load_dword v43, v4, s[74:75] nt
	v_add_u32_e32 v4, s36, v4
	global_load_dword v44, v4, s[74:75] nt
	v_add_u32_e32 v4, s36, v4
	global_load_dword v45, v4, s[74:75] nt
	v_add_u32_e32 v4, s36, v4
	global_load_dword v46, v4, s[74:75] nt
	v_add_u32_e32 v4, s36, v4
	global_load_dword v47, v4, s[74:75] nt
	s_waitcnt vmcnt(36)
	ds_write_b32 v5, v48 offset:0
	ds_write_b32 v5, v49 offset:264
	ds_write_b32 v5, v50 offset:528
	ds_write_b32 v5, v51 offset:792
	ds_write_b32 v5, v52 offset:1056
	ds_write_b32 v5, v53 offset:1320
	ds_write_b32 v5, v54 offset:1584
	ds_write_b32 v5, v55 offset:1848
	ds_write_b32 v5, v56 offset:2112
	ds_write_b32 v5, v57 offset:2376
	ds_write_b32 v5, v58 offset:2640
	ds_write_b32 v5, v59 offset:2904
	ds_write_b32 v5, v60 offset:3168
	ds_write_b32 v5, v61 offset:3432
	ds_write_b32 v5, v62 offset:3696
	ds_write_b32 v5, v63 offset:3960
	ds_write_b32 v5, v64 offset:4224
	ds_write_b32 v5, v65 offset:4488
	ds_write_b32 v5, v66 offset:4752
	ds_write_b32 v5, v67 offset:5016
	ds_write_b32 v5, v68 offset:5280
	ds_write_b32 v5, v69 offset:5544
	ds_write_b32 v5, v70 offset:5808
	ds_write_b32 v5, v71 offset:6072
	ds_write_b32 v5, v72 offset:6336
	ds_write_b32 v5, v73 offset:6600
	ds_write_b32 v5, v74 offset:6864
	ds_write_b32 v5, v75 offset:7128
	ds_write_b32 v5, v76 offset:7392
	ds_write_b32 v5, v77 offset:7656
	ds_write_b32 v5, v78 offset:7920
	ds_write_b32 v5, v79 offset:8184
	s_waitcnt lgkmcnt(0)
	ds_read2_b32 v[80:81], v6 offset0:0 offset1:33
	ds_read2_b32 v[82:83], v6 offset0:66 offset1:99
	ds_read2_b32 v[84:85], v6 offset0:132 offset1:165
	ds_read2_b32 v[86:87], v6 offset0:198 offset1:231
	ds_read2_b32 v[88:89], v6 offset0:8 offset1:41
	ds_read2_b32 v[90:91], v6 offset0:74 offset1:107
	ds_read2_b32 v[92:93], v6 offset0:140 offset1:173
	ds_read2_b32 v[94:95], v6 offset0:206 offset1:239
	ds_read2_b32 v[136:137], v6 offset0:16 offset1:49
	ds_read2_b32 v[138:139], v6 offset0:82 offset1:115
	ds_read2_b32 v[140:141], v6 offset0:148 offset1:181
	ds_read2_b32 v[142:143], v6 offset0:214 offset1:247
	ds_read2_b32 v[144:145], v6 offset0:24 offset1:57
	ds_read2_b32 v[146:147], v6 offset0:90 offset1:123
	ds_read2_b32 v[148:149], v6 offset0:156 offset1:189
	ds_read2_b32 v[150:151], v6 offset0:222 offset1:255
	s_waitcnt lgkmcnt(12)
	v_cvt_pk_bf16_f32 v96, v80, v81
	v_cvt_pk_bf16_f32 v97, v82, v83
	v_cvt_pk_bf16_f32 v98, v84, v85
	v_cvt_pk_bf16_f32 v99, v86, v87
	global_store_dwordx4 v13, v[96:99], s[54:55]
	v_add_u32_e32 v13, s57, v13
	s_waitcnt lgkmcnt(8)
	v_cvt_pk_bf16_f32 v100, v88, v89
	v_cvt_pk_bf16_f32 v101, v90, v91
	v_cvt_pk_bf16_f32 v102, v92, v93
	v_cvt_pk_bf16_f32 v103, v94, v95
	global_store_dwordx4 v13, v[100:103], s[54:55]
	v_add_u32_e32 v13, s57, v13
	s_waitcnt lgkmcnt(4)
	v_cvt_pk_bf16_f32 v104, v136, v137
	v_cvt_pk_bf16_f32 v105, v138, v139
	v_cvt_pk_bf16_f32 v106, v140, v141
	v_cvt_pk_bf16_f32 v107, v142, v143
	global_store_dwordx4 v13, v[104:107], s[54:55]
	v_add_u32_e32 v13, s57, v13
	s_waitcnt lgkmcnt(0)
	v_cvt_pk_bf16_f32 v108, v144, v145
	v_cvt_pk_bf16_f32 v109, v146, v147
	v_cvt_pk_bf16_f32 v110, v148, v149
	v_cvt_pk_bf16_f32 v111, v150, v151
	global_store_dwordx4 v13, v[108:111], s[54:55]
	s_cmp_lt_u32 s58, s59
	s_cbranch_scc1 .Ldc4_n6
	v_readfirstlane_b32 s58, v2
	s_lshl_b32 s58, s58, 3
	s_cmp_ge_u32 s58, 0x3400
	s_cbranch_scc1 .Ldc4_fin0
	s_add_u32 s59, s58, 8
	s_mov_b64 exec, 1
	global_atomic_add v2, v1, v9, s[70:71] sc0
	s_mov_b64 exec, -1

.Ldc4_i7_d:
	s_lshl_b32 s84, s84, 6
	s_lshl_b32 s85, s85, 5
	s_mul_i32 s86, s84, s78
	s_lshl_b32 s36, s85, 2
	s_add_u32 s86, s86, s36
	s_add_u32 s74, s74, s86
	s_addc_u32 s75, s75, 0
	s_mul_i32 s86, s85, s79
	s_lshl_b32 s36, s84, 1
	s_add_u32 s86, s86, s36
	s_add_u32 s54, s76, s86
	s_addc_u32 s55, s77, 0
	s_lshl_b32 s57, s79, 3
	v_mad_u32_u24 v13, v10, s79, v11
	v_mad_u32_u24 v4, v7, s78, v8
	s_lshl_b32 s36, s78, 1
	global_load_dword v48, v4, s[74:75] nt
	v_add_u32_e32 v4, s36, v4
	global_load_dword v49, v4, s[74:75] nt
	v_add_u32_e32 v4, s36, v4
	global_load_dword v50, v4, s[74:75] nt
	v_add_u32_e32 v4, s36, v4
	global_load_dword v51, v4, s[74:75] nt
	v_add_u32_e32 v4, s36, v4
	global_load_dword v52, v4, s[74:75] nt
	v_add_u32_e32 v4, s36, v4
	global_load_dword v53, v4, s[74:75] nt
	v_add_u32_e32 v4, s36, v4
	global_load_dword v54, v4, s[74:75] nt
	v_add_u32_e32 v4, s36, v4
	global_load_dword v55, v4, s[74:75] nt
	v_add_u32_e32 v4, s36, v4
	global_load_dword v56, v4, s[74:75] nt
	v_add_u32_e32 v4, s36, v4
	global_load_dword v57, v4, s[74:75] nt
	v_add_u32_e32 v4, s36, v4
	global_load_dword v58, v4, s[74:75] nt
	v_add_u32_e32 v4, s36, v4
	global_load_dword v59, v4, s[74:75] nt
	v_add_u32_e32 v4, s36, v4
	global_load_dword v60, v4, s[74:75] nt
	v_add_u32_e32 v4, s36, v4
	global_load_dword v61, v4, s[74:75] nt
	v_add_u32_e32 v4, s36, v4
	global_load_dword v62, v4, s[74:75] nt
	v_add_u32_e32 v4, s36, v4
	global_load_dword v63, v4, s[74:75] nt
	v_add_u32_e32 v4, s36, v4
	s_waitcnt vmcnt(46)
	global_load_dword v64, v4, s[74:75] nt
	v_add_u32_e32 v4, s36, v4
	global_load_dword v65, v4, s[74:75] nt
	v_add_u32_e32 v4, s36, v4
	global_load_dword v66, v4, s[74:75] nt
	v_add_u32_e32 v4, s36, v4
	global_load_dword v67, v4, s[74:75] nt
	v_add_u32_e32 v4, s36, v4
	global_load_dword v68, v4, s[74:75] nt
	v_add_u32_e32 v4, s36, v4
	global_load_dword v69, v4, s[74:75] nt
	v_add_u32_e32 v4, s36, v4
	global_load_dword v70, v4, s[74:75] nt
	v_add_u32_e32 v4, s36, v4
	global_load_dword v71, v4, s[74:75] nt
	v_add_u32_e32 v4, s36, v4
	global_load_dword v72, v4, s[74:75] nt
	v_add_u32_e32 v4, s36, v4
	global_load_dword v73, v4, s[74:75] nt
	v_add_u32_e32 v4, s36, v4
	global_load_dword v74, v4, s[74:75] nt
	v_add_u32_e32 v4, s36, v4
	global_load_dword v75, v4, s[74:75] nt
	v_add_u32_e32 v4, s36, v4
	global_load_dword v76, v4, s[74:75] nt
	v_add_u32_e32 v4, s36, v4
	global_load_dword v77, v4, s[74:75] nt
	v_add_u32_e32 v4, s36, v4
	global_load_dword v78, v4, s[74:75] nt
	v_add_u32_e32 v4, s36, v4
	global_load_dword v79, v4, s[74:75] nt
	s_waitcnt vmcnt(36)
	ds_write_b32 v5, v16 offset:0
	ds_write_b32 v5, v17 offset:264
	ds_write_b32 v5, v18 offset:528
	ds_write_b32 v5, v19 offset:792
	ds_write_b32 v5, v20 offset:1056
	ds_write_b32 v5, v21 offset:1320
	ds_write_b32 v5, v22 offset:1584
	ds_write_b32 v5, v23 offset:1848
	ds_write_b32 v5, v24 offset:2112
	ds_write_b32 v5, v25 offset:2376
	ds_write_b32 v5, v26 offset:2640
	ds_write_b32 v5, v27 offset:2904
	ds_write_b32 v5, v28 offset:3168
	ds_write_b32 v5, v29 offset:3432
	ds_write_b32 v5, v30 offset:3696
	ds_write_b32 v5, v31 offset:3960
	ds_write_b32 v5, v32 offset:4224
	ds_write_b32 v5, v33 offset:4488
	ds_write_b32 v5, v34 offset:4752
	ds_write_b32 v5, v35 offset:5016
	ds_write_b32 v5, v36 offset:5280
	ds_write_b32 v5, v37 offset:5544
	ds_write_b32 v5, v38 offset:5808
	ds_write_b32 v5, v39 offset:6072
	ds_write_b32 v5, v40 offset:6336
	ds_write_b32 v5, v41 offset:6600
	ds_write_b32 v5, v42 offset:6864
	ds_write_b32 v5, v43 offset:7128
	ds_write_b32 v5, v44 offset:7392
	ds_write_b32 v5, v45 offset:7656
	ds_write_b32 v5, v46 offset:7920
	ds_write_b32 v5, v47 offset:8184
	s_waitcnt lgkmcnt(0)
	ds_read2_b32 v[80:81], v6 offset0:0 offset1:33
	ds_read2_b32 v[82:83], v6 offset0:66 offset1:99
	ds_read2_b32 v[84:85], v6 offset0:132 offset1:165
	ds_read2_b32 v[86:87], v6 offset0:198 offset1:231
	ds_read2_b32 v[88:89], v6 offset0:8 offset1:41
	ds_read2_b32 v[90:91], v6 offset0:74 offset1:107
	ds_read2_b32 v[92:93], v6 offset0:140 offset1:173
	ds_read2_b32 v[94:95], v6 offset0:206 offset1:239
	ds_read2_b32 v[136:137], v6 offset0:16 offset1:49
	ds_read2_b32 v[138:139], v6 offset0:82 offset1:115
	ds_read2_b32 v[140:141], v6 offset0:148 offset1:181
	ds_read2_b32 v[142:143], v6 offset0:214 offset1:247
	ds_read2_b32 v[144:145], v6 offset0:24 offset1:57
	ds_read2_b32 v[146:147], v6 offset0:90 offset1:123
	ds_read2_b32 v[148:149], v6 offset0:156 offset1:189
	ds_read2_b32 v[150:151], v6 offset0:222 offset1:255
	s_waitcnt lgkmcnt(12)
	v_cvt_pk_bf16_f32 v96, v80, v81
	v_cvt_pk_bf16_f32 v97, v82, v83
	v_cvt_pk_bf16_f32 v98, v84, v85
	v_cvt_pk_bf16_f32 v99, v86, v87
	global_store_dwordx4 v12, v[96:99], s[40:41]
	v_add_u32_e32 v12, s39, v12
	s_waitcnt lgkmcnt(8)
	v_cvt_pk_bf16_f32 v100, v88, v89
	v_cvt_pk_bf16_f32 v101, v90, v91
	v_cvt_pk_bf16_f32 v102, v92, v93
	v_cvt_pk_bf16_f32 v103, v94, v95
	global_store_dwordx4 v12, v[100:103], s[40:41]
	v_add_u32_e32 v12, s39, v12
	s_waitcnt lgkmcnt(4)
	v_cvt_pk_bf16_f32 v104, v136, v137
	v_cvt_pk_bf16_f32 v105, v138, v139
	v_cvt_pk_bf16_f32 v106, v140, v141
	v_cvt_pk_bf16_f32 v107, v142, v143
	global_store_dwordx4 v12, v[104:107], s[40:41]
	v_add_u32_e32 v12, s39, v12
	s_waitcnt lgkmcnt(0)
	v_cvt_pk_bf16_f32 v108, v144, v145
	v_cvt_pk_bf16_f32 v109, v146, v147
	v_cvt_pk_bf16_f32 v110, v148, v149
	v_cvt_pk_bf16_f32 v111, v150, v151
	global_store_dwordx4 v12, v[108:111], s[40:41]
	s_cmp_lt_u32 s58, s59
	s_cbranch_scc1 .Ldc4_n8
	v_readfirstlane_b32 s58, v2
	s_lshl_b32 s58, s58, 3
	s_cmp_ge_u32 s58, 0x3400
	s_cbranch_scc1 .Ldc4_fin1
	s_add_u32 s59, s58, 8
	s_mov_b64 exec, 1
	global_atomic_add v2, v1, v9, s[70:71] sc0
	s_mov_b64 exec, -1
.Ldc4_n8:
	s_mov_b32 s73, s58
	s_add_u32 s58, s58, 1
	s_branch .Ldc4_loop
.Ldc4_fin0:
	s_waitcnt vmcnt(0)
	ds_write_b32 v5, v16 offset:0
	ds_write_b32 v5, v17 offset:264
	ds_write_b32 v5, v18 offset:528
	ds_write_b32 v5, v19 offset:792
	ds_write_b32 v5, v20 offset:1056
	ds_write_b32 v5, v21 offset:1320
	ds_write_b32 v5, v22 offset:1584
	ds_write_b32 v5, v23 offset:1848
	ds_write_b32 v5, v24 offset:2112
	ds_write_b32 v5, v25 offset:2376
	ds_write_b32 v5, v26 offset:2640
	ds_write_b32 v5, v27 offset:2904
	ds_write_b32 v5, v28 offset:3168
	ds_write_b32 v5, v29 offset:3432
	ds_write_b32 v5, v30 offset:3696
	ds_write_b32 v5, v31 offset:3960
	ds_write_b32 v5, v32 offset:4224
	ds_write_b32 v5, v33 offset:4488
	ds_write_b32 v5, v34 offset:4752
	ds_write_b32 v5, v35 offset:5016
	ds_write_b32 v5, v36 offset:5280
	ds_write_b32 v5, v37 offset:5544
	ds_write_b32 v5, v38 offset:5808
	ds_write_b32 v5, v39 offset:6072
	ds_write_b32 v5, v40 offset:6336
	ds_write_b32 v5, v41 offset:6600
	ds_write_b32 v5, v42 offset:6864
	ds_write_b32 v5, v43 offset:7128
	ds_write_b32 v5, v44 offset:7392
	ds_write_b32 v5, v45 offset:7656
	ds_write_b32 v5, v46 offset:7920
	ds_write_b32 v5, v47 offset:8184
	s_waitcnt lgkmcnt(0)
	ds_read2_b32 v[80:81], v6 offset0:0 offset1:33
	ds_read2_b32 v[82:83], v6 offset0:66 offset1:99
	ds_read2_b32 v[84:85], v6 offset0:132 offset1:165
	ds_read2_b32 v[86:87], v6 offset0:198 offset1:231
	ds_read2_b32 v[88:89], v6 offset0:8 offset1:41
	ds_read2_b32 v[90:91], v6 offset0:74 offset1:107
	ds_read2_b32 v[92:93], v6 offset0:140 offset1:173
	ds_read2_b32 v[94:95], v6 offset0:206 offset1:239
	ds_read2_b32 v[136:137], v6 offset0:16 offset1:49
	ds_read2_b32 v[138:139], v6 offset0:82 offset1:115
	ds_read2_b32 v[140:141], v6 offset0:148 offset1:181
	ds_read2_b32 v[142:143], v6 offset0:214 offset1:247
	ds_read2_b32 v[144:145], v6 offset0:24 offset1:57
	ds_read2_b32 v[146:147], v6 offset0:90 offset1:123
	ds_read2_b32 v[148:149], v6 offset0:156 offset1:189
	ds_read2_b32 v[150:151], v6 offset0:222 offset1:255
	s_waitcnt lgkmcnt(12)
	v_cvt_pk_bf16_f32 v96, v80, v81
	v_cvt_pk_bf16_f32 v97, v82, v83
	v_cvt_pk_bf16_f32 v98, v84, v85
	v_cvt_pk_bf16_f32 v99, v86, v87
	global_store_dwordx4 v12, v[96:99], s[40:41]
	v_add_u32_e32 v12, s39, v12
	s_waitcnt lgkmcnt(8)
	v_cvt_pk_bf16_f32 v100, v88, v89
	v_cvt_pk_bf16_f32 v101, v90, v91
	v_cvt_pk_bf16_f32 v102, v92, v93
	v_cvt_pk_bf16_f32 v103, v94, v95
	global_store_dwordx4 v12, v[100:103], s[40:41]
	v_add_u32_e32 v12, s39, v12
	s_waitcnt lgkmcnt(4)
	v_cvt_pk_bf16_f32 v104, v136, v137
	v_cvt_pk_bf16_f32 v105, v138, v139
	v_cvt_pk_bf16_f32 v106, v140, v141
	v_cvt_pk_bf16_f32 v107, v142, v143
	global_store_dwordx4 v12, v[104:107], s[40:41]
	v_add_u32_e32 v12, s39, v12
	s_waitcnt lgkmcnt(0)
	v_cvt_pk_bf16_f32 v108, v144, v145
	v_cvt_pk_bf16_f32 v109, v146, v147
	v_cvt_pk_bf16_f32 v110, v148, v149
	v_cvt_pk_bf16_f32 v111, v150, v151
	global_store_dwordx4 v12, v[108:111], s[40:41]
	s_branch .Ldc4_done
.Ldc4_fin1:
	s_waitcnt vmcnt(0)
	ds_write_b32 v5, v48 offset:0
	ds_write_b32 v5, v49 offset:264
	ds_write_b32 v5, v50 offset:528
	ds_write_b32 v5, v51 offset:792
	ds_write_b32 v5, v52 offset:1056
	ds_write_b32 v5, v53 offset:1320
	ds_write_b32 v5, v54 offset:1584
	ds_write_b32 v5, v55 offset:1848
	ds_write_b32 v5, v56 offset:2112
	ds_write_b32 v5, v57 offset:2376
	ds_write_b32 v5, v58 offset:2640
	ds_write_b32 v5, v59 offset:2904
	ds_write_b32 v5, v60 offset:3168
	ds_write_b32 v5, v61 offset:3432
	ds_write_b32 v5, v62 offset:3696
	ds_write_b32 v5, v63 offset:3960
	ds_write_b32 v5, v64 offset:4224
	ds_write_b32 v5, v65 offset:4488
	ds_write_b32 v5, v66 offset:4752
	ds_write_b32 v5, v67 offset:5016
	ds_write_b32 v5, v68 offset:5280
	ds_write_b32 v5, v69 offset:5544
	ds_write_b32 v5, v70 offset:5808
	ds_write_b32 v5, v71 offset:6072
	ds_write_b32 v5, v72 offset:6336
	ds_write_b32 v5, v73 offset:6600
	ds_write_b32 v5, v74 offset:6864
	ds_write_b32 v5, v75 offset:7128
	ds_write_b32 v5, v76 offset:7392
	ds_write_b32 v5, v77 offset:7656
	ds_write_b32 v5, v78 offset:7920
	ds_write_b32 v5, v79 offset:8184
	s_waitcnt lgkmcnt(0)
	ds_read2_b32 v[80:81], v6 offset0:0 offset1:33
	ds_read2_b32 v[82:83], v6 offset0:66 offset1:99
	ds_read2_b32 v[84:85], v6 offset0:132 offset1:165
	ds_read2_b32 v[86:87], v6 offset0:198 offset1:231
	ds_read2_b32 v[88:89], v6 offset0:8 offset1:41
	ds_read2_b32 v[90:91], v6 offset0:74 offset1:107
	ds_read2_b32 v[92:93], v6 offset0:140 offset1:173
	ds_read2_b32 v[94:95], v6 offset0:206 offset1:239
	ds_read2_b32 v[136:137], v6 offset0:16 offset1:49
	ds_read2_b32 v[138:139], v6 offset0:82 offset1:115
	ds_read2_b32 v[140:141], v6 offset0:148 offset1:181
	ds_read2_b32 v[142:143], v6 offset0:214 offset1:247
	ds_read2_b32 v[144:145], v6 offset0:24 offset1:57
	ds_read2_b32 v[146:147], v6 offset0:90 offset1:123
	ds_read2_b32 v[148:149], v6 offset0:156 offset1:189
	ds_read2_b32 v[150:151], v6 offset0:222 offset1:255
	s_waitcnt lgkmcnt(12)
	v_cvt_pk_bf16_f32 v96, v80, v81
	v_cvt_pk_bf16_f32 v97, v82, v83
	v_cvt_pk_bf16_f32 v98, v84, v85
	v_cvt_pk_bf16_f32 v99, v86, v87
	global_store_dwordx4 v13, v[96:99], s[54:55]
	v_add_u32_e32 v13, s57, v13
	s_waitcnt lgkmcnt(8)
	v_cvt_pk_bf16_f32 v100, v88, v89
	v_cvt_pk_bf16_f32 v101, v90, v91
	v_cvt_pk_bf16_f32 v102, v92, v93
	v_cvt_pk_bf16_f32 v103, v94, v95
	global_store_dwordx4 v13, v[100:103], s[54:55]
	v_add_u32_e32 v13, s57, v13
	s_waitcnt lgkmcnt(4)
	v_cvt_pk_bf16_f32 v104, v136, v137
	v_cvt_pk_bf16_f32 v105, v138, v139
	v_cvt_pk_bf16_f32 v106, v140, v141
	v_cvt_pk_bf16_f32 v107, v142, v143
	global_store_dwordx4 v13, v[104:107], s[54:55]
	v_add_u32_e32 v13, s57, v13
	s_waitcnt lgkmcnt(0)
	v_cvt_pk_bf16_f32 v108, v144, v145
	v_cvt_pk_bf16_f32 v109, v146, v147
	v_cvt_pk_bf16_f32 v110, v148, v149
	v_cvt_pk_bf16_f32 v111, v150, v151
	global_store_dwordx4 v13, v[108:111], s[54:55]
.Ldc4_done:
	s_waitcnt vmcnt(0)
	s_branch .LBB0_552
.Ldc8_entry:
	s_mov_b64 exec, -1
	v_readlane_b32 s0, v250, 0
	v_readlane_b32 s1, v250, 1
	v_mbcnt_lo_u32_b32 v3, -1, 0
	v_mbcnt_hi_u32_b32 v3, -1, v3
	s_sub_u32 s0, s0, 0x120
	s_subb_u32 s1, s1, 0
	s_load_dwordx4 s[80:83], s[0:1], 0xe0
	s_load_dwordx2 s[64:65], s[0:1], 0x68
	s_add_u32 s70, s24, 0x5016700
	s_addc_u32 s71, s25, 0
	v_readfirstlane_b32 s84, v159
	v_mov_b32_e32 v9, 1
	v_lshrrev_b32_e32 v7, 5, v3
	v_and_b32_e32 v8, 31, v3
	s_lshr_b32 s84, s84, 6
	s_lshl_b32 s72, s84, 14
	v_lshlrev_b32_e32 v8, 2, v8
	v_lshrrev_b32_e32 v10, 3, v3
	v_and_b32_e32 v11, 7, v3
	v_mul_u32_u24_e32 v5, 0x84, v7
	v_add3_u32 v5, v5, v8, s72
	v_mul_u32_u24_e32 v6, 0x420, v11
	v_lshl_add_u32 v6, v10, 2, v6
	v_add_u32_e32 v6, s72, v6
	v_lshlrev_b32_e32 v11, 4, v11
	s_mov_b32 s58, 0
	s_mov_b32 s59, 0
	s_waitcnt lgkmcnt(0)
	s_mov_b64 exec, 1
	global_atomic_add v2, v1, v9, s[70:71] sc0
	s_mov_b64 exec, -1
	s_waitcnt vmcnt(0)
	s_cmp_lt_u32 s58, s59
	s_cbranch_scc1 .Ldc8_n0
	v_readfirstlane_b32 s58, v2
	s_lshl_b32 s58, s58, 3
	s_cmp_ge_u32 s58, 0x1600
	s_cbranch_scc1 .Ldc8_done
	s_add_u32 s59, s58, 8
	s_mov_b64 exec, 1
	global_atomic_add v2, v1, v9, s[70:71] sc0
	s_mov_b64 exec, -1
.Ldc8_n0:
	s_mov_b32 s73, s58
	s_add_u32 s58, s58, 1
	s_mov_b64 s[74:75], s[20:21]
	s_add_u32 s76, s24, 0x3400000
	s_addc_u32 s77, s25, 0
	s_mov_b32 s78, 0x2000
	s_mov_b32 s79, 0x2c00
	s_lshr_b32 s84, s73, 6
	s_and_b32 s85, s73, 63
.Ldc8_i1_d:
	s_lshl_b32 s84, s84, 6
	s_lshl_b32 s85, s85, 5
	s_mul_i32 s86, s84, s78
	s_lshl_b32 s36, s85, 2
	s_add_u32 s86, s86, s36
	s_add_u32 s74, s74, s86
	s_addc_u32 s75, s75, 0
	s_mul_i32 s86, s85, s79
	s_lshl_b32 s36, s84, 1
	s_add_u32 s86, s86, s36
	s_add_u32 s40, s76, s86
	s_addc_u32 s41, s77, 0
	s_lshl_b32 s39, s79, 3
	v_mad_u32_u24 v12, v10, s79, v11
	v_mad_u32_u24 v4, v7, s78, v8
	s_lshl_b32 s36, s78, 1
	global_load_dword v16, v4, s[74:75] nt
	v_add_u32_e32 v4, s36, v4
	global_load_dword v17, v4, s[74:75] nt
	v_add_u32_e32 v4, s36, v4
	global_load_dword v18, v4, s[74:75] nt
	v_add_u32_e32 v4, s36, v4
	global_load_dword v19, v4, s[74:75] nt
	v_add_u32_e32 v4, s36, v4
	global_load_dword v20, v4, s[74:75] nt
	v_add_u32_e32 v4, s36, v4
	global_load_dword v21, v4, s[74:75] nt
	v_add_u32_e32 v4, s36, v4
	global_load_dword v22, v4, s[74:75] nt
	v_add_u32_e32 v4, s36, v4
	global_load_dword v23, v4, s[74:75] nt
	v_add_u32_e32 v4, s36, v4
	global_load_dword v24, v4, s[74:75] nt
	v_add_u32_e32 v4, s36, v4
	global_load_dword v25, v4, s[74:75] nt
	v_add_u32_e32 v4, s36, v4
	global_load_dword v26, v4, s[74:75] nt
	v_add_u32_e32 v4, s36, v4
	global_load_dword v27, v4, s[74:75] nt
	v_add_u32_e32 v4, s36, v4
	global_load_dword v28, v4, s[74:75] nt
	v_add_u32_e32 v4, s36, v4
	global_load_dword v29, v4, s[74:75] nt
	v_add_u32_e32 v4, s36, v4
	global_load_dword v30, v4, s[74:75] nt
	v_add_u32_e32 v4, s36, v4
	global_load_dword v31, v4, s[74:75] nt
	v_add_u32_e32 v4, s36, v4
	s_waitcnt vmcnt(46)
	global_load_dword v32, v4, s[74:75] nt
	v_add_u32_e32 v4, s36, v4
	global_load_dword v33, v4, s[74:75] nt
	v_add_u32_e32 v4, s36, v4
	global_load_dword v34, v4, s[74:75] nt
	v_add_u32_e32 v4, s36, v4
	global_load_dword v35, v4, s[74:75] nt
	v_add_u32_e32 v4, s36, v4
	global_load_dword v36, v4, s[74:75] nt
	v_add_u32_e32 v4, s36, v4
	global_load_dword v37, v4, s[74:75] nt
	v_add_u32_e32 v4, s36, v4
	global_load_dword v38, v4, s[74:75] nt
	v_add_u32_e32 v4, s36, v4
	global_load_dword v39, v4, s[74:75] nt
	v_add_u32_e32 v4, s36, v4
	global_load_dword v40, v4, s[74:75] nt
	v_add_u32_e32 v4, s36, v4
	global_load_dword v41, v4, s[74:75] nt
	v_add_u32_e32 v4, s36, v4
	global_load_dword v42, v4, s[74:75] nt
	v_add_u32_e32 v4, s36, v4
	global_load_dword v43, v4, s[74:75] nt
	v_add_u32_e32 v4, s36, v4
	global_load_dword v44, v4, s[74:75] nt
	v_add_u32_e32 v4, s36, v4
	global_load_dword v45, v4, s[74:75] nt
	v_add_u32_e32 v4, s36, v4
	global_load_dword v46, v4, s[74:75] nt
	v_add_u32_e32 v4, s36, v4
	global_load_dword v47, v4, s[74:75] nt
	s_cmp_lt_u32 s58, s59
	s_cbranch_scc1 .Ldc8_n2
	v_readfirstlane_b32 s58, v2
	s_lshl_b32 s58, s58, 3
	s_cmp_ge_u32 s58, 0x1600
	s_cbranch_scc1 .Ldc8_fin0
	s_add_u32 s59, s58, 8
	s_mov_b64 exec, 1
	global_atomic_add v2, v1, v9, s[70:71] sc0
	s_mov_b64 exec, -1

.Ldc8_i3_d:
	s_lshl_b32 s84, s84, 6
	s_lshl_b32 s85, s85, 5
	s_mul_i32 s86, s84, s78
	s_lshl_b32 s36, s85, 2
	s_add_u32 s86, s86, s36
	s_add_u32 s74, s74, s86
	s_addc_u32 s75, s75, 0
	s_mul_i32 s86, s85, s79
	s_lshl_b32 s36, s84, 1
	s_add_u32 s86, s86, s36
	s_add_u32 s54, s76, s86
	s_addc_u32 s55, s77, 0
	s_lshl_b32 s57, s79, 3
	v_mad_u32_u24 v13, v10, s79, v11
	v_mad_u32_u24 v4, v7, s78, v8
	s_lshl_b32 s36, s78, 1
	global_load_dword v48, v4, s[74:75] nt
	v_add_u32_e32 v4, s36, v4
	global_load_dword v49, v4, s[74:75] nt
	v_add_u32_e32 v4, s36, v4
	global_load_dword v50, v4, s[74:75] nt
	v_add_u32_e32 v4, s36, v4
	global_load_dword v51, v4, s[74:75] nt
	v_add_u32_e32 v4, s36, v4
	global_load_dword v52, v4, s[74:75] nt
	v_add_u32_e32 v4, s36, v4
	global_load_dword v53, v4, s[74:75] nt
	v_add_u32_e32 v4, s36, v4
	global_load_dword v54, v4, s[74:75] nt
	v_add_u32_e32 v4, s36, v4
	global_load_dword v55, v4, s[74:75] nt
	v_add_u32_e32 v4, s36, v4
	global_load_dword v56, v4, s[74:75] nt
	v_add_u32_e32 v4, s36, v4
	global_load_dword v57, v4, s[74:75] nt
	v_add_u32_e32 v4, s36, v4
	global_load_dword v58, v4, s[74:75] nt
	v_add_u32_e32 v4, s36, v4
	global_load_dword v59, v4, s[74:75] nt
	v_add_u32_e32 v4, s36, v4
	global_load_dword v60, v4, s[74:75] nt
	v_add_u32_e32 v4, s36, v4
	global_load_dword v61, v4, s[74:75] nt
	v_add_u32_e32 v4, s36, v4
	global_load_dword v62, v4, s[74:75] nt
	v_add_u32_e32 v4, s36, v4
	global_load_dword v63, v4, s[74:75] nt
	v_add_u32_e32 v4, s36, v4
	s_waitcnt vmcnt(46)
	global_load_dword v64, v4, s[74:75] nt
	v_add_u32_e32 v4, s36, v4
	global_load_dword v65, v4, s[74:75] nt
	v_add_u32_e32 v4, s36, v4
	global_load_dword v66, v4, s[74:75] nt
	v_add_u32_e32 v4, s36, v4
	global_load_dword v67, v4, s[74:75] nt
	v_add_u32_e32 v4, s36, v4
	global_load_dword v68, v4, s[74:75] nt
	v_add_u32_e32 v4, s36, v4
	global_load_dword v69, v4, s[74:75] nt
	v_add_u32_e32 v4, s36, v4
	global_load_dword v70, v4, s[74:75] nt
	v_add_u32_e32 v4, s36, v4
	global_load_dword v71, v4, s[74:75] nt
	v_add_u32_e32 v4, s36, v4
	global_load_dword v72, v4, s[74:75] nt
	v_add_u32_e32 v4, s36, v4
	global_load_dword v73, v4, s[74:75] nt
	v_add_u32_e32 v4, s36, v4
	global_load_dword v74, v4, s[74:75] nt
	v_add_u32_e32 v4, s36, v4
	global_load_dword v75, v4, s[74:75] nt
	v_add_u32_e32 v4, s36, v4
	global_load_dword v76, v4, s[74:75] nt
	v_add_u32_e32 v4, s36, v4
	global_load_dword v77, v4, s[74:75] nt
	v_add_u32_e32 v4, s36, v4
	global_load_dword v78, v4, s[74:75] nt
	v_add_u32_e32 v4, s36, v4
	global_load_dword v79, v4, s[74:75] nt
	s_waitcnt vmcnt(32)
	ds_write_b32 v5, v16 offset:0
	ds_write_b32 v5, v17 offset:264
	ds_write_b32 v5, v18 offset:528
	ds_write_b32 v5, v19 offset:792
	ds_write_b32 v5, v20 offset:1056
	ds_write_b32 v5, v21 offset:1320
	ds_write_b32 v5, v22 offset:1584
	ds_write_b32 v5, v23 offset:1848
	ds_write_b32 v5, v24 offset:2112
	ds_write_b32 v5, v25 offset:2376
	ds_write_b32 v5, v26 offset:2640
	ds_write_b32 v5, v27 offset:2904
	ds_write_b32 v5, v28 offset:3168
	ds_write_b32 v5, v29 offset:3432
	ds_write_b32 v5, v30 offset:3696
	ds_write_b32 v5, v31 offset:3960
	ds_write_b32 v5, v32 offset:4224
	ds_write_b32 v5, v33 offset:4488
	ds_write_b32 v5, v34 offset:4752
	ds_write_b32 v5, v35 offset:5016
	ds_write_b32 v5, v36 offset:5280
	ds_write_b32 v5, v37 offset:5544
	ds_write_b32 v5, v38 offset:5808
	ds_write_b32 v5, v39 offset:6072
	ds_write_b32 v5, v40 offset:6336
	ds_write_b32 v5, v41 offset:6600
	ds_write_b32 v5, v42 offset:6864
	ds_write_b32 v5, v43 offset:7128
	ds_write_b32 v5, v44 offset:7392
	ds_write_b32 v5, v45 offset:7656
	ds_write_b32 v5, v46 offset:7920
	ds_write_b32 v5, v47 offset:8184
	s_waitcnt lgkmcnt(0)
	ds_read2_b32 v[80:81], v6 offset0:0 offset1:33
	ds_read2_b32 v[82:83], v6 offset0:66 offset1:99
	ds_read2_b32 v[84:85], v6 offset0:132 offset1:165
	ds_read2_b32 v[86:87], v6 offset0:198 offset1:231
	ds_read2_b32 v[88:89], v6 offset0:8 offset1:41
	ds_read2_b32 v[90:91], v6 offset0:74 offset1:107
	ds_read2_b32 v[92:93], v6 offset0:140 offset1:173
	ds_read2_b32 v[94:95], v6 offset0:206 offset1:239
	ds_read2_b32 v[136:137], v6 offset0:16 offset1:49
	ds_read2_b32 v[138:139], v6 offset0:82 offset1:115
	ds_read2_b32 v[140:141], v6 offset0:148 offset1:181
	ds_read2_b32 v[142:143], v6 offset0:214 offset1:247
	ds_read2_b32 v[144:145], v6 offset0:24 offset1:57
	ds_read2_b32 v[146:147], v6 offset0:90 offset1:123
	ds_read2_b32 v[148:149], v6 offset0:156 offset1:189
	ds_read2_b32 v[150:151], v6 offset0:222 offset1:255
	s_waitcnt lgkmcnt(12)
	v_cvt_pk_bf16_f32 v96, v80, v81
	v_cvt_pk_bf16_f32 v97, v82, v83
	v_cvt_pk_bf16_f32 v98, v84, v85
	v_cvt_pk_bf16_f32 v99, v86, v87
	global_store_dwordx4 v12, v[96:99], s[40:41]
	v_add_u32_e32 v12, s39, v12
	s_waitcnt lgkmcnt(8)
	v_cvt_pk_bf16_f32 v100, v88, v89
	v_cvt_pk_bf16_f32 v101, v90, v91
	v_cvt_pk_bf16_f32 v102, v92, v93
	v_cvt_pk_bf16_f32 v103, v94, v95
	global_store_dwordx4 v12, v[100:103], s[40:41]
	v_add_u32_e32 v12, s39, v12
	s_waitcnt lgkmcnt(4)
	v_cvt_pk_bf16_f32 v104, v136, v137
	v_cvt_pk_bf16_f32 v105, v138, v139
	v_cvt_pk_bf16_f32 v106, v140, v141
	v_cvt_pk_bf16_f32 v107, v142, v143
	global_store_dwordx4 v12, v[104:107], s[40:41]
	v_add_u32_e32 v12, s39, v12
	s_waitcnt lgkmcnt(0)
	v_cvt_pk_bf16_f32 v108, v144, v145
	v_cvt_pk_bf16_f32 v109, v146, v147
	v_cvt_pk_bf16_f32 v110, v148, v149
	v_cvt_pk_bf16_f32 v111, v150, v151
	global_store_dwordx4 v12, v[108:111], s[40:41]
	s_cmp_lt_u32 s58, s59
	s_cbranch_scc1 .Ldc8_n4
	v_readfirstlane_b32 s58, v2
	s_lshl_b32 s58, s58, 3
	s_cmp_ge_u32 s58, 0x1600
	s_cbranch_scc1 .Ldc8_fin1
	s_add_u32 s59, s58, 8
	s_mov_b64 exec, 1
	global_atomic_add v2, v1, v9, s[70:71] sc0
	s_mov_b64 exec, -1

.Ldc8_loop:
	s_mov_b64 s[74:75], s[20:21]
	s_add_u32 s76, s24, 0x3400000
	s_addc_u32 s77, s25, 0
	s_mov_b32 s78, 0x2000
	s_mov_b32 s79, 0x2c00
	s_lshr_b32 s84, s73, 6
	s_and_b32 s85, s73, 63
.Ldc8_i5_d:
	s_lshl_b32 s84, s84, 6
	s_lshl_b32 s85, s85, 5
	s_mul_i32 s86, s84, s78
	s_lshl_b32 s36, s85, 2
	s_add_u32 s86, s86, s36
	s_add_u32 s74, s74, s86
	s_addc_u32 s75, s75, 0
	s_mul_i32 s86, s85, s79
	s_lshl_b32 s36, s84, 1
	s_add_u32 s86, s86, s36
	s_add_u32 s40, s76, s86
	s_addc_u32 s41, s77, 0
	s_lshl_b32 s39, s79, 3
	v_mad_u32_u24 v12, v10, s79, v11
	v_mad_u32_u24 v4, v7, s78, v8
	s_lshl_b32 s36, s78, 1
	global_load_dword v16, v4, s[74:75] nt
	v_add_u32_e32 v4, s36, v4
	global_load_dword v17, v4, s[74:75] nt
	v_add_u32_e32 v4, s36, v4
	global_load_dword v18, v4, s[74:75] nt
	v_add_u32_e32 v4, s36, v4
	global_load_dword v19, v4, s[74:75] nt
	v_add_u32_e32 v4, s36, v4
	global_load_dword v20, v4, s[74:75] nt
	v_add_u32_e32 v4, s36, v4
	global_load_dword v21, v4, s[74:75] nt
	v_add_u32_e32 v4, s36, v4
	global_load_dword v22, v4, s[74:75] nt
	v_add_u32_e32 v4, s36, v4
	global_load_dword v23, v4, s[74:75] nt
	v_add_u32_e32 v4, s36, v4
	global_load_dword v24, v4, s[74:75] nt
	v_add_u32_e32 v4, s36, v4
	global_load_dword v25, v4, s[74:75] nt
	v_add_u32_e32 v4, s36, v4
	global_load_dword v26, v4, s[74:75] nt
	v_add_u32_e32 v4, s36, v4
	global_load_dword v27, v4, s[74:75] nt
	v_add_u32_e32 v4, s36, v4
	global_load_dword v28, v4, s[74:75] nt
	v_add_u32_e32 v4, s36, v4
	global_load_dword v29, v4, s[74:75] nt
	v_add_u32_e32 v4, s36, v4
	global_load_dword v30, v4, s[74:75] nt
	v_add_u32_e32 v4, s36, v4
	global_load_dword v31, v4, s[74:75] nt
	v_add_u32_e32 v4, s36, v4
	s_waitcnt vmcnt(46)
	global_load_dword v32, v4, s[74:75] nt
	v_add_u32_e32 v4, s36, v4
	global_load_dword v33, v4, s[74:75] nt
	v_add_u32_e32 v4, s36, v4
	global_load_dword v34, v4, s[74:75] nt
	v_add_u32_e32 v4, s36, v4
	global_load_dword v35, v4, s[74:75] nt
	v_add_u32_e32 v4, s36, v4
	global_load_dword v36, v4, s[74:75] nt
	v_add_u32_e32 v4, s36, v4
	global_load_dword v37, v4, s[74:75] nt
	v_add_u32_e32 v4, s36, v4
	global_load_dword v38, v4, s[74:75] nt
	v_add_u32_e32 v4, s36, v4
	global_load_dword v39, v4, s[74:75] nt
	v_add_u32_e32 v4, s36, v4
	global_load_dword v40, v4, s[74:75] nt
	v_add_u32_e32 v4, s36, v4
	global_load_dword v41, v4, s[74:75] nt
	v_add_u32_e32 v4, s36, v4
	global_load_dword v42, v4, s[74:75] nt
	v_add_u32_e32 v4, s36, v4
	global_load_dword v43, v4, s[74:75] nt
	v_add_u32_e32 v4, s36, v4
	global_load_dword v44, v4, s[74:75] nt
	v_add_u32_e32 v4, s36, v4
	global_load_dword v45, v4, s[74:75] nt
	v_add_u32_e32 v4, s36, v4
	global_load_dword v46, v4, s[74:75] nt
	v_add_u32_e32 v4, s36, v4
	global_load_dword v47, v4, s[74:75] nt
	s_waitcnt vmcnt(36)
	ds_write_b32 v5, v48 offset:0
	ds_write_b32 v5, v49 offset:264
	ds_write_b32 v5, v50 offset:528
	ds_write_b32 v5, v51 offset:792
	ds_write_b32 v5, v52 offset:1056
	ds_write_b32 v5, v53 offset:1320
	ds_write_b32 v5, v54 offset:1584
	ds_write_b32 v5, v55 offset:1848
	ds_write_b32 v5, v56 offset:2112
	ds_write_b32 v5, v57 offset:2376
	ds_write_b32 v5, v58 offset:2640
	ds_write_b32 v5, v59 offset:2904
	ds_write_b32 v5, v60 offset:3168
	ds_write_b32 v5, v61 offset:3432
	ds_write_b32 v5, v62 offset:3696
	ds_write_b32 v5, v63 offset:3960
	ds_write_b32 v5, v64 offset:4224
	ds_write_b32 v5, v65 offset:4488
	ds_write_b32 v5, v66 offset:4752
	ds_write_b32 v5, v67 offset:5016
	ds_write_b32 v5, v68 offset:5280
	ds_write_b32 v5, v69 offset:5544
	ds_write_b32 v5, v70 offset:5808
	ds_write_b32 v5, v71 offset:6072
	ds_write_b32 v5, v72 offset:6336
	ds_write_b32 v5, v73 offset:6600
	ds_write_b32 v5, v74 offset:6864
	ds_write_b32 v5, v75 offset:7128
	ds_write_b32 v5, v76 offset:7392
	ds_write_b32 v5, v77 offset:7656
	ds_write_b32 v5, v78 offset:7920
	ds_write_b32 v5, v79 offset:8184
	s_waitcnt lgkmcnt(0)
	ds_read2_b32 v[80:81], v6 offset0:0 offset1:33
	ds_read2_b32 v[82:83], v6 offset0:66 offset1:99
	ds_read2_b32 v[84:85], v6 offset0:132 offset1:165
	ds_read2_b32 v[86:87], v6 offset0:198 offset1:231
	ds_read2_b32 v[88:89], v6 offset0:8 offset1:41
	ds_read2_b32 v[90:91], v6 offset0:74 offset1:107
	ds_read2_b32 v[92:93], v6 offset0:140 offset1:173
	ds_read2_b32 v[94:95], v6 offset0:206 offset1:239
	ds_read2_b32 v[136:137], v6 offset0:16 offset1:49
	ds_read2_b32 v[138:139], v6 offset0:82 offset1:115
	ds_read2_b32 v[140:141], v6 offset0:148 offset1:181
	ds_read2_b32 v[142:143], v6 offset0:214 offset1:247
	ds_read2_b32 v[144:145], v6 offset0:24 offset1:57
	ds_read2_b32 v[146:147], v6 offset0:90 offset1:123
	ds_read2_b32 v[148:149], v6 offset0:156 offset1:189
	ds_read2_b32 v[150:151], v6 offset0:222 offset1:255
	s_waitcnt lgkmcnt(12)
	v_cvt_pk_bf16_f32 v96, v80, v81
	v_cvt_pk_bf16_f32 v97, v82, v83
	v_cvt_pk_bf16_f32 v98, v84, v85
	v_cvt_pk_bf16_f32 v99, v86, v87
	global_store_dwordx4 v13, v[96:99], s[54:55]
	v_add_u32_e32 v13, s57, v13
	s_waitcnt lgkmcnt(8)
	v_cvt_pk_bf16_f32 v100, v88, v89
	v_cvt_pk_bf16_f32 v101, v90, v91
	v_cvt_pk_bf16_f32 v102, v92, v93
	v_cvt_pk_bf16_f32 v103, v94, v95
	global_store_dwordx4 v13, v[100:103], s[54:55]
	v_add_u32_e32 v13, s57, v13
	s_waitcnt lgkmcnt(4)
	v_cvt_pk_bf16_f32 v104, v136, v137
	v_cvt_pk_bf16_f32 v105, v138, v139
	v_cvt_pk_bf16_f32 v106, v140, v141
	v_cvt_pk_bf16_f32 v107, v142, v143
	global_store_dwordx4 v13, v[104:107], s[54:55]
	v_add_u32_e32 v13, s57, v13
	s_waitcnt lgkmcnt(0)
	v_cvt_pk_bf16_f32 v108, v144, v145
	v_cvt_pk_bf16_f32 v109, v146, v147
	v_cvt_pk_bf16_f32 v110, v148, v149
	v_cvt_pk_bf16_f32 v111, v150, v151
	global_store_dwordx4 v13, v[108:111], s[54:55]
	s_cmp_lt_u32 s58, s59
	s_cbranch_scc1 .Ldc8_n6
	v_readfirstlane_b32 s58, v2
	s_lshl_b32 s58, s58, 3
	s_cmp_ge_u32 s58, 0x1600
	s_cbranch_scc1 .Ldc8_fin0
	s_add_u32 s59, s58, 8
	s_mov_b64 exec, 1
	global_atomic_add v2, v1, v9, s[70:71] sc0
	s_mov_b64 exec, -1

.Ldc8_i7_d:
	s_lshl_b32 s84, s84, 6
	s_lshl_b32 s85, s85, 5
	s_mul_i32 s86, s84, s78
	s_lshl_b32 s36, s85, 2
	s_add_u32 s86, s86, s36
	s_add_u32 s74, s74, s86
	s_addc_u32 s75, s75, 0
	s_mul_i32 s86, s85, s79
	s_lshl_b32 s36, s84, 1
	s_add_u32 s86, s86, s36
	s_add_u32 s54, s76, s86
	s_addc_u32 s55, s77, 0
	s_lshl_b32 s57, s79, 3
	v_mad_u32_u24 v13, v10, s79, v11
	v_mad_u32_u24 v4, v7, s78, v8
	s_lshl_b32 s36, s78, 1
	global_load_dword v48, v4, s[74:75] nt
	v_add_u32_e32 v4, s36, v4
	global_load_dword v49, v4, s[74:75] nt
	v_add_u32_e32 v4, s36, v4
	global_load_dword v50, v4, s[74:75] nt
	v_add_u32_e32 v4, s36, v4
	global_load_dword v51, v4, s[74:75] nt
	v_add_u32_e32 v4, s36, v4
	global_load_dword v52, v4, s[74:75] nt
	v_add_u32_e32 v4, s36, v4
	global_load_dword v53, v4, s[74:75] nt
	v_add_u32_e32 v4, s36, v4
	global_load_dword v54, v4, s[74:75] nt
	v_add_u32_e32 v4, s36, v4
	global_load_dword v55, v4, s[74:75] nt
	v_add_u32_e32 v4, s36, v4
	global_load_dword v56, v4, s[74:75] nt
	v_add_u32_e32 v4, s36, v4
	global_load_dword v57, v4, s[74:75] nt
	v_add_u32_e32 v4, s36, v4
	global_load_dword v58, v4, s[74:75] nt
	v_add_u32_e32 v4, s36, v4
	global_load_dword v59, v4, s[74:75] nt
	v_add_u32_e32 v4, s36, v4
	global_load_dword v60, v4, s[74:75] nt
	v_add_u32_e32 v4, s36, v4
	global_load_dword v61, v4, s[74:75] nt
	v_add_u32_e32 v4, s36, v4
	global_load_dword v62, v4, s[74:75] nt
	v_add_u32_e32 v4, s36, v4
	global_load_dword v63, v4, s[74:75] nt
	v_add_u32_e32 v4, s36, v4
	s_waitcnt vmcnt(46)
	global_load_dword v64, v4, s[74:75] nt
	v_add_u32_e32 v4, s36, v4
	global_load_dword v65, v4, s[74:75] nt
	v_add_u32_e32 v4, s36, v4
	global_load_dword v66, v4, s[74:75] nt
	v_add_u32_e32 v4, s36, v4
	global_load_dword v67, v4, s[74:75] nt
	v_add_u32_e32 v4, s36, v4
	global_load_dword v68, v4, s[74:75] nt
	v_add_u32_e32 v4, s36, v4
	global_load_dword v69, v4, s[74:75] nt
	v_add_u32_e32 v4, s36, v4
	global_load_dword v70, v4, s[74:75] nt
	v_add_u32_e32 v4, s36, v4
	global_load_dword v71, v4, s[74:75] nt
	v_add_u32_e32 v4, s36, v4
	global_load_dword v72, v4, s[74:75] nt
	v_add_u32_e32 v4, s36, v4
	global_load_dword v73, v4, s[74:75] nt
	v_add_u32_e32 v4, s36, v4
	global_load_dword v74, v4, s[74:75] nt
	v_add_u32_e32 v4, s36, v4
	global_load_dword v75, v4, s[74:75] nt
	v_add_u32_e32 v4, s36, v4
	global_load_dword v76, v4, s[74:75] nt
	v_add_u32_e32 v4, s36, v4
	global_load_dword v77, v4, s[74:75] nt
	v_add_u32_e32 v4, s36, v4
	global_load_dword v78, v4, s[74:75] nt
	v_add_u32_e32 v4, s36, v4
	global_load_dword v79, v4, s[74:75] nt
	s_waitcnt vmcnt(36)
	ds_write_b32 v5, v16 offset:0
	ds_write_b32 v5, v17 offset:264
	ds_write_b32 v5, v18 offset:528
	ds_write_b32 v5, v19 offset:792
	ds_write_b32 v5, v20 offset:1056
	ds_write_b32 v5, v21 offset:1320
	ds_write_b32 v5, v22 offset:1584
	ds_write_b32 v5, v23 offset:1848
	ds_write_b32 v5, v24 offset:2112
	ds_write_b32 v5, v25 offset:2376
	ds_write_b32 v5, v26 offset:2640
	ds_write_b32 v5, v27 offset:2904
	ds_write_b32 v5, v28 offset:3168
	ds_write_b32 v5, v29 offset:3432
	ds_write_b32 v5, v30 offset:3696
	ds_write_b32 v5, v31 offset:3960
	ds_write_b32 v5, v32 offset:4224
	ds_write_b32 v5, v33 offset:4488
	ds_write_b32 v5, v34 offset:4752
	ds_write_b32 v5, v35 offset:5016
	ds_write_b32 v5, v36 offset:5280
	ds_write_b32 v5, v37 offset:5544
	ds_write_b32 v5, v38 offset:5808
	ds_write_b32 v5, v39 offset:6072
	ds_write_b32 v5, v40 offset:6336
	ds_write_b32 v5, v41 offset:6600
	ds_write_b32 v5, v42 offset:6864
	ds_write_b32 v5, v43 offset:7128
	ds_write_b32 v5, v44 offset:7392
	ds_write_b32 v5, v45 offset:7656
	ds_write_b32 v5, v46 offset:7920
	ds_write_b32 v5, v47 offset:8184
	s_waitcnt lgkmcnt(0)
	ds_read2_b32 v[80:81], v6 offset0:0 offset1:33
	ds_read2_b32 v[82:83], v6 offset0:66 offset1:99
	ds_read2_b32 v[84:85], v6 offset0:132 offset1:165
	ds_read2_b32 v[86:87], v6 offset0:198 offset1:231
	ds_read2_b32 v[88:89], v6 offset0:8 offset1:41
	ds_read2_b32 v[90:91], v6 offset0:74 offset1:107
	ds_read2_b32 v[92:93], v6 offset0:140 offset1:173
	ds_read2_b32 v[94:95], v6 offset0:206 offset1:239
	ds_read2_b32 v[136:137], v6 offset0:16 offset1:49
	ds_read2_b32 v[138:139], v6 offset0:82 offset1:115
	ds_read2_b32 v[140:141], v6 offset0:148 offset1:181
	ds_read2_b32 v[142:143], v6 offset0:214 offset1:247
	ds_read2_b32 v[144:145], v6 offset0:24 offset1:57
	ds_read2_b32 v[146:147], v6 offset0:90 offset1:123
	ds_read2_b32 v[148:149], v6 offset0:156 offset1:189
	ds_read2_b32 v[150:151], v6 offset0:222 offset1:255
	s_waitcnt lgkmcnt(12)
	v_cvt_pk_bf16_f32 v96, v80, v81
	v_cvt_pk_bf16_f32 v97, v82, v83
	v_cvt_pk_bf16_f32 v98, v84, v85
	v_cvt_pk_bf16_f32 v99, v86, v87
	global_store_dwordx4 v12, v[96:99], s[40:41]
	v_add_u32_e32 v12, s39, v12
	s_waitcnt lgkmcnt(8)
	v_cvt_pk_bf16_f32 v100, v88, v89
	v_cvt_pk_bf16_f32 v101, v90, v91
	v_cvt_pk_bf16_f32 v102, v92, v93
	v_cvt_pk_bf16_f32 v103, v94, v95
	global_store_dwordx4 v12, v[100:103], s[40:41]
	v_add_u32_e32 v12, s39, v12
	s_waitcnt lgkmcnt(4)
	v_cvt_pk_bf16_f32 v104, v136, v137
	v_cvt_pk_bf16_f32 v105, v138, v139
	v_cvt_pk_bf16_f32 v106, v140, v141
	v_cvt_pk_bf16_f32 v107, v142, v143
	global_store_dwordx4 v12, v[104:107], s[40:41]
	v_add_u32_e32 v12, s39, v12
	s_waitcnt lgkmcnt(0)
	v_cvt_pk_bf16_f32 v108, v144, v145
	v_cvt_pk_bf16_f32 v109, v146, v147
	v_cvt_pk_bf16_f32 v110, v148, v149
	v_cvt_pk_bf16_f32 v111, v150, v151
	global_store_dwordx4 v12, v[108:111], s[40:41]
	s_cmp_lt_u32 s58, s59
	s_cbranch_scc1 .Ldc8_n8
	v_readfirstlane_b32 s58, v2
	s_lshl_b32 s58, s58, 3
	s_cmp_ge_u32 s58, 0x1600
	s_cbranch_scc1 .Ldc8_fin1
	s_add_u32 s59, s58, 8
	s_mov_b64 exec, 1
	global_atomic_add v2, v1, v9, s[70:71] sc0
	s_mov_b64 exec, -1

.LBB0_728:
	s_mov_b64 s[46:47], exec
	v_lshlrev_b32_e32 v172, 1, v137
	v_and_b32_e32 v172, 0x70, v172
	v_lshlrev_b32_e32 v173, 1, v90
	s_movk_i32 s13, 0xffe8
	v_mul_u32_u24_e32 v167, 0xaaab, v83
	v_lshrrev_b32_e32 v167, 20, v167
	v_mad_i32_i24 v168, v167, s13, v83
	v_add_u32_e32 v169, s12, v167
	v_ashrrev_i32_e32 v168, 3, v168
	v_max_i32_e32 v169, 0, v169
	v_mul_u32_u24_e32 v169, 0x1a00, v169
	v_mad_u32_u24 v4, v167, s49, v130
	v_lshl_add_u32 v169, v168, 11, v169
	v_lshl_add_u32 v4, v168, 7, v4
	v_add3_u32 v169, v169, v173, v172
	v_add_u32_e32 v4, v172, v4
	global_load_dwordx4 v[92:95], v169, s[10:11]
	v_add_u32_e32 v0, 0x40, v83
	v_mul_u32_u24_e32 v167, 0xaaab, v0
	v_lshrrev_b32_e32 v167, 20, v167
	v_mad_i32_i24 v168, v167, s13, v0
	v_add_u32_e32 v169, s12, v167
	v_ashrrev_i32_e32 v168, 3, v168
	v_max_i32_e32 v169, 0, v169
	v_mul_u32_u24_e32 v169, 0x1a00, v169
	v_mad_u32_u24 v5, v167, s49, v130
	v_lshl_add_u32 v169, v168, 11, v169
	v_lshl_add_u32 v5, v168, 7, v5
	v_add3_u32 v169, v169, v173, v172
	v_add_u32_e32 v5, v172, v5
	global_load_dwordx4 v[96:99], v169, s[10:11]
	v_add_u32_e32 v0, 0x80, v83
	v_mul_u32_u24_e32 v167, 0xaaab, v0
	v_lshrrev_b32_e32 v167, 20, v167
	v_mad_i32_i24 v168, v167, s13, v0
	v_add_u32_e32 v169, s12, v167
	v_ashrrev_i32_e32 v168, 3, v168
	v_max_i32_e32 v169, 0, v169
	v_mul_u32_u24_e32 v169, 0x1a00, v169
	v_mad_u32_u24 v6, v167, s49, v130
	v_lshl_add_u32 v169, v168, 11, v169
	v_lshl_add_u32 v6, v168, 7, v6
	v_add3_u32 v169, v169, v173, v172
	v_add_u32_e32 v6, v172, v6
	global_load_dwordx4 v[100:103], v169, s[10:11]
	v_add_u32_e32 v0, 0xc0, v83
	v_mul_u32_u24_e32 v167, 0xaaab, v0
	v_lshrrev_b32_e32 v167, 20, v167
	v_mad_i32_i24 v168, v167, s13, v0
	v_add_u32_e32 v169, s12, v167
	v_ashrrev_i32_e32 v168, 3, v168
	v_max_i32_e32 v169, 0, v169
	v_mul_u32_u24_e32 v169, 0x1a00, v169
	v_mad_u32_u24 v7, v167, s49, v130
	v_lshl_add_u32 v169, v168, 11, v169
	v_lshl_add_u32 v7, v168, 7, v7
	v_add3_u32 v169, v169, v173, v172
	v_add_u32_e32 v7, v172, v7
	global_load_dwordx4 v[104:107], v169, s[10:11]
	v_add_u32_e32 v0, 0x100, v83
	v_mul_u32_u24_e32 v167, 0xaaab, v0
	v_lshrrev_b32_e32 v167, 20, v167
	v_mad_i32_i24 v168, v167, s13, v0
	v_add_u32_e32 v169, s12, v167
	v_ashrrev_i32_e32 v168, 3, v168
	v_max_i32_e32 v169, 0, v169
	v_mul_u32_u24_e32 v169, 0x1a00, v169
	v_mad_u32_u24 v8, v167, s49, v130
	v_lshl_add_u32 v169, v168, 11, v169
	v_lshl_add_u32 v8, v168, 7, v8
	v_add3_u32 v169, v169, v173, v172
	v_add_u32_e32 v8, v172, v8
	global_load_dwordx4 v[108:111], v169, s[10:11]
	v_add_u32_e32 v0, 0x140, v83
	v_mul_u32_u24_e32 v167, 0xaaab, v0
	v_lshrrev_b32_e32 v167, 20, v167
	v_mad_i32_i24 v168, v167, s13, v0
	v_add_u32_e32 v169, s12, v167
	v_ashrrev_i32_e32 v168, 3, v168
	v_max_i32_e32 v169, 0, v169
	v_mul_u32_u24_e32 v169, 0x1a00, v169
	v_mad_u32_u24 v9, v167, s49, v130
	v_lshl_add_u32 v169, v168, 11, v169
	v_lshl_add_u32 v9, v168, 7, v9
	v_add3_u32 v169, v169, v173, v172
	v_add_u32_e32 v9, v172, v9
	global_load_dwordx4 v[112:115], v169, s[10:11]
	v_add_u32_e32 v0, 0x180, v83
	v_mul_u32_u24_e32 v167, 0xaaab, v0
	v_lshrrev_b32_e32 v167, 20, v167
	v_mad_i32_i24 v168, v167, s13, v0
	v_add_u32_e32 v169, s12, v167
	v_ashrrev_i32_e32 v168, 3, v168
	v_max_i32_e32 v169, 0, v169
	v_mul_u32_u24_e32 v169, 0x1a00, v169
	v_mad_u32_u24 v10, v167, s49, v130
	v_lshl_add_u32 v169, v168, 11, v169
	v_lshl_add_u32 v10, v168, 7, v10
	v_add3_u32 v169, v169, v173, v172
	v_add_u32_e32 v10, v172, v10
	global_load_dwordx4 v[116:119], v169, s[10:11]
	v_add_u32_e32 v0, 0x1c0, v83
	v_mul_u32_u24_e32 v167, 0xaaab, v0
	v_lshrrev_b32_e32 v167, 20, v167
	v_mad_i32_i24 v168, v167, s13, v0
	v_add_u32_e32 v169, s12, v167
	v_ashrrev_i32_e32 v168, 3, v168
	v_max_i32_e32 v169, 0, v169
	v_mul_u32_u24_e32 v169, 0x1a00, v169
	v_mad_u32_u24 v11, v167, s49, v130
	v_lshl_add_u32 v169, v168, 11, v169
	v_lshl_add_u32 v11, v168, 7, v11
	v_add3_u32 v169, v169, v173, v172
	v_add_u32_e32 v11, v172, v11
	global_load_dwordx4 v[120:123], v169, s[10:11]
	v_add_u32_e32 v0, 0x200, v83
	v_mul_u32_u24_e32 v167, 0xaaab, v0
	v_lshrrev_b32_e32 v167, 20, v167
	v_mad_i32_i24 v168, v167, s13, v0
	v_add_u32_e32 v169, s12, v167
	v_ashrrev_i32_e32 v168, 3, v168
	v_max_i32_e32 v169, 0, v169
	v_mul_u32_u24_e32 v169, 0x1a00, v169
	v_mad_u32_u24 v12, v167, s49, v130
	v_lshl_add_u32 v169, v168, 11, v169
	v_lshl_add_u32 v12, v168, 7, v12
	v_add3_u32 v169, v169, v173, v172
	v_add_u32_e32 v12, v172, v12
	global_load_dwordx4 v[124:127], v169, s[10:11]
	v_add_u32_e32 v0, 0x240, v83
	v_mul_u32_u24_e32 v167, 0xaaab, v0
	v_lshrrev_b32_e32 v167, 20, v167
	v_mad_i32_i24 v168, v167, s13, v0
	v_add_u32_e32 v169, s12, v167
	v_ashrrev_i32_e32 v168, 3, v168
	v_max_i32_e32 v169, 0, v169
	v_mul_u32_u24_e32 v169, 0x1a00, v169
	v_mad_u32_u24 v13, v167, s49, v130
	v_lshl_add_u32 v169, v168, 11, v169
	v_lshl_add_u32 v13, v168, 7, v13
	v_add3_u32 v169, v169, v173, v172
	v_add_u32_e32 v13, v172, v13
	global_load_dwordx4 v[140:143], v169, s[10:11]
	v_add_u32_e32 v0, 0x280, v83
	v_mul_u32_u24_e32 v167, 0xaaab, v0
	v_lshrrev_b32_e32 v167, 20, v167
	v_mad_i32_i24 v168, v167, s13, v0
	v_add_u32_e32 v169, s12, v167
	v_ashrrev_i32_e32 v168, 3, v168
	v_max_i32_e32 v169, 0, v169
	v_mul_u32_u24_e32 v169, 0x1a00, v169
	v_mad_u32_u24 v14, v167, s49, v130
	v_lshl_add_u32 v169, v168, 11, v169
	v_lshl_add_u32 v14, v168, 7, v14
	v_add3_u32 v169, v169, v173, v172
	v_add_u32_e32 v14, v172, v14
	global_load_dwordx4 v[144:147], v169, s[10:11]
	v_add_u32_e32 v0, 0x2c0, v83
	v_mul_u32_u24_e32 v167, 0xaaab, v0
	v_lshrrev_b32_e32 v167, 20, v167
	v_mad_i32_i24 v168, v167, s13, v0
	v_add_u32_e32 v169, s12, v167
	v_ashrrev_i32_e32 v168, 3, v168
	v_max_i32_e32 v169, 0, v169
	v_mul_u32_u24_e32 v169, 0x1a00, v169
	v_mad_u32_u24 v15, v167, s49, v130
	v_lshl_add_u32 v169, v168, 11, v169
	v_lshl_add_u32 v15, v168, 7, v15
	v_add3_u32 v169, v169, v173, v172
	v_add_u32_e32 v15, v172, v15
	global_load_dwordx4 v[148:151], v169, s[10:11]
	v_cmp_gt_u32_e32 vcc, 24, v83
	s_and_b64 exec, exec, vcc
	v_add_u32_e32 v0, 0x300, v83
	v_mul_u32_u24_e32 v167, 0xaaab, v0
	v_lshrrev_b32_e32 v167, 20, v167
	v_mad_i32_i24 v168, v167, s13, v0
	v_add_u32_e32 v169, s12, v167
	v_ashrrev_i32_e32 v168, 3, v168
	v_max_i32_e32 v169, 0, v169
	v_mul_u32_u24_e32 v169, 0x1a00, v169
	v_mad_u32_u24 v16, v167, s49, v130
	v_lshl_add_u32 v169, v168, 11, v169
	v_lshl_add_u32 v16, v168, 7, v16
	v_add3_u32 v169, v169, v173, v172
	v_add_u32_e32 v16, v172, v16
	global_load_dwordx4 v[224:227], v169, s[10:11]
	s_mov_b64 exec, s[46:47]
	s_waitcnt vmcnt(12)
	ds_write_b128 v4, v[92:95] offset:16896
	s_waitcnt vmcnt(11)
	ds_write_b128 v5, v[96:99] offset:16896
	s_waitcnt vmcnt(10)
	ds_write_b128 v6, v[100:103] offset:16896
	s_waitcnt vmcnt(9)
	ds_write_b128 v7, v[104:107] offset:16896
	s_waitcnt vmcnt(8)
	ds_write_b128 v8, v[108:111] offset:16896
	s_waitcnt vmcnt(7)
	ds_write_b128 v9, v[112:115] offset:16896
	s_waitcnt vmcnt(6)
	ds_write_b128 v10, v[116:119] offset:16896
	s_waitcnt vmcnt(5)
	ds_write_b128 v11, v[120:123] offset:16896
	s_waitcnt vmcnt(4)
	ds_write_b128 v12, v[124:127] offset:16896
	s_waitcnt vmcnt(3)
	ds_write_b128 v13, v[140:143] offset:16896
	s_waitcnt vmcnt(2)
	ds_write_b128 v14, v[144:147] offset:16896
	s_waitcnt vmcnt(1)
	ds_write_b128 v15, v[148:151] offset:16896
	s_waitcnt vmcnt(0)
	s_and_b64 exec, exec, vcc
	ds_write_b128 v16, v[224:227] offset:16896
	s_mov_b64 exec, s[46:47]
	s_movk_i32 s13, 0x2d7
	s_mov_b64 s[0:1], 0
	s_mov_b64 s[38:39], s[90:91]
	s_mov_b32 s18, s88
	s_or_b64 exec, exec, s[0:1]
	v_lshlrev_b32_e32 v2, 3, v139
	v_readlane_b32 s0, v255, 37
	v_lshlrev_b32_e32 v0, 2, v139
	v_ashrrev_i32_e32 v3, 31, v2
	v_readlane_b32 s1, v255, 38
	v_add_u32_e32 v94, s36, v0
	v_ashrrev_i32_e32 v95, 31, v94
	v_lshl_add_u64 v[96:97], v[2:3], 1, s[0:1]
	v_or_b32_e32 v2, 1, v94
	v_ashrrev_i32_e32 v3, 31, v2
	v_lshlrev_b64 v[100:101], 11, v[2:3]
	v_or_b32_e32 v2, 2, v94
	v_ashrrev_i32_e32 v3, 31, v2
	v_lshlrev_b64 v[102:103], 11, v[2:3]
	v_or_b32_e32 v2, 3, v94
	v_ashrrev_i32_e32 v3, 31, v2
	v_lshlrev_b64 v[104:105], 11, v[2:3]
	v_add_u32_e32 v2, 8, v94
	v_ashrrev_i32_e32 v3, 31, v2
	v_lshlrev_b64 v[106:107], 11, v[2:3]
	v_add_u32_e32 v2, 9, v94
	v_ashrrev_i32_e32 v3, 31, v2
	v_lshlrev_b64 v[108:109], 11, v[2:3]
	v_add_u32_e32 v2, 10, v94
	v_ashrrev_i32_e32 v3, 31, v2
	v_lshlrev_b64 v[110:111], 11, v[2:3]
	v_add_u32_e32 v2, 11, v94
	v_ashrrev_i32_e32 v3, 31, v2
	v_lshlrev_b64 v[112:113], 11, v[2:3]
	v_add_u32_e32 v2, 16, v94
	v_ashrrev_i32_e32 v3, 31, v2
	v_lshlrev_b64 v[114:115], 11, v[2:3]
	v_add_u32_e32 v2, 17, v94
	v_ashrrev_i32_e32 v3, 31, v2
	v_lshlrev_b64 v[116:117], 11, v[2:3]
	v_add_u32_e32 v2, 18, v94
	v_ashrrev_i32_e32 v3, 31, v2
	v_lshlrev_b64 v[118:119], 11, v[2:3]
	v_add_u32_e32 v2, 19, v94
	v_ashrrev_i32_e32 v3, 31, v2
	v_lshlrev_b64 v[120:121], 11, v[2:3]
	v_add_u32_e32 v2, 24, v94
	v_ashrrev_i32_e32 v3, 31, v2
	v_lshlrev_b64 v[122:123], 11, v[2:3]
	v_add_u32_e32 v2, 25, v94
	v_ashrrev_i32_e32 v3, 31, v2
	v_lshlrev_b64 v[124:125], 11, v[2:3]
	v_add_u32_e32 v2, 26, v94
	v_ashrrev_i32_e32 v3, 31, v2
	v_lshlrev_b64 v[126:127], 11, v[2:3]
	v_add_u32_e32 v2, 27, v94
	v_ashrrev_i32_e32 v3, 31, v2
	v_readlane_b32 s46, v250, 24
	v_add_u32_e32 v92, v88, v90
	v_lshlrev_b64 v[98:99], 11, v[94:95]
	v_lshlrev_b64 v[128:129], 11, v[2:3]
	s_mov_b32 s12, 0
	s_mov_b64 s[0:1], -1
	v_readlane_b32 s47, v250, 25
.LBB0_730:
	v_add_u32_e32 v144, s12, v92
	v_ashrrev_i32_e32 v145, 31, v144
	v_lshlrev_b64 v[2:3], 9, v[144:145]
	v_lshl_add_u64 v[146:147], v[96:97], 0, v[2:3]
	global_load_dwordx4 v[140:143], v[146:147], off offset:256
	global_load_dwordx4 v[148:151], v[146:147], off offset:288
	global_load_dwordx4 v[224:227], v[146:147], off offset:320
	global_load_dwordx4 v[228:231], v[146:147], off offset:352
	global_load_dwordx4 v[232:235], v[146:147], off offset:384
	global_load_dwordx4 v[236:239], v[146:147], off offset:416
	global_load_dwordx4 v[240:243], v[146:147], off offset:448
	global_load_dwordx4 v[244:247], v[146:147], off offset:480
	s_mov_b32 s12, 32
	s_and_b64 vcc, exec, s[0:1]
	s_waitcnt vmcnt(7) lgkmcnt(8)
	v_mfma_f32_32x32x16_bf16 v[2:17], v[18:21], v[140:143], 0
	s_waitcnt vmcnt(6) lgkmcnt(7)
	v_mfma_f32_32x32x16_bf16 v[2:17], v[22:25], v[148:151], v[2:17]
	s_waitcnt vmcnt(5) lgkmcnt(6)
	v_mfma_f32_32x32x16_bf16 v[2:17], v[26:29], v[224:227], v[2:17]
	s_waitcnt vmcnt(4) lgkmcnt(5)
	v_mfma_f32_32x32x16_bf16 v[2:17], v[30:33], v[228:231], v[2:17]
	s_waitcnt vmcnt(3) lgkmcnt(4)
	v_mfma_f32_32x32x16_bf16 v[2:17], v[66:69], v[232:235], v[2:17]
	s_waitcnt vmcnt(2) lgkmcnt(3)
	v_mfma_f32_32x32x16_bf16 v[2:17], v[70:73], v[236:239], v[2:17]
	s_waitcnt vmcnt(1) lgkmcnt(2)
	v_mfma_f32_32x32x16_bf16 v[2:17], v[74:77], v[240:243], v[2:17]
	s_waitcnt vmcnt(0) lgkmcnt(1)
	v_mfma_f32_32x32x16_bf16 v[2:17], v[78:81], v[244:247], v[2:17]
	v_lshl_add_u64 v[140:141], v[144:145], 1, s[46:47]
	v_lshl_add_u64 v[142:143], v[140:141], 0, v[98:99]
	s_nop 9
	v_cvt_pk_bf16_f32 v2, v2, s0
	global_store_short v[142:143], v2, off
	v_cvt_pk_bf16_f32 v87, v3, s0
	v_lshl_add_u64 v[2:3], v[140:141], 0, v[100:101]
	global_store_short v[2:3], v87, off
	v_cvt_pk_bf16_f32 v4, v4, s0
	v_lshl_add_u64 v[2:3], v[140:141], 0, v[102:103]
	global_store_short v[2:3], v4, off
	v_cvt_pk_bf16_f32 v4, v5, s0
	v_lshl_add_u64 v[2:3], v[140:141], 0, v[104:105]
	global_store_short v[2:3], v4, off
	v_cvt_pk_bf16_f32 v4, v6, s0
	v_lshl_add_u64 v[2:3], v[140:141], 0, v[106:107]
	global_store_short v[2:3], v4, off
	v_cvt_pk_bf16_f32 v4, v7, s0
	v_lshl_add_u64 v[2:3], v[140:141], 0, v[108:109]
	global_store_short v[2:3], v4, off
	v_cvt_pk_bf16_f32 v4, v8, s0
	v_lshl_add_u64 v[2:3], v[140:141], 0, v[110:111]
	global_store_short v[2:3], v4, off
	v_cvt_pk_bf16_f32 v4, v9, s0
	v_lshl_add_u64 v[2:3], v[140:141], 0, v[112:113]
	global_store_short v[2:3], v4, off
	v_cvt_pk_bf16_f32 v4, v10, s0
	v_lshl_add_u64 v[2:3], v[140:141], 0, v[114:115]
	global_store_short v[2:3], v4, off
	v_cvt_pk_bf16_f32 v4, v11, s0
	v_lshl_add_u64 v[2:3], v[140:141], 0, v[116:117]
	global_store_short v[2:3], v4, off
	v_cvt_pk_bf16_f32 v4, v12, s0
	v_lshl_add_u64 v[2:3], v[140:141], 0, v[118:119]
	global_store_short v[2:3], v4, off
	v_cvt_pk_bf16_f32 v4, v13, s0
	v_lshl_add_u64 v[2:3], v[140:141], 0, v[120:121]
	global_store_short v[2:3], v4, off
	v_cvt_pk_bf16_f32 v4, v14, s0
	v_lshl_add_u64 v[2:3], v[140:141], 0, v[122:123]
	global_store_short v[2:3], v4, off
	v_cvt_pk_bf16_f32 v4, v15, s0
	v_lshl_add_u64 v[2:3], v[140:141], 0, v[124:125]
	global_store_short v[2:3], v4, off
	v_cvt_pk_bf16_f32 v4, v16, s0
	v_lshl_add_u64 v[2:3], v[140:141], 0, v[126:127]
	global_store_short v[2:3], v4, off
	v_cvt_pk_bf16_f32 v4, v17, s0
	v_lshl_add_u64 v[2:3], v[140:141], 0, v[128:129]
	s_mov_b64 s[0:1], 0
	global_store_short v[2:3], v4, off
	s_cbranch_vccnz .LBB0_730
	s_add_i32 s0, s36, 0xffffe000
	s_ashr_i32 s12, s0, 4
	s_or_b32 s13, s12, 1
	s_and_b64 s[0:1], s[44:45], exec
	s_cselect_b32 s0, s13, 0
	v_readlane_b32 s64, v253, 58
	s_mul_hi_i32 s1, s0, 0x3400
	s_mulk_i32 s0, 0x3400
	v_readlane_b32 s78, v254, 8
	v_readlane_b32 s79, v254, 9
	s_add_u32 s48, s78, s0
	s_addc_u32 s49, s79, s1
	s_add_u32 s50, s48, 0x1000
	s_addc_u32 s51, s49, 0
	s_and_b64 s[0:1], s[44:45], exec
	s_cselect_b32 s0, s12, 0
	v_readlane_b32 s65, v253, 59
	v_readlane_b32 s66, v253, 60
	v_readlane_b32 s67, v253, 61
	v_readlane_b32 s68, v253, 62
	v_readlane_b32 s69, v253, 63
	v_readlane_b32 s70, v254, 0
	v_readlane_b32 s71, v254, 1
	v_readlane_b32 s72, v254, 2
	v_readlane_b32 s73, v254, 3
	v_readlane_b32 s74, v254, 4
	v_readlane_b32 s75, v254, 5
	s_mul_hi_i32 s1, s0, 0x3400
	s_mulk_i32 s0, 0x3400
	v_ashrrev_i32_e32 v93, 31, v92
	v_readlane_b32 s60, v251, 3
	s_add_u32 s52, s78, s0
	v_lshlrev_b64 v[2:3], 2, v[92:93]
	v_readlane_b32 s62, v251, 5
	v_readlane_b32 s63, v251, 6
	s_addc_u32 s53, s79, s1
	s_movk_i32 s13, 0x1000
	v_lshl_add_u64 v[4:5], s[62:63], 0, v[2:3]
	s_add_u32 s54, s52, 0x2000
	v_add_co_u32_e32 v4, vcc, s13, v4
	s_addc_u32 s55, s53, 0
	v_readlane_b32 s74, v251, 17
	v_readlane_b32 s75, v251, 18
	v_addc_co_u32_e32 v5, vcc, 0, v5, vcc
	s_add_u32 s56, s52, 0x1000
	global_load_dword v8, v[4:5], off
	v_lshl_add_u64 v[4:5], s[74:75], 0, v[2:3]
	s_addc_u32 s57, s53, 0
	global_load_dword v9, v[4:5], off
	v_lshl_add_u64 v[4:5], s[56:57], 0, v[2:3]
	global_load_dword v10, v[4:5], off
	v_lshl_add_u64 v[2:3], s[50:51], 0, v[2:3]
	global_load_dword v15, v[2:3], off
	v_readlane_b32 s61, v251, 4
	s_movk_i32 s61, 0x640
	v_and_b32_e32 v12, 12, v0
	v_and_b32_e32 v6, 0x7fc, v94
	v_ashrrev_i32_e32 v89, 31, v88
	v_mul_lo_u32 v5, v139, s61
	v_lshlrev_b32_e32 v11, 1, v88
	v_cndmask_b32_e64 v14, v6, v12, s[44:45]
	v_lshl_add_u64 v[6:7], v[88:89], 0, v[90:91]
	v_add_u32_e32 v4, 32, v92
	v_add3_u32 v13, v130, v5, v11
	v_lshlrev_b64 v[6:7], 2, v[6:7]
	v_ashrrev_i32_e32 v5, 31, v4
	ds_read_u16 v16, v13 offset:17424
	ds_read_u16 v17, v13 offset:17024
	ds_read_u16 v18, v13 offset:17824
	ds_read_u16 v19, v13 offset:18224
	ds_read_u16 v20, v13 offset:18288
	ds_read_u16 v21, v13 offset:17888
	ds_read_u16 v22, v13 offset:17488
	ds_read_u16 v23, v13 offset:17088
	ds_read_u16 v24, v13 offset:18624
	ds_read_u16 v25, v13 offset:20224
	ds_read_u16 v26, v13 offset:20624
	ds_read_u16 v27, v13 offset:21024
	ds_read_u16 v28, v13 offset:21088
	ds_read_u16 v29, v13 offset:20688
	ds_read_u16 v30, v13 offset:20288
	ds_read_u16 v31, v13 offset:18688
	v_lshl_add_u64 v[2:3], s[74:75], 0, v[6:7]
	v_lshlrev_b64 v[4:5], 2, v[4:5]
	global_load_dword v32, v[2:3], off offset:128
	s_waitcnt lgkmcnt(14)
	v_lshlrev_b32_e32 v16, 16, v16
	s_waitcnt lgkmcnt(13)
	v_lshlrev_b32_e32 v18, 16, v18
	s_waitcnt lgkmcnt(6)
	v_lshlrev_b32_e32 v2, 16, v25
	s_waitcnt lgkmcnt(5)
	v_lshlrev_b32_e32 v25, 16, v26
	v_lshlrev_b32_e32 v19, 16, v19
	s_waitcnt lgkmcnt(4)
	v_lshlrev_b32_e32 v26, 16, v27
	v_sub_f32_e32 v27, v16, v18
	v_sub_f32_e32 v67, v2, v25
	v_lshl_add_u64 v[2:3], s[50:51], 0, v[4:5]
	v_lshl_add_u64 v[4:5], s[56:57], 0, v[4:5]
	v_lshlrev_b32_e32 v24, 16, v24
	v_sub_f32_e32 v33, v18, v19
	global_load_dword v69, v[2:3], off
	s_nop 0
	global_load_dword v4, v[4:5], off
	v_lshlrev_b32_e32 v17, 16, v17
	v_sub_f32_e32 v66, v19, v24
	v_cmp_eq_u32_e32 vcc, 0, v14
	v_lshl_add_u64 v[6:7], s[62:63], 0, v[6:7]
	v_sub_f32_e32 v68, v25, v26
	v_add_u32_e32 v0, 16, v0
	s_movk_i32 s60, 0x190
	v_readlane_b32 s76, v254, 6
	v_readlane_b32 s77, v254, 7
	s_add_u32 s58, s48, 0x2000
	v_readlane_b32 s6, v255, 33
	v_readlane_b32 s8, v255, 35
	v_readlane_b32 s10, v255, 37
	v_readlane_b32 s76, v254, 45
	v_readlane_b32 s64, v251, 7
	v_readlane_b32 s65, v251, 8
	v_readlane_b32 s68, v251, 11
	v_readlane_b32 s69, v251, 12
	s_mov_b32 s12, 0
	s_addc_u32 s59, s49, 0
	v_ashrrev_i32_e32 v87, 31, v86
	v_readlane_b32 s7, v255, 34
	v_readlane_b32 s9, v255, 36
	v_readlane_b32 s11, v255, 38
	v_readlane_b32 s77, v254, 46
	v_readlane_b32 s78, v254, 47
	v_readlane_b32 s79, v254, 48
	v_readlane_b32 s66, v251, 9
	v_readlane_b32 s67, v251, 10
	v_readlane_b32 s70, v251, 13
	v_readlane_b32 s71, v251, 14
	v_readlane_b32 s72, v251, 15
	v_readlane_b32 s73, v251, 16
	v_readlane_b32 s80, v254, 49
	v_readlane_b32 s81, v254, 50
	v_readlane_b32 s82, v254, 51
	v_readlane_b32 s83, v254, 52
	v_readlane_b32 s84, v254, 53
	v_readlane_b32 s85, v254, 54
	v_readlane_b32 s86, v254, 55
	v_readlane_b32 s87, v254, 56
	v_readlane_b32 s88, v254, 57
	s_waitcnt vmcnt(6)
	v_fma_f32 v2, v8, v27, v18
	v_fma_f32 v3, v8, v33, v19
	v_fma_f32 v5, v8, v67, v25
	s_waitcnt vmcnt(5)
	v_mul_f32_e32 v19, v9, v2
	v_mul_f32_e32 v25, v9, v3
	s_waitcnt vmcnt(4)
	v_cndmask_b32_e64 v2, 0, v10, s[44:45]
	v_cndmask_b32_e32 v2, v17, v2, vcc
	v_sub_f32_e32 v2, v2, v16
	v_fma_f32 v2, v8, v2, v16
	v_mul_f32_e32 v10, v9, v2
	v_add_co_u32_e64 v2, s[0:1], s13, v6
	v_fma_f32 v18, v8, v68, v26
	s_nop 0
	v_addc_co_u32_e64 v3, s[0:1], 0, v7, s[0:1]
	global_load_dword v7, v[2:3], off offset:128
	ds_read_u16 v2, v13 offset:21424
	ds_read_u16 v3, v13 offset:21824
	ds_read_u16 v6, v13 offset:24224
	ds_read_u16 v14, v13 offset:24624
	ds_read_u16 v16, v13 offset:24688
	ds_read_u16 v17, v13 offset:24288
	ds_read_u16 v27, v13 offset:21888
	ds_read_u16 v33, v13 offset:21488
	s_waitcnt lgkmcnt(7)
	v_lshlrev_b32_e32 v2, 16, v2
	v_sub_f32_e32 v26, v26, v2
	s_waitcnt lgkmcnt(6)
	v_lshlrev_b32_e32 v3, 16, v3
	v_fma_f32 v26, v8, v26, v2
	v_sub_f32_e32 v2, v2, v3
	v_fmac_f32_e32 v3, v8, v2
	v_mul_lo_u32 v2, v0, s60
	v_add3_u32 v2, v130, v2, v11
	ds_read_u16 v11, v2 offset:17424
	v_fmac_f32_e32 v24, v8, v66
	ds_read_u16 v66, v2 offset:17024
	ds_read_u16 v67, v2 offset:17488
	ds_read_u16 v2, v2 offset:17088
	v_add_u32_e32 v0, s36, v0
	v_and_b32_e32 v0, 0x7fc, v0
	v_cndmask_b32_e64 v0, v0, v12, s[44:45]
	s_waitcnt vmcnt(4)
	v_cndmask_b32_e64 v12, 0, v15, s[44:45]
	s_waitcnt lgkmcnt(2)
	v_lshlrev_b32_e32 v15, 16, v66
	v_cmp_eq_u32_e64 s[0:1], 0, v0
	v_lshlrev_b32_e32 v11, 16, v11
	v_lshlrev_b32_e32 v6, 16, v6
	v_cndmask_b32_e64 v0, v15, v12, s[0:1]
	v_sub_f32_e32 v0, v0, v11
	v_fma_f32 v0, v8, v0, v11
	v_sub_f32_e32 v11, v11, v6
	v_lshlrev_b32_e32 v12, 16, v14
	v_fma_f32 v11, v8, v11, v6
	v_sub_f32_e32 v6, v6, v12
	v_fma_f32 v6, v8, v6, v12
	v_mul_f32_e32 v14, v9, v6
	ds_read_u16 v6, v13 offset:25024
	ds_read_u16 v15, v13 offset:26624
	ds_read_u16 v66, v13 offset:27024
	ds_read_u16 v68, v13 offset:27424
	ds_read_u16 v70, v13 offset:27488
	ds_read_u16 v71, v13 offset:27088
	ds_read_u16 v72, v13 offset:26688
	ds_read_u16 v73, v13 offset:25088
	s_waitcnt lgkmcnt(7)
	v_lshlrev_b32_e32 v6, 16, v6
	v_sub_f32_e32 v12, v12, v6
	v_fmac_f32_e32 v6, v8, v12
	v_mul_f32_e32 v12, v9, v6
	s_waitcnt lgkmcnt(6)
	v_lshlrev_b32_e32 v6, 16, v15
	s_waitcnt lgkmcnt(5)
	v_lshlrev_b32_e32 v15, 16, v66
	v_sub_f32_e32 v6, v6, v15
	v_fma_f32 v6, v8, v6, v15
	v_mul_f32_e32 v66, v9, v6
	s_waitcnt lgkmcnt(4)
	v_lshlrev_b32_e32 v6, 16, v68
	ds_read_u16 v68, v13 offset:27824
	v_sub_f32_e32 v15, v15, v6
	ds_read_u16 v74, v13 offset:28224
	ds_read_u16 v75, v13 offset:28288
	ds_read_u16 v13, v13 offset:27888
	v_fma_f32 v15, v8, v15, v6
	v_mul_f32_e32 v24, v9, v24
	s_waitcnt lgkmcnt(3)
	v_lshlrev_b32_e32 v68, 16, v68
	v_sub_f32_e32 v6, v6, v68
	v_fma_f32 v6, v8, v6, v68
	v_mul_f32_e32 v76, v9, v6
	s_waitcnt lgkmcnt(2)
	v_lshlrev_b32_e32 v6, 16, v74
	v_sub_f32_e32 v68, v68, v6
	v_fmac_f32_e32 v6, v8, v68
	v_mul_f32_e32 v5, v9, v5
	v_mul_f32_e32 v18, v9, v18
	v_mul_f32_e32 v26, v9, v26
	v_mul_f32_e32 v3, v9, v3
	v_mul_f32_e32 v0, v9, v0
	v_mul_f32_e32 v11, v9, v11
	v_mul_f32_e32 v15, v9, v15
	v_mul_f32_e32 v8, v9, v6
	s_waitcnt vmcnt(1)
	v_cndmask_b32_e64 v4, 0, v4, s[44:45]
	v_lshlrev_b32_e32 v9, 16, v23
	v_lshlrev_b32_e32 v6, 16, v22
	v_cndmask_b32_e32 v4, v9, v4, vcc
	v_sub_f32_e32 v4, v4, v6
	v_lshlrev_b32_e32 v2, 16, v2
	s_mov_b32 s13, 0xf800000
	v_readlane_b32 s89, v254, 58
	v_readlane_b32 s90, v254, 59
	v_readlane_b32 s91, v254, 60
	s_waitcnt vmcnt(0)
	v_fma_f32 v4, v7, v4, v6
	v_mul_f32_e32 v4, v32, v4
	v_mul_f32_e32 v9, v4, v4
	v_lshlrev_b32_e32 v4, 16, v21
	v_sub_f32_e32 v6, v6, v4
	v_fma_f32 v6, v7, v6, v4
	v_mul_f32_e32 v6, v32, v6
	v_fmac_f32_e32 v9, v10, v10
	v_mul_f32_e32 v10, v6, v6
	v_lshlrev_b32_e32 v6, 16, v20
	v_sub_f32_e32 v4, v4, v6
	v_fma_f32 v4, v7, v4, v6
	v_mul_f32_e32 v4, v32, v4
	v_fmac_f32_e32 v10, v19, v19
	v_mul_f32_e32 v19, v4, v4
	v_lshlrev_b32_e32 v4, 16, v31
	v_sub_f32_e32 v6, v6, v4
	v_fmac_f32_e32 v4, v7, v6
	v_mul_f32_e32 v4, v32, v4
	v_mul_f32_e32 v20, v4, v4
	v_lshlrev_b32_e32 v4, 16, v30
	v_lshlrev_b32_e32 v6, 16, v29
	v_sub_f32_e32 v4, v4, v6
	v_fma_f32 v4, v7, v4, v6
	v_mul_f32_e32 v4, v32, v4
	v_mul_f32_e32 v21, v4, v4
	v_lshlrev_b32_e32 v4, 16, v28
	v_fmac_f32_e32 v21, v5, v5
	v_sub_f32_e32 v5, v6, v4
	v_fma_f32 v5, v7, v5, v4
	v_mul_f32_e32 v5, v32, v5
	v_mul_f32_e32 v22, v5, v5
	v_lshlrev_b32_e32 v5, 16, v33
	v_sub_f32_e32 v4, v4, v5
	v_fma_f32 v4, v7, v4, v5
	v_mul_f32_e32 v4, v32, v4
	v_fmac_f32_e32 v22, v18, v18
	v_mul_f32_e32 v18, v4, v4
	v_lshlrev_b32_e32 v4, 16, v27
	v_sub_f32_e32 v5, v5, v4
	v_fmac_f32_e32 v4, v7, v5
	v_mul_f32_e32 v4, v32, v4
	v_mul_f32_e32 v23, v4, v4
	v_cndmask_b32_e64 v4, 0, v69, s[44:45]
	v_fmac_f32_e32 v23, v3, v3
	v_lshlrev_b32_e32 v3, 16, v67
	v_cndmask_b32_e64 v2, v2, v4, s[0:1]
	v_sub_f32_e32 v2, v2, v3
	v_fma_f32 v2, v7, v2, v3
	v_mul_f32_e32 v2, v32, v2
	v_fmac_f32_e32 v20, v24, v24
	v_mul_f32_e32 v24, v2, v2
	v_fmac_f32_e32 v24, v0, v0
	v_lshlrev_b32_e32 v0, 16, v17
	v_sub_f32_e32 v2, v3, v0
	v_fma_f32 v2, v7, v2, v0
	v_mul_f32_e32 v2, v32, v2
	v_mul_f32_e32 v17, v2, v2
	v_lshlrev_b32_e32 v2, 16, v16
	v_sub_f32_e32 v0, v0, v2
	v_fma_f32 v0, v7, v0, v2
	v_mul_f32_e32 v0, v32, v0
	v_mul_f32_e32 v6, v0, v0
	v_lshlrev_b32_e32 v0, 16, v73
	v_sub_f32_e32 v2, v2, v0
	v_fmac_f32_e32 v0, v7, v2
	v_mul_f32_e32 v0, v32, v0
	v_mul_f32_e32 v5, v0, v0
	v_lshlrev_b32_e32 v0, 16, v72
	v_lshlrev_b32_e32 v2, 16, v71
	v_sub_f32_e32 v0, v0, v2
	v_fma_f32 v0, v7, v0, v2
	v_mul_f32_e32 v0, v32, v0
	v_mul_f32_e32 v4, v0, v0
	v_lshlrev_b32_e32 v0, 16, v70
	v_sub_f32_e32 v2, v2, v0
	v_fma_f32 v2, v7, v2, v0
	v_fmac_f32_e32 v17, v11, v11
	v_mul_f32_e32 v2, v32, v2
	s_waitcnt lgkmcnt(0)
	v_lshlrev_b32_e32 v11, 16, v13
	v_and_b32_e32 v13, 64, v163
	v_mul_f32_e32 v3, v2, v2
	v_xor_b32_e32 v2, 16, v163
	v_add_u32_e32 v13, 64, v13
	v_cmp_lt_i32_e32 vcc, v2, v13
	v_sub_f32_e32 v0, v0, v11
	v_fma_f32 v0, v7, v0, v11
	v_cndmask_b32_e32 v2, v163, v2, vcc
	v_lshlrev_b32_e32 v89, 2, v2
	v_mul_f32_e32 v0, v32, v0
	v_add_f32_dpp v2, v9, v9 row_ror:8 row_mask:0xf bank_mask:0xf bound_ctrl:1
	v_fmac_f32_e32 v5, v12, v12
	v_lshlrev_b32_e32 v12, 16, v75
	v_add_f32_dpp v2, v2, v2 row_ror:4 row_mask:0xf bank_mask:0xf bound_ctrl:1
	v_sub_f32_e32 v11, v11, v12
	v_fmac_f32_e32 v12, v7, v11
	v_add_f32_dpp v2, v2, v2 row_ror:2 row_mask:0xf bank_mask:0xf bound_ctrl:1
	v_add_f32_dpp v10, v10, v10 row_ror:8 row_mask:0xf bank_mask:0xf bound_ctrl:1
	v_fmac_f32_e32 v6, v14, v14
	v_add_f32_dpp v9, v2, v2 row_ror:1 row_mask:0xf bank_mask:0xf bound_ctrl:1
	ds_bpermute_b32 v13, v89, v9
	v_mul_f32_e32 v2, v0, v0
	v_add_f32_dpp v10, v10, v10 row_ror:4 row_mask:0xf bank_mask:0xf bound_ctrl:1
	v_fmac_f32_e32 v19, v25, v25
	v_fmac_f32_e32 v18, v26, v26
	s_waitcnt lgkmcnt(0)
	v_add_f32_e32 v0, v9, v13
	v_mul_f32_e32 v9, 0x4f800000, v0
	v_cmp_gt_f32_e32 vcc, s13, v0
	v_add_f32_dpp v10, v10, v10 row_ror:2 row_mask:0xf bank_mask:0xf bound_ctrl:1
	v_add_f32_dpp v6, v6, v6 row_ror:8 row_mask:0xf bank_mask:0xf bound_ctrl:1
	v_cndmask_b32_e32 v0, v0, v9, vcc
	v_sqrt_f32_e32 v9, v0
	v_add_f32_dpp v10, v10, v10 row_ror:1 row_mask:0xf bank_mask:0xf bound_ctrl:1
	v_add_f32_dpp v6, v6, v6 row_ror:4 row_mask:0xf bank_mask:0xf bound_ctrl:1
	v_add_f32_dpp v5, v5, v5 row_ror:8 row_mask:0xf bank_mask:0xf bound_ctrl:1
	v_add_u32_e32 v7, -1, v9
	v_fma_f32 v11, -v7, v9, v0
	v_cmp_ge_f32_e64 s[0:1], 0, v11
	v_add_u32_e32 v11, 1, v9
	v_add_f32_dpp v6, v6, v6 row_ror:2 row_mask:0xf bank_mask:0xf bound_ctrl:1
	v_cndmask_b32_e64 v7, v9, v7, s[0:1]
	v_fma_f32 v9, -v11, v9, v0
	v_cmp_lt_f32_e64 s[0:1], 0, v9
	v_add_f32_dpp v6, v6, v6 row_ror:1 row_mask:0xf bank_mask:0xf bound_ctrl:1
	v_add_f32_dpp v5, v5, v5 row_ror:4 row_mask:0xf bank_mask:0xf bound_ctrl:1
	v_cndmask_b32_e64 v7, v7, v11, s[0:1]
	v_mul_f32_e32 v9, 0x37800000, v7
	v_cndmask_b32_e32 v7, v7, v9, vcc
	v_cmp_class_f32_e32 vcc, v0, v202
	v_add_f32_dpp v5, v5, v5 row_ror:2 row_mask:0xf bank_mask:0xf bound_ctrl:1
	v_fmac_f32_e32 v4, v66, v66
	v_cndmask_b32_e32 v0, v7, v0, vcc
	v_max_f32_e32 v7, 0x2b8cbccc, v0
	v_mul_f32_e32 v0, v32, v12
	ds_bpermute_b32 v12, v89, v10
	v_div_scale_f32 v9, s[0:1], v7, v7, 1.0
	v_rcp_f32_e32 v11, v9
	v_mul_f32_e32 v0, v0, v0
	s_waitcnt lgkmcnt(0)
	v_add_f32_e32 v10, v10, v12
	v_mul_f32_e32 v12, 0x4f800000, v10
	v_cmp_gt_f32_e64 s[0:1], s13, v10
	v_fmac_f32_e32 v0, v8, v8
	v_fma_f32 v8, -v9, v11, 1.0
	v_cndmask_b32_e64 v10, v10, v12, s[0:1]
	v_fmac_f32_e32 v11, v8, v11
	v_div_scale_f32 v8, vcc, 1.0, v7, 1.0
	v_sqrt_f32_e32 v12, v10
	v_mul_f32_e32 v13, v8, v11
	v_fma_f32 v14, -v9, v13, v8
	v_fmac_f32_e32 v13, v14, v11
	v_fma_f32 v8, -v9, v13, v8
	v_add_u32_e32 v9, -1, v12
	v_fma_f32 v14, -v9, v12, v10
	v_cmp_ge_f32_e64 s[46:47], 0, v14
	v_add_u32_e32 v14, 1, v12
	v_div_fmas_f32 v8, v8, v11, v13
	v_cndmask_b32_e64 v9, v12, v9, s[46:47]
	v_fma_f32 v12, -v14, v12, v10
	v_cmp_lt_f32_e64 s[46:47], 0, v12
	v_div_fixup_f32 v91, v8, v7, 1.0
	v_add_f32_dpp v8, v19, v19 row_ror:8 row_mask:0xf bank_mask:0xf bound_ctrl:1
	v_cndmask_b32_e64 v9, v9, v14, s[46:47]
	v_mul_f32_e32 v12, 0x37800000, v9
	v_add_f32_dpp v8, v8, v8 row_ror:4 row_mask:0xf bank_mask:0xf bound_ctrl:1
	v_cndmask_b32_e64 v9, v9, v12, s[0:1]
	v_cmp_class_f32_e64 s[0:1], v10, v202
	v_add_f32_dpp v8, v8, v8 row_ror:2 row_mask:0xf bank_mask:0xf bound_ctrl:1
	v_add_f32_dpp v5, v5, v5 row_ror:1 row_mask:0xf bank_mask:0xf bound_ctrl:1
	v_cndmask_b32_e64 v9, v9, v10, s[0:1]
	v_add_f32_dpp v8, v8, v8 row_ror:1 row_mask:0xf bank_mask:0xf bound_ctrl:1
	ds_bpermute_b32 v11, v89, v8
	v_max_f32_e32 v9, 0x2b8cbccc, v9
	v_div_scale_f32 v10, s[0:1], v9, v9, 1.0
	v_rcp_f32_e32 v12, v10
	s_waitcnt lgkmcnt(0)
	v_add_f32_e32 v8, v8, v11
	v_mul_f32_e32 v11, 0x4f800000, v8
	v_cmp_gt_f32_e64 s[0:1], s13, v8
	v_fma_f32 v7, -v10, v12, 1.0
	v_fmac_f32_e32 v12, v7, v12
	v_cndmask_b32_e64 v8, v8, v11, s[0:1]
	v_div_scale_f32 v7, vcc, 1.0, v9, 1.0
	v_sqrt_f32_e32 v11, v8
	v_mul_f32_e32 v13, v7, v12
	v_fma_f32 v14, -v10, v13, v7
	v_fmac_f32_e32 v13, v14, v12
	v_fma_f32 v7, -v10, v13, v7
	v_add_u32_e32 v10, -1, v11
	v_fma_f32 v14, -v10, v11, v8
	v_cmp_ge_f32_e64 s[46:47], 0, v14
	v_add_u32_e32 v14, 1, v11
	v_div_fmas_f32 v7, v7, v12, v13
	v_cndmask_b32_e64 v10, v11, v10, s[46:47]
	v_fma_f32 v11, -v14, v11, v8
	v_cmp_lt_f32_e64 s[46:47], 0, v11
	v_div_fixup_f32 v110, v7, v9, 1.0
	v_add_f32_dpp v9, v20, v20 row_ror:8 row_mask:0xf bank_mask:0xf bound_ctrl:1
	v_cndmask_b32_e64 v10, v10, v14, s[46:47]
	v_mul_f32_e32 v11, 0x37800000, v10
	v_add_f32_dpp v9, v9, v9 row_ror:4 row_mask:0xf bank_mask:0xf bound_ctrl:1
	v_cndmask_b32_e64 v10, v10, v11, s[0:1]
	v_cmp_class_f32_e64 s[0:1], v8, v202
	v_add_f32_dpp v9, v9, v9 row_ror:2 row_mask:0xf bank_mask:0xf bound_ctrl:1
	v_add_f32_dpp v4, v4, v4 row_ror:8 row_mask:0xf bank_mask:0xf bound_ctrl:1
	v_cndmask_b32_e64 v8, v10, v8, s[0:1]
	v_add_f32_dpp v9, v9, v9 row_ror:1 row_mask:0xf bank_mask:0xf bound_ctrl:1
	ds_bpermute_b32 v12, v89, v9
	v_max_f32_e32 v8, 0x2b8cbccc, v8
	v_div_scale_f32 v10, s[0:1], v8, v8, 1.0
	v_rcp_f32_e32 v11, v10
	s_waitcnt lgkmcnt(0)
	v_add_f32_e32 v9, v9, v12
	v_mul_f32_e32 v12, 0x4f800000, v9
	v_cmp_gt_f32_e64 s[0:1], s13, v9
	v_fma_f32 v7, -v10, v11, 1.0
	v_fmac_f32_e32 v11, v7, v11
	v_cndmask_b32_e64 v9, v9, v12, s[0:1]
	v_div_scale_f32 v7, vcc, 1.0, v8, 1.0
	v_sqrt_f32_e32 v12, v9
	v_mul_f32_e32 v13, v7, v11
	v_fma_f32 v14, -v10, v13, v7
	v_fmac_f32_e32 v13, v14, v11
	v_fma_f32 v7, -v10, v13, v7
	v_add_u32_e32 v10, -1, v12
	v_fma_f32 v14, -v10, v12, v9
	v_cmp_ge_f32_e64 s[46:47], 0, v14
	v_add_u32_e32 v14, 1, v12
	v_div_fmas_f32 v7, v7, v11, v13
	v_cndmask_b32_e64 v10, v12, v10, s[46:47]
	v_fma_f32 v12, -v14, v12, v9
	v_cmp_lt_f32_e64 s[46:47], 0, v12
	v_div_fixup_f32 v111, v7, v8, 1.0
	v_add_f32_dpp v8, v21, v21 row_ror:8 row_mask:0xf bank_mask:0xf bound_ctrl:1
	v_cndmask_b32_e64 v10, v10, v14, s[46:47]
	v_mul_f32_e32 v12, 0x37800000, v10
	v_add_f32_dpp v8, v8, v8 row_ror:4 row_mask:0xf bank_mask:0xf bound_ctrl:1
	v_cndmask_b32_e64 v10, v10, v12, s[0:1]
	v_cmp_class_f32_e64 s[0:1], v9, v202
	v_add_f32_dpp v8, v8, v8 row_ror:2 row_mask:0xf bank_mask:0xf bound_ctrl:1
	v_add_f32_dpp v4, v4, v4 row_ror:4 row_mask:0xf bank_mask:0xf bound_ctrl:1
	v_cndmask_b32_e64 v9, v10, v9, s[0:1]
	v_add_f32_dpp v8, v8, v8 row_ror:1 row_mask:0xf bank_mask:0xf bound_ctrl:1
	ds_bpermute_b32 v11, v89, v8
	v_max_f32_e32 v9, 0x2b8cbccc, v9
	v_div_scale_f32 v10, s[0:1], v9, v9, 1.0
	v_rcp_f32_e32 v12, v10
	s_waitcnt lgkmcnt(0)
	v_add_f32_e32 v8, v8, v11
	v_mul_f32_e32 v11, 0x4f800000, v8
	v_cmp_gt_f32_e64 s[0:1], s13, v8
	v_fma_f32 v7, -v10, v12, 1.0
	v_fmac_f32_e32 v12, v7, v12
	v_cndmask_b32_e64 v8, v8, v11, s[0:1]
	v_div_scale_f32 v7, vcc, 1.0, v9, 1.0
	v_sqrt_f32_e32 v11, v8
	v_mul_f32_e32 v13, v7, v12
	v_fma_f32 v14, -v10, v13, v7
	v_fmac_f32_e32 v13, v14, v12
	v_fma_f32 v7, -v10, v13, v7
	v_add_u32_e32 v10, -1, v11
	v_fma_f32 v14, -v10, v11, v8
	v_cmp_ge_f32_e64 s[46:47], 0, v14
	v_add_u32_e32 v14, 1, v11
	v_div_fmas_f32 v7, v7, v12, v13
	v_cndmask_b32_e64 v10, v11, v10, s[46:47]
	v_fma_f32 v11, -v14, v11, v8
	v_cmp_lt_f32_e64 s[46:47], 0, v11
	v_div_fixup_f32 v112, v7, v9, 1.0
	v_add_f32_dpp v9, v22, v22 row_ror:8 row_mask:0xf bank_mask:0xf bound_ctrl:1
	v_cndmask_b32_e64 v10, v10, v14, s[46:47]
	v_mul_f32_e32 v11, 0x37800000, v10
	v_add_f32_dpp v9, v9, v9 row_ror:4 row_mask:0xf bank_mask:0xf bound_ctrl:1
	v_cndmask_b32_e64 v10, v10, v11, s[0:1]
	v_cmp_class_f32_e64 s[0:1], v8, v202
	v_add_f32_dpp v9, v9, v9 row_ror:2 row_mask:0xf bank_mask:0xf bound_ctrl:1
	v_add_f32_dpp v4, v4, v4 row_ror:2 row_mask:0xf bank_mask:0xf bound_ctrl:1
	v_cndmask_b32_e64 v8, v10, v8, s[0:1]
	v_add_f32_dpp v9, v9, v9 row_ror:1 row_mask:0xf bank_mask:0xf bound_ctrl:1
	ds_bpermute_b32 v12, v89, v9
	v_max_f32_e32 v8, 0x2b8cbccc, v8
	v_div_scale_f32 v10, s[0:1], v8, v8, 1.0
	v_rcp_f32_e32 v11, v10
	s_waitcnt lgkmcnt(0)
	v_add_f32_e32 v9, v9, v12
	v_mul_f32_e32 v12, 0x4f800000, v9
	v_cmp_gt_f32_e64 s[0:1], s13, v9
	v_fma_f32 v7, -v10, v11, 1.0
	v_fmac_f32_e32 v11, v7, v11
	v_cndmask_b32_e64 v9, v9, v12, s[0:1]
	v_div_scale_f32 v7, vcc, 1.0, v8, 1.0
	v_sqrt_f32_e32 v12, v9
	v_mul_f32_e32 v13, v7, v11
	v_fma_f32 v14, -v10, v13, v7
	v_fmac_f32_e32 v13, v14, v11
	v_fma_f32 v7, -v10, v13, v7
	v_add_u32_e32 v10, -1, v12
	v_fma_f32 v14, -v10, v12, v9
	v_cmp_ge_f32_e64 s[46:47], 0, v14
	v_add_u32_e32 v14, 1, v12
	v_div_fmas_f32 v7, v7, v11, v13
	v_cndmask_b32_e64 v10, v12, v10, s[46:47]
	v_fma_f32 v12, -v14, v12, v9
	v_cmp_lt_f32_e64 s[46:47], 0, v12
	v_div_fixup_f32 v113, v7, v8, 1.0
	v_add_f32_dpp v8, v18, v18 row_ror:8 row_mask:0xf bank_mask:0xf bound_ctrl:1
	v_cndmask_b32_e64 v10, v10, v14, s[46:47]
	v_mul_f32_e32 v12, 0x37800000, v10
	v_add_f32_dpp v8, v8, v8 row_ror:4 row_mask:0xf bank_mask:0xf bound_ctrl:1
	v_cndmask_b32_e64 v10, v10, v12, s[0:1]
	v_cmp_class_f32_e64 s[0:1], v9, v202
	v_add_f32_dpp v8, v8, v8 row_ror:2 row_mask:0xf bank_mask:0xf bound_ctrl:1
	v_add_f32_dpp v4, v4, v4 row_ror:1 row_mask:0xf bank_mask:0xf bound_ctrl:1
	v_cndmask_b32_e64 v9, v10, v9, s[0:1]
	v_add_f32_dpp v8, v8, v8 row_ror:1 row_mask:0xf bank_mask:0xf bound_ctrl:1
	ds_bpermute_b32 v11, v89, v8
	v_max_f32_e32 v9, 0x2b8cbccc, v9
	v_div_scale_f32 v10, s[0:1], v9, v9, 1.0
	v_rcp_f32_e32 v12, v10
	s_waitcnt lgkmcnt(0)
	v_add_f32_e32 v8, v8, v11
	v_mul_f32_e32 v11, 0x4f800000, v8
	v_cmp_gt_f32_e64 s[0:1], s13, v8
	v_fma_f32 v7, -v10, v12, 1.0
	v_fmac_f32_e32 v12, v7, v12
	v_cndmask_b32_e64 v8, v8, v11, s[0:1]
	v_div_scale_f32 v7, vcc, 1.0, v9, 1.0
	v_sqrt_f32_e32 v11, v8
	v_mul_f32_e32 v13, v7, v12
	v_fma_f32 v14, -v10, v13, v7
	v_fmac_f32_e32 v13, v14, v12
	v_fma_f32 v7, -v10, v13, v7
	v_add_u32_e32 v10, -1, v11
	v_fma_f32 v14, -v10, v11, v8
	v_cmp_ge_f32_e64 s[46:47], 0, v14
	v_add_u32_e32 v14, 1, v11
	v_div_fmas_f32 v7, v7, v12, v13
	v_cndmask_b32_e64 v10, v11, v10, s[46:47]
	v_fma_f32 v11, -v14, v11, v8
	v_cmp_lt_f32_e64 s[46:47], 0, v11
	v_div_fixup_f32 v114, v7, v9, 1.0
	v_add_f32_dpp v9, v23, v23 row_ror:8 row_mask:0xf bank_mask:0xf bound_ctrl:1
	v_cndmask_b32_e64 v10, v10, v14, s[46:47]
	v_mul_f32_e32 v11, 0x37800000, v10
	v_add_f32_dpp v9, v9, v9 row_ror:4 row_mask:0xf bank_mask:0xf bound_ctrl:1
	v_cndmask_b32_e64 v10, v10, v11, s[0:1]
	v_cmp_class_f32_e64 s[0:1], v8, v202
	v_add_f32_dpp v9, v9, v9 row_ror:2 row_mask:0xf bank_mask:0xf bound_ctrl:1
	v_fmac_f32_e32 v3, v15, v15
	v_cndmask_b32_e64 v8, v10, v8, s[0:1]
	v_add_f32_dpp v9, v9, v9 row_ror:1 row_mask:0xf bank_mask:0xf bound_ctrl:1
	ds_bpermute_b32 v12, v89, v9
	v_max_f32_e32 v8, 0x2b8cbccc, v8
	v_div_scale_f32 v10, s[0:1], v8, v8, 1.0
	v_rcp_f32_e32 v11, v10
	s_waitcnt lgkmcnt(0)
	v_add_f32_e32 v9, v9, v12
	v_mul_f32_e32 v12, 0x4f800000, v9
	v_cmp_gt_f32_e64 s[0:1], s13, v9
	v_fma_f32 v7, -v10, v11, 1.0
	v_fmac_f32_e32 v11, v7, v11
	v_cndmask_b32_e64 v9, v9, v12, s[0:1]
	v_div_scale_f32 v7, vcc, 1.0, v8, 1.0
	v_sqrt_f32_e32 v12, v9
	v_mul_f32_e32 v13, v7, v11
	v_fma_f32 v14, -v10, v13, v7
	v_fmac_f32_e32 v13, v14, v11
	v_fma_f32 v7, -v10, v13, v7
	v_add_u32_e32 v10, -1, v12
	v_fma_f32 v14, -v10, v12, v9
	v_cmp_ge_f32_e64 s[46:47], 0, v14
	v_add_u32_e32 v14, 1, v12
	v_div_fmas_f32 v7, v7, v11, v13
	v_cndmask_b32_e64 v10, v12, v10, s[46:47]
	v_fma_f32 v12, -v14, v12, v9
	v_cmp_lt_f32_e64 s[46:47], 0, v12
	v_div_fixup_f32 v115, v7, v8, 1.0
	v_add_f32_dpp v8, v24, v24 row_ror:8 row_mask:0xf bank_mask:0xf bound_ctrl:1
	v_cndmask_b32_e64 v10, v10, v14, s[46:47]
	v_mul_f32_e32 v12, 0x37800000, v10
	v_add_f32_dpp v8, v8, v8 row_ror:4 row_mask:0xf bank_mask:0xf bound_ctrl:1
	v_cndmask_b32_e64 v10, v10, v12, s[0:1]
	v_cmp_class_f32_e64 s[0:1], v9, v202
	v_add_f32_dpp v8, v8, v8 row_ror:2 row_mask:0xf bank_mask:0xf bound_ctrl:1
	v_add_f32_dpp v3, v3, v3 row_ror:8 row_mask:0xf bank_mask:0xf bound_ctrl:1
	v_cndmask_b32_e64 v9, v10, v9, s[0:1]
	v_add_f32_dpp v8, v8, v8 row_ror:1 row_mask:0xf bank_mask:0xf bound_ctrl:1
	ds_bpermute_b32 v11, v89, v8
	v_max_f32_e32 v9, 0x2b8cbccc, v9
	v_div_scale_f32 v10, s[0:1], v9, v9, 1.0
	v_rcp_f32_e32 v12, v10
	s_waitcnt lgkmcnt(0)
	v_add_f32_e32 v8, v8, v11
	v_mul_f32_e32 v11, 0x4f800000, v8
	v_cmp_gt_f32_e64 s[0:1], s13, v8
	v_fma_f32 v7, -v10, v12, 1.0
	v_fmac_f32_e32 v12, v7, v12
	v_cndmask_b32_e64 v8, v8, v11, s[0:1]
	v_div_scale_f32 v7, vcc, 1.0, v9, 1.0
	v_sqrt_f32_e32 v11, v8
	v_mul_f32_e32 v13, v7, v12
	v_fma_f32 v14, -v10, v13, v7
	v_fmac_f32_e32 v13, v14, v12
	v_fma_f32 v7, -v10, v13, v7
	v_add_u32_e32 v10, -1, v11
	v_fma_f32 v14, -v10, v11, v8
	v_cmp_ge_f32_e64 s[46:47], 0, v14
	v_add_u32_e32 v14, 1, v11
	v_div_fmas_f32 v7, v7, v12, v13
	v_cndmask_b32_e64 v10, v11, v10, s[46:47]
	v_fma_f32 v11, -v14, v11, v8
	v_cmp_lt_f32_e64 s[46:47], 0, v11
	v_div_fixup_f32 v116, v7, v9, 1.0
	v_add_f32_dpp v9, v17, v17 row_ror:8 row_mask:0xf bank_mask:0xf bound_ctrl:1
	v_cndmask_b32_e64 v10, v10, v14, s[46:47]
	v_mul_f32_e32 v11, 0x37800000, v10
	v_add_f32_dpp v9, v9, v9 row_ror:4 row_mask:0xf bank_mask:0xf bound_ctrl:1
	v_cndmask_b32_e64 v10, v10, v11, s[0:1]
	v_cmp_class_f32_e64 s[0:1], v8, v202
	v_add_f32_dpp v9, v9, v9 row_ror:2 row_mask:0xf bank_mask:0xf bound_ctrl:1
	v_add_f32_dpp v3, v3, v3 row_ror:4 row_mask:0xf bank_mask:0xf bound_ctrl:1
	v_cndmask_b32_e64 v8, v10, v8, s[0:1]
	v_add_f32_dpp v9, v9, v9 row_ror:1 row_mask:0xf bank_mask:0xf bound_ctrl:1
	ds_bpermute_b32 v12, v89, v9
	v_max_f32_e32 v8, 0x2b8cbccc, v8
	v_div_scale_f32 v10, s[0:1], v8, v8, 1.0
	v_rcp_f32_e32 v11, v10
	s_waitcnt lgkmcnt(0)
	v_add_f32_e32 v9, v9, v12
	v_mul_f32_e32 v12, 0x4f800000, v9
	v_cmp_gt_f32_e64 s[0:1], s13, v9
	v_fma_f32 v7, -v10, v11, 1.0
	v_fmac_f32_e32 v11, v7, v11
	v_cndmask_b32_e64 v9, v9, v12, s[0:1]
	v_div_scale_f32 v7, vcc, 1.0, v8, 1.0
	v_sqrt_f32_e32 v12, v9
	v_mul_f32_e32 v13, v7, v11
	v_fma_f32 v14, -v10, v13, v7
	v_fmac_f32_e32 v13, v14, v11
	v_fma_f32 v7, -v10, v13, v7
	v_add_u32_e32 v10, -1, v12
	v_fma_f32 v14, -v10, v12, v9
	v_cmp_ge_f32_e64 s[46:47], 0, v14
	v_add_u32_e32 v14, 1, v12
	v_div_fmas_f32 v7, v7, v11, v13
	v_cndmask_b32_e64 v10, v12, v10, s[46:47]
	v_fma_f32 v12, -v14, v12, v9
	v_cmp_lt_f32_e64 s[46:47], 0, v12
	v_div_fixup_f32 v117, v7, v8, 1.0
	ds_bpermute_b32 v8, v89, v6
	v_cndmask_b32_e64 v10, v10, v14, s[46:47]
	v_mul_f32_e32 v12, 0x37800000, v10
	v_cndmask_b32_e64 v10, v10, v12, s[0:1]
	v_cmp_class_f32_e64 s[0:1], v9, v202
	s_waitcnt lgkmcnt(0)
	v_add_f32_e32 v6, v6, v8
	v_mul_f32_e32 v8, 0x4f800000, v6
	v_cndmask_b32_e64 v9, v10, v9, s[0:1]
	v_max_f32_e32 v9, 0x2b8cbccc, v9
	v_div_scale_f32 v10, s[0:1], v9, v9, 1.0
	v_rcp_f32_e32 v12, v10
	v_cmp_gt_f32_e64 s[0:1], s13, v6
	v_add_f32_dpp v3, v3, v3 row_ror:2 row_mask:0xf bank_mask:0xf bound_ctrl:1
	v_fmac_f32_e32 v2, v76, v76
	v_fma_f32 v7, -v10, v12, 1.0
	v_cndmask_b32_e64 v6, v6, v8, s[0:1]
	v_fmac_f32_e32 v12, v7, v12
	v_div_scale_f32 v7, vcc, 1.0, v9, 1.0
	v_sqrt_f32_e32 v8, v6
	v_mul_f32_e32 v11, v7, v12
	v_fma_f32 v13, -v10, v11, v7
	v_fmac_f32_e32 v11, v13, v12
	v_fma_f32 v7, -v10, v11, v7
	v_add_u32_e32 v10, -1, v8
	v_fma_f32 v13, -v10, v8, v6
	v_cmp_ge_f32_e64 s[46:47], 0, v13
	v_add_u32_e32 v13, 1, v8
	v_div_fmas_f32 v7, v7, v12, v11
	v_cndmask_b32_e64 v10, v8, v10, s[46:47]
	v_fma_f32 v8, -v13, v8, v6
	v_cmp_lt_f32_e64 s[46:47], 0, v8
	v_div_fixup_f32 v118, v7, v9, 1.0
	ds_bpermute_b32 v9, v89, v5
	v_cndmask_b32_e64 v8, v10, v13, s[46:47]
	v_mul_f32_e32 v10, 0x37800000, v8
	v_cndmask_b32_e64 v8, v8, v10, s[0:1]
	v_cmp_class_f32_e64 s[0:1], v6, v202
	s_waitcnt lgkmcnt(0)
	v_add_f32_e32 v5, v5, v9
	v_mul_f32_e32 v9, 0x4f800000, v5
	v_cndmask_b32_e64 v6, v8, v6, s[0:1]
	v_max_f32_e32 v6, 0x2b8cbccc, v6
	v_div_scale_f32 v8, s[0:1], v6, v6, 1.0
	v_rcp_f32_e32 v10, v8
	v_cmp_gt_f32_e64 s[0:1], s13, v5
	v_add_f32_dpp v3, v3, v3 row_ror:1 row_mask:0xf bank_mask:0xf bound_ctrl:1
	v_add_f32_dpp v2, v2, v2 row_ror:8 row_mask:0xf bank_mask:0xf bound_ctrl:1
	v_fma_f32 v7, -v8, v10, 1.0
	v_cndmask_b32_e64 v5, v5, v9, s[0:1]
	v_fmac_f32_e32 v10, v7, v10
	v_div_scale_f32 v7, vcc, 1.0, v6, 1.0
	v_sqrt_f32_e32 v9, v5
	v_mul_f32_e32 v11, v7, v10
	v_fma_f32 v12, -v8, v11, v7
	v_fmac_f32_e32 v11, v12, v10
	v_fma_f32 v7, -v8, v11, v7
	v_add_u32_e32 v8, -1, v9
	v_fma_f32 v12, -v8, v9, v5
	v_cmp_ge_f32_e64 s[46:47], 0, v12
	v_add_u32_e32 v12, 1, v9
	v_div_fmas_f32 v7, v7, v10, v11
	v_cndmask_b32_e64 v8, v9, v8, s[46:47]
	v_fma_f32 v9, -v12, v9, v5
	v_cmp_lt_f32_e64 s[46:47], 0, v9
	v_div_fixup_f32 v119, v7, v6, 1.0
	ds_bpermute_b32 v7, v89, v4
	v_cndmask_b32_e64 v8, v8, v12, s[46:47]
	v_mul_f32_e32 v9, 0x37800000, v8
	v_cndmask_b32_e64 v8, v8, v9, s[0:1]
	v_cmp_class_f32_e64 s[0:1], v5, v202
	s_waitcnt lgkmcnt(0)
	v_add_f32_e32 v4, v4, v7
	v_mul_f32_e32 v7, 0x4f800000, v4
	v_cndmask_b32_e64 v5, v8, v5, s[0:1]
	v_max_f32_e32 v5, 0x2b8cbccc, v5
	v_div_scale_f32 v8, s[0:1], v5, v5, 1.0
	v_rcp_f32_e32 v9, v8
	v_cmp_gt_f32_e64 s[0:1], s13, v4
	v_add_f32_dpp v2, v2, v2 row_ror:4 row_mask:0xf bank_mask:0xf bound_ctrl:1
	v_add_f32_dpp v0, v0, v0 row_ror:8 row_mask:0xf bank_mask:0xf bound_ctrl:1
	v_fma_f32 v6, -v8, v9, 1.0
	v_cndmask_b32_e64 v4, v4, v7, s[0:1]
	v_fmac_f32_e32 v9, v6, v9
	v_div_scale_f32 v6, vcc, 1.0, v5, 1.0
	v_sqrt_f32_e32 v7, v4
	v_mul_f32_e32 v10, v6, v9
	v_fma_f32 v11, -v8, v10, v6
	v_fmac_f32_e32 v10, v11, v9
	v_fma_f32 v6, -v8, v10, v6
	v_add_u32_e32 v8, -1, v7
	v_fma_f32 v11, -v8, v7, v4
	v_cmp_ge_f32_e64 s[46:47], 0, v11
	v_add_u32_e32 v11, 1, v7
	v_div_fmas_f32 v6, v6, v9, v10
	v_cndmask_b32_e64 v8, v7, v8, s[46:47]
	v_fma_f32 v7, -v11, v7, v4
	v_cmp_lt_f32_e64 s[46:47], 0, v7
	v_div_fixup_f32 v120, v6, v5, 1.0
	ds_bpermute_b32 v6, v89, v3
	v_cndmask_b32_e64 v7, v8, v11, s[46:47]
	v_mul_f32_e32 v8, 0x37800000, v7
	v_cndmask_b32_e64 v7, v7, v8, s[0:1]
	v_cmp_class_f32_e64 s[0:1], v4, v202
	s_waitcnt lgkmcnt(0)
	v_add_f32_e32 v3, v3, v6
	v_mul_f32_e32 v6, 0x4f800000, v3
	v_cndmask_b32_e64 v4, v7, v4, s[0:1]
	v_max_f32_e32 v4, 0x2b8cbccc, v4
	v_div_scale_f32 v7, s[0:1], v4, v4, 1.0
	v_rcp_f32_e32 v8, v7
	v_cmp_gt_f32_e64 s[0:1], s13, v3
	v_add_f32_dpp v2, v2, v2 row_ror:2 row_mask:0xf bank_mask:0xf bound_ctrl:1
	v_add_f32_dpp v0, v0, v0 row_ror:4 row_mask:0xf bank_mask:0xf bound_ctrl:1
	v_fma_f32 v5, -v7, v8, 1.0
	v_cndmask_b32_e64 v3, v3, v6, s[0:1]
	v_fmac_f32_e32 v8, v5, v8
	v_div_scale_f32 v5, vcc, 1.0, v4, 1.0
	v_sqrt_f32_e32 v6, v3
	v_mul_f32_e32 v9, v5, v8
	v_fma_f32 v10, -v7, v9, v5
	v_fmac_f32_e32 v9, v10, v8
	v_fma_f32 v5, -v7, v9, v5
	v_add_u32_e32 v7, -1, v6
	v_fma_f32 v10, -v7, v6, v3
	v_cmp_ge_f32_e64 s[46:47], 0, v10
	v_add_u32_e32 v10, 1, v6
	v_div_fmas_f32 v5, v5, v8, v9
	v_cndmask_b32_e64 v7, v6, v7, s[46:47]
	v_fma_f32 v6, -v10, v6, v3
	v_cmp_lt_f32_e64 s[46:47], 0, v6
	v_add_f32_dpp v2, v2, v2 row_ror:1 row_mask:0xf bank_mask:0xf bound_ctrl:1
	v_div_fixup_f32 v121, v5, v4, 1.0
	v_cndmask_b32_e64 v6, v7, v10, s[46:47]
	v_mul_f32_e32 v7, 0x37800000, v6
	v_cndmask_b32_e64 v6, v6, v7, s[0:1]
	v_cmp_class_f32_e64 s[0:1], v3, v202
	ds_bpermute_b32 v5, v89, v2
	v_add_f32_dpp v0, v0, v0 row_ror:2 row_mask:0xf bank_mask:0xf bound_ctrl:1
	v_cndmask_b32_e64 v3, v6, v3, s[0:1]
	v_max_f32_e32 v3, 0x2b8cbccc, v3
	v_div_scale_f32 v6, s[0:1], v3, v3, 1.0
	v_rcp_f32_e32 v7, v6
	s_waitcnt lgkmcnt(0)
	v_add_f32_e32 v2, v2, v5
	v_mul_f32_e32 v5, 0x4f800000, v2
	v_cmp_gt_f32_e64 s[0:1], s13, v2
	v_fma_f32 v4, -v6, v7, 1.0
	v_fmac_f32_e32 v7, v4, v7
	v_cndmask_b32_e64 v2, v2, v5, s[0:1]
	v_div_scale_f32 v4, vcc, 1.0, v3, 1.0
	v_sqrt_f32_e32 v5, v2
	v_mul_f32_e32 v8, v4, v7
	v_fma_f32 v9, -v6, v8, v4
	v_fmac_f32_e32 v8, v9, v7
	v_fma_f32 v4, -v6, v8, v4
	v_add_u32_e32 v6, -1, v5
	v_fma_f32 v9, -v6, v5, v2
	v_cmp_ge_f32_e64 s[46:47], 0, v9
	v_add_u32_e32 v9, 1, v5
	v_div_fmas_f32 v4, v4, v7, v8
	v_cndmask_b32_e64 v6, v5, v6, s[46:47]
	v_fma_f32 v5, -v9, v5, v2
	v_cmp_lt_f32_e64 s[46:47], 0, v5
	v_add_f32_dpp v0, v0, v0 row_ror:1 row_mask:0xf bank_mask:0xf bound_ctrl:1
	v_div_fixup_f32 v122, v4, v3, 1.0
	v_cndmask_b32_e64 v5, v6, v9, s[46:47]
	v_mul_f32_e32 v6, 0x37800000, v5
	v_cndmask_b32_e64 v5, v5, v6, s[0:1]
	v_cmp_class_f32_e64 s[0:1], v2, v202
	ds_bpermute_b32 v4, v89, v0
	v_mov_b32_e32 v66, 0
	v_cndmask_b32_e64 v2, v5, v2, s[0:1]
	v_max_f32_e32 v2, 0x2b8cbccc, v2
	v_div_scale_f32 v5, s[0:1], v2, v2, 1.0
	v_rcp_f32_e32 v6, v5
	s_waitcnt lgkmcnt(0)
	v_add_f32_e32 v0, v0, v4
	v_mul_f32_e32 v4, 0x4f800000, v0
	v_cmp_gt_f32_e64 s[0:1], s13, v0
	v_fma_f32 v3, -v5, v6, 1.0
	v_fmac_f32_e32 v6, v3, v6
	v_cndmask_b32_e64 v0, v0, v4, s[0:1]
	v_div_scale_f32 v3, vcc, 1.0, v2, 1.0
	v_sqrt_f32_e32 v4, v0
	v_mul_f32_e32 v7, v3, v6
	v_fma_f32 v8, -v5, v7, v3
	v_fmac_f32_e32 v7, v8, v6
	v_fma_f32 v3, -v5, v7, v3
	v_add_u32_e32 v5, -1, v4
	v_fma_f32 v8, -v5, v4, v0
	v_cmp_ge_f32_e64 s[46:47], 0, v8
	v_add_u32_e32 v8, 1, v4
	v_div_fmas_f32 v3, v3, v6, v7
	v_cndmask_b32_e64 v5, v4, v5, s[46:47]
	v_fma_f32 v4, -v8, v4, v0
	v_cmp_lt_f32_e64 s[46:47], 0, v4
	v_div_fixup_f32 v123, v3, v2, 1.0
	v_mov_b32_e32 v67, v66
	v_cndmask_b32_e64 v4, v5, v8, s[46:47]
	v_mul_f32_e32 v5, 0x37800000, v4
	v_cndmask_b32_e64 v4, v4, v5, s[0:1]
	v_cmp_class_f32_e64 s[0:1], v0, v202
	s_mov_b64 s[46:47], -1
	v_mov_b32_e32 v68, v66
	v_cndmask_b32_e64 v0, v4, v0, s[0:1]
	v_max_f32_e32 v0, 0x2b8cbccc, v0
	v_div_scale_f32 v4, s[0:1], v0, v0, 1.0
	v_rcp_f32_e32 v5, v4
	v_mov_b32_e32 v69, v66
	v_mov_b32_e32 v70, v66
	v_mov_b32_e32 v71, v66
	v_fma_f32 v2, -v4, v5, 1.0
	v_fmac_f32_e32 v5, v2, v5
	v_div_scale_f32 v2, vcc, 1.0, v0, 1.0
	v_mul_f32_e32 v3, v2, v5
	v_fma_f32 v6, -v4, v3, v2
	v_fmac_f32_e32 v3, v6, v5
	v_fma_f32 v2, -v4, v3, v2
	v_div_fmas_f32 v2, v2, v5, v3
	v_div_fixup_f32 v124, v2, v0, 1.0
	v_mov_b32_e32 v72, v66
	v_mov_b32_e32 v73, v66
	v_mov_b32_e32 v74, v66
	v_mov_b32_e32 v75, v66
	v_mov_b32_e32 v76, v66
	v_mov_b32_e32 v77, v66
	v_mov_b32_e32 v78, v66
	v_mov_b32_e32 v79, v66
	v_mov_b32_e32 v80, v66
	v_mov_b32_e32 v81, v66
	s_movk_i32 s13, 0x2000
.LBB0_732:
	s_nop 0
	v_add_u32_e32 v102, s12, v88
	v_add_u32_e32 v92, v102, v90
	v_ashrrev_i32_e32 v93, 31, v92
	v_lshlrev_b64 v[2:3], 9, v[92:93]
	v_lshlrev_b32_e32 v4, 3, v139
	v_lshl_add_u64 v[2:3], s[10:11], 0, v[2:3]
	v_ashrrev_i32_e32 v5, 31, v4
	v_lshl_add_u64 v[26:27], v[4:5], 1, v[2:3]
	global_load_dwordx4 v[18:21], v[26:27], off
	global_load_dwordx4 v[94:97], v[26:27], off offset:32
	global_load_dwordx4 v[98:101], v[26:27], off offset:64
	global_load_dwordx4 v[104:107], v[26:27], off offset:96
	global_load_dwordx4 v[2:5], v[26:27], off offset:128
	global_load_dwordx4 v[22:25], v[26:27], off offset:160
	global_load_dwordx4 v[148:151], v[26:27], off offset:192
	global_load_dwordx4 v[224:227], v[26:27], off offset:224
	v_lshlrev_b32_e32 v140, 1, v102
	v_ashrrev_i32_e32 v103, 31, v102
	v_lshlrev_b32_e32 v146, 2, v139
	v_and_b32_e32 v144, 12, v146
	s_mov_b32 s12, 32
	s_waitcnt vmcnt(3)
	v_mfma_f32_32x32x16_bf16 v[2:17], v[50:53], v[2:5], 0
	s_waitcnt vmcnt(2)
	v_mfma_f32_32x32x16_bf16 v[2:17], v[54:57], v[22:25], v[2:17]
	s_waitcnt vmcnt(1)
	v_mfma_f32_32x32x16_bf16 v[2:17], v[58:61], v[148:151], v[2:17]
	s_waitcnt vmcnt(0)
	v_mfma_f32_32x32x16_bf16 v[2:17], v[62:65], v[224:227], v[2:17]
	v_mfma_f32_32x32x16_bf16 v[18:33], v[34:37], v[18:21], 0
	v_mfma_f32_32x32x16_bf16 v[18:33], v[38:41], v[94:97], v[18:33]
	v_mfma_f32_32x32x16_bf16 v[18:33], v[42:45], v[98:101], v[18:33]
	v_lshl_add_u64 v[100:101], v[102:103], 2, s[8:9]
	v_lshl_add_u64 v[98:99], v[102:103], 1, s[6:7]
	v_mfma_f32_32x32x16_bf16 v[18:33], v[46:49], v[104:107], v[18:33]
	v_lshlrev_b64 v[104:105], 2, v[92:93]
	v_lshl_add_u64 v[94:95], s[64:65], 0, v[104:105]
	v_lshl_add_u64 v[96:97], s[78:79], 0, v[104:105]
	global_load_dword v129, v[94:95], off
	v_lshl_add_u64 v[94:95], s[68:69], 0, v[104:105]
	global_load_dword v0, v[96:97], off
	v_lshl_add_u64 v[96:97], s[62:63], 0, v[104:105]
	global_load_dword v128, v[94:95], off
	v_lshl_add_u64 v[94:95], s[74:75], 0, v[104:105]
	global_load_dword v127, v[96:97], off
	v_add_co_u32_e32 v96, vcc, s13, v96
	global_load_dword v125, v[94:95], off
	v_lshl_add_u64 v[94:95], s[76:77], 0, v[104:105]
	v_addc_co_u32_e32 v97, vcc, 0, v97, vcc
	global_load_dword v94, v[94:95], off
	s_nop 0
	global_load_dword v95, v[96:97], off offset:-4096
	global_load_dword v126, v[96:97], off
	v_lshl_add_u64 v[96:97], s[48:49], 0, v[104:105]
	global_load_dword v143, v[96:97], off
	v_lshl_add_u64 v[96:97], s[56:57], 0, v[104:105]
	global_load_dword v106, v[96:97], off
	v_lshl_add_u64 v[96:97], s[50:51], 0, v[104:105]
	global_load_dword v142, v[96:97], off
	v_lshl_add_u64 v[96:97], s[54:55], 0, v[104:105]
	global_load_dword v107, v[96:97], off
	v_lshl_add_u64 v[96:97], s[58:59], 0, v[104:105]
	global_load_dword v141, v[96:97], off
	v_lshl_add_u64 v[96:97], v[92:93], 1, s[96:97]
	v_mul_lo_u32 v93, v139, s61
	v_add3_u32 v93, v130, v93, v140
	ds_read_u16 v102, v93 offset:17296
	v_add_u32_e32 v92, s36, v146
	v_lshl_add_u64 v[104:105], s[52:53], 0, v[104:105]
	s_waitcnt lgkmcnt(0)
	v_lshlrev_b32_e32 v103, 16, v102
	v_and_b32_e32 v102, 0x7fc, v92
	v_cndmask_b32_e64 v102, v102, v144, s[44:45]
	v_cmp_eq_u32_e32 vcc, 0, v102
	global_load_dword v102, v[104:105], off
	ds_read_u16 v104, v93 offset:16896
	s_waitcnt lgkmcnt(0)
	v_lshlrev_b32_e32 v104, 16, v104
	s_waitcnt vmcnt(13)
	v_add_f32_e32 v18, v129, v18
	s_waitcnt vmcnt(11)
	v_add_f32_e32 v2, v2, v128
	v_mul_f32_e32 v2, 0xbfb8aa3b, v2
	v_exp_f32_e32 v2, v2
	v_add_f32_e32 v3, v3, v128
	v_mul_f32_e32 v3, 0xbfb8aa3b, v3
	v_exp_f32_e32 v3, v3
	v_add_f32_e32 v2, 1.0, v2
	v_add_f32_e32 v3, 1.0, v3
	s_waitcnt vmcnt(0)
	v_cndmask_b32_e64 v102, 0, v102, s[44:45]
	v_cndmask_b32_e32 v102, v104, v102, vcc
	v_sub_f32_e32 v145, v102, v103
	ds_read_u16 v102, v93 offset:17424
	ds_read_u16 v104, v93 offset:17024
	v_fmac_f32_e32 v103, v127, v145
	s_waitcnt lgkmcnt(1)
	v_lshlrev_b32_e32 v161, 16, v102
	v_cndmask_b32_e64 v102, 0, v106, s[44:45]
	s_waitcnt lgkmcnt(0)
	v_lshlrev_b32_e32 v104, 16, v104
	v_cndmask_b32_e32 v102, v104, v102, vcc
	v_sub_f32_e32 v105, v102, v161
	ds_read_u16 v102, v93 offset:17552
	ds_read_u16 v93, v93 offset:17152
	v_cndmask_b32_e64 v104, 0, v107, s[44:45]
	s_waitcnt lgkmcnt(1)
	v_lshlrev_b32_e32 v102, 16, v102
	s_waitcnt lgkmcnt(0)
	v_lshlrev_b32_e32 v93, 16, v93
	v_cndmask_b32_e32 v93, v93, v104, vcc
	v_sub_f32_e32 v93, v93, v102
	v_fmac_f32_e32 v102, v126, v93
	v_max_f32_e64 v93, -v18, 0
	v_mul_f32_e64 v18, |v18|, s3
	v_exp_f32_e32 v18, v18
	s_nop 0
	v_add_f32_e32 v18, 1.0, v18
	v_cmp_gt_f32_e32 vcc, s5, v18
	s_nop 1
	v_cndmask_b32_e64 v104, 0, 32, vcc
	v_ldexp_f32 v18, v18, v104
	v_log_f32_e32 v18, v18
	s_nop 0
	v_mul_f32_e32 v104, 0x3f317217, v18
	v_fma_f32 v104, v18, s33, -v104
	v_fmac_f32_e32 v104, 0x3377d1cf, v18
	v_fmac_f32_e32 v104, 0x3f317217, v18
	v_cmp_lt_f32_e64 s[0:1], |v18|, s14
	s_nop 1
	v_cndmask_b32_e64 v18, v18, v104, s[0:1]
	v_cndmask_b32_e32 v104, 0, v219, vcc
	v_sub_f32_e32 v18, v18, v104
	v_add_f32_e32 v18, v93, v18
	v_div_scale_f32 v93, s[0:1], v2, v2, 1.0
	v_rcp_f32_e32 v104, v93
	v_sub_f32_e32 v18, -0.5, v18
	v_mul_f32_e32 v18, 0x3fb8aa3b, v18
	v_exp_f32_e32 v18, v18
	v_fma_f32 v106, -v93, v104, 1.0
	v_fmac_f32_e32 v104, v106, v104
	v_div_scale_f32 v106, vcc, 1.0, v2, 1.0
	v_mul_f32_e32 v107, v106, v104
	v_fma_f32 v108, -v93, v107, v106
	v_fmac_f32_e32 v107, v108, v104
	v_fma_f32 v93, -v93, v107, v106
	v_div_fmas_f32 v93, v93, v104, v107
	v_div_fixup_f32 v2, v93, v2, 1.0
	v_add_f32_e32 v104, -1.0, v2
	v_pk_fma_f32 v[108:109], v[94:95], v[104:105], v[160:161]
	v_mul_f32_e32 v18, 0xbfb8aa3b, v18
	v_mul_f32_e32 v93, v125, v109
	v_exp_f32_e32 v18, v18
	v_mul_f32_e32 v147, v91, v93
	v_ashrrev_i32_e32 v93, 31, v92
	v_lshl_add_u64 v[104:105], v[92:93], 4, v[86:87]
	v_lshlrev_b64 v[106:107], 8, v[104:105]
	v_lshl_add_u64 v[106:107], v[100:101], 0, v[106:107]
	v_lshlrev_b64 v[104:105], 9, v[104:105]
	v_mul_f32_e32 v2, v2, v147
	global_store_dword v[106:107], v18, off nt
	v_lshl_add_u64 v[106:107], v[98:99], 0, v[104:105]
	v_cvt_pk_bf16_f32 v18, v147, s0
	global_store_short v[106:107], v18, off offset:256 nt
	v_cvt_pk_bf16_f32 v2, v2, s0
	v_or_b32_e32 v18, 1, v146
	global_store_short v[106:107], v2, off offset:384 nt
	v_add_u32_e32 v2, s36, v18
	v_mul_lo_u32 v18, v18, s60
	v_add3_u32 v140, v130, v18, v140
	v_add_f32_e32 v18, v129, v19
	v_max_f32_e64 v19, -v18, 0
	v_mul_f32_e64 v18, |v18|, s3
	v_exp_f32_e32 v18, v18
	v_cvt_pk_bf16_f32 v102, v102, s0
	v_pk_mul_f32 v[108:109], v[108:109], v[108:109] op_sel:[0,1] op_sel_hi:[1,0]
	v_lshlrev_b64 v[104:105], 11, v[92:93]
	v_add_f32_e32 v18, 1.0, v18
	v_cmp_gt_f32_e32 vcc, s5, v18
	v_lshl_add_u64 v[104:105], v[96:97], 0, v[104:105]
	s_nop 0
	v_cndmask_b32_e64 v146, 0, 32, vcc
	v_ldexp_f32 v18, v18, v146
	v_log_f32_e32 v18, v18
	s_nop 0
	v_mul_f32_e32 v146, 0x3f317217, v18
	v_fma_f32 v146, v18, s33, -v146
	v_fmac_f32_e32 v146, 0x3377d1cf, v18
	v_fmac_f32_e32 v146, 0x3f317217, v18
	v_cmp_lt_f32_e64 s[0:1], |v18|, s14
	s_nop 1
	v_cndmask_b32_e64 v18, v18, v146, s[0:1]
	v_cndmask_b32_e32 v146, 0, v219, vcc
	v_sub_f32_e32 v18, v18, v146
	v_add_f32_e32 v18, v19, v18
	v_sub_f32_e32 v18, -0.5, v18
	v_mul_f32_e32 v18, 0x3fb8aa3b, v18
	v_exp_f32_e32 v18, v18
	s_nop 0
	v_mul_f32_e32 v18, 0xbfb8aa3b, v18
	v_exp_f32_e32 v146, v18
	v_div_scale_f32 v18, s[0:1], v3, v3, 1.0
	v_rcp_f32_e32 v19, v18
	s_nop 0
	v_fma_f32 v147, -v18, v19, 1.0
	v_fmac_f32_e32 v19, v147, v19
	v_div_scale_f32 v147, vcc, 1.0, v3, 1.0
	v_mul_f32_e32 v148, v147, v19
	v_fma_f32 v149, -v18, v148, v147
	v_fmac_f32_e32 v148, v149, v19
	v_fma_f32 v18, -v18, v148, v147
	v_div_fmas_f32 v18, v18, v19, v148
	v_div_fixup_f32 v3, v18, v3, 1.0
	v_cvt_pk_bf16_f32 v19, v103, s0
	v_add_f32_e32 v18, -1.0, v3
	global_store_short v[106:107], v19, off nt
	v_cvt_pk_bf16_f32 v19, v108, s0
	global_store_short v[106:107], v19, off offset:128 nt
	global_store_short v[104:105], v102, off nt
	ds_read_u16 v19, v140 offset:16896
	ds_read_u16 v102, v140 offset:17296
	ds_read_u16 v104, v140 offset:17024
	ds_read_u16 v105, v140 offset:17424
	ds_read_u16 v109, v140 offset:17552
	ds_read_u16 v145, v140 offset:17152
	s_waitcnt lgkmcnt(4)
	v_lshlrev_b32_e32 v102, 16, v102
	v_lshlrev_b32_e32 v19, 16, v19
	v_sub_f32_e32 v19, v19, v102
	s_waitcnt lgkmcnt(3)
	v_lshlrev_b32_e32 v104, 16, v104
	v_fmac_f32_e32 v102, v127, v19
	s_waitcnt lgkmcnt(2)
	v_lshlrev_b32_e32 v105, 16, v105
	v_mov_b32_e32 v19, v104
	v_pk_add_f32 v[106:107], v[18:19], v[104:105] neg_lo:[0,1] neg_hi:[0,1]
	v_mov_b32_e32 v161, v105
	v_mov_b32_e32 v19, v107
	v_pk_fma_f32 v[18:19], v[94:95], v[18:19], v[160:161]
	s_nop 0
	v_pk_mul_f32 v[104:105], v[18:19], v[18:19] op_sel:[0,1] op_sel_hi:[1,0]
	s_waitcnt lgkmcnt(0)
	v_lshlrev_b32_e32 v18, 16, v145
	v_mov_b32_e32 v105, v108
	v_pk_mul_f32 v[106:107], v[102:103], v[104:105]
	v_lshlrev_b32_e32 v103, 16, v109
	v_sub_f32_e32 v18, v18, v103
	v_fmac_f32_e32 v103, v126, v18
	v_mul_f32_e32 v18, v125, v19
	v_mul_f32_e32 v105, v110, v18
	v_mul_f32_e32 v108, v3, v105
	v_ashrrev_i32_e32 v3, 31, v2
	v_lshl_add_u64 v[18:19], v[2:3], 4, v[86:87]
	v_pk_fma_f32 v[80:81], v[0:1], v[106:107], v[80:81] op_sel_hi:[0,1,1]
	v_lshlrev_b64 v[106:107], 8, v[18:19]
	v_lshlrev_b64 v[18:19], 9, v[18:19]
	v_lshl_add_u64 v[18:19], v[98:99], 0, v[18:19]
	v_cvt_pk_bf16_f32 v102, v102, s0
	global_store_short v[18:19], v102, off nt
	v_cvt_pk_bf16_f32 v102, v104, s0
	global_store_short v[18:19], v102, off offset:128 nt
	v_cvt_pk_bf16_f32 v102, v105, s0
	global_store_short v[18:19], v102, off offset:256 nt
	v_cvt_pk_bf16_f32 v102, v108, s0
	v_lshlrev_b64 v[2:3], 11, v[2:3]
	v_lshl_add_u64 v[106:107], v[100:101], 0, v[106:107]
	global_store_short v[18:19], v102, off offset:384 nt
	v_cvt_pk_bf16_f32 v18, v103, s0
	v_lshl_add_u64 v[2:3], v[96:97], 0, v[2:3]
	global_store_dword v[106:107], v146, off nt
	global_store_short v[2:3], v18, off nt
	ds_read_u16 v3, v140 offset:17696
	ds_read_u16 v18, v140 offset:17296
	ds_read_u16 v102, v140 offset:17824
	ds_read_u16 v103, v140 offset:17952
	ds_read_u16 v104, v140 offset:17552
	v_add_f32_e32 v20, v129, v20
	s_waitcnt lgkmcnt(4)
	v_lshlrev_b32_e32 v19, 16, v3
	ds_read_u16 v3, v140 offset:17424
	s_waitcnt lgkmcnt(2)
	v_lshlrev_b32_e32 v108, 16, v103
	v_mul_f32_e64 v103, |v20|, s3
	s_waitcnt lgkmcnt(1)
	v_lshlrev_b32_e32 v106, 16, v104
	v_exp_f32_e32 v104, v103
	v_lshlrev_b32_e32 v103, 16, v102
	s_waitcnt lgkmcnt(0)
	v_lshlrev_b32_e32 v102, 16, v3
	v_add_u32_e32 v2, 2, v92
	v_add_f32_e32 v104, 1.0, v104
	v_cmp_gt_f32_e32 vcc, s5, v104
	v_mov_b32_e32 v3, v102
	v_add_f32_e32 v4, v4, v128
	v_cndmask_b32_e64 v105, 0, 32, vcc
	v_ldexp_f32 v104, v104, v105
	v_log_f32_e32 v107, v104
	v_pk_add_f32 v[104:105], v[2:3], v[102:103] neg_lo:[0,1] neg_hi:[0,1]
	v_mul_f32_e32 v4, 0xbfb8aa3b, v4
	v_cndmask_b32_e32 v104, 0, v219, vcc
	v_mul_f32_e32 v102, 0x3f317217, v107
	v_fma_f32 v102, v107, s33, -v102
	v_fmac_f32_e32 v102, 0x3377d1cf, v107
	v_fmac_f32_e32 v102, 0x3f317217, v107
	v_cmp_lt_f32_e64 s[0:1], |v107|, s14
	v_exp_f32_e32 v4, v4
	v_max_f32_e64 v20, -v20, 0
	v_cndmask_b32_e64 v102, v107, v102, s[0:1]
	v_sub_f32_e32 v102, v102, v104
	v_add_f32_e32 v20, v20, v102
	v_sub_f32_e32 v20, -0.5, v20
	v_mul_f32_e32 v20, 0x3fb8aa3b, v20
	v_add_f32_e32 v4, 1.0, v4
	v_exp_f32_e32 v20, v20
	v_div_scale_f32 v102, s[0:1], v4, v4, 1.0
	v_rcp_f32_e32 v104, v102
	v_sub_f32_e32 v3, v106, v108
	v_fmac_f32_e32 v108, v126, v3
	v_mul_f32_e32 v3, 0xbfb8aa3b, v20
	v_exp_f32_e32 v20, v3
	v_fma_f32 v3, -v102, v104, 1.0
	v_fmac_f32_e32 v104, v3, v104
	v_div_scale_f32 v3, vcc, 1.0, v4, 1.0
	v_mul_f32_e32 v106, v3, v104
	v_fma_f32 v107, -v102, v106, v3
	v_fmac_f32_e32 v106, v107, v104
	v_fma_f32 v3, -v102, v106, v3
	v_div_fmas_f32 v3, v3, v104, v106
	v_div_fixup_f32 v3, v3, v4, 1.0
	v_add_f32_e32 v104, -1.0, v3
	v_mov_b32_e32 v161, v103
	v_pk_fma_f32 v[102:103], v[94:95], v[104:105], v[160:161]
	v_add_f32_e32 v5, v5, v128
	v_mul_f32_e32 v4, v125, v103
	v_mul_f32_e32 v4, v111, v4
	v_mul_f32_e32 v109, v3, v4
	v_ashrrev_i32_e32 v3, 31, v2
	v_lshl_add_u64 v[104:105], v[2:3], 4, v[86:87]
	v_lshlrev_b64 v[106:107], 8, v[104:105]
	v_lshlrev_b64 v[104:105], 9, v[104:105]
	v_lshl_add_u64 v[104:105], v[98:99], 0, v[104:105]
	v_cvt_pk_bf16_f32 v4, v4, s0
	v_lshl_add_u64 v[106:107], v[100:101], 0, v[106:107]
	global_store_short v[104:105], v4, off offset:256 nt
	v_add_f32_e32 v4, v129, v21
	global_store_dword v[106:107], v20, off nt
	v_mul_f32_e64 v20, |v4|, s3
	v_exp_f32_e32 v20, v20
	v_cvt_pk_bf16_f32 v21, v109, s0
	global_store_short v[104:105], v21, off offset:384 nt
	v_cvt_pk_bf16_f32 v21, v108, s0
	v_add_f32_e32 v20, 1.0, v20
	v_cmp_gt_f32_e32 vcc, s5, v20
	v_mul_f32_e32 v5, 0xbfb8aa3b, v5
	v_exp_f32_e32 v5, v5
	v_cndmask_b32_e64 v106, 0, 32, vcc
	v_ldexp_f32 v20, v20, v106
	v_log_f32_e32 v20, v20
	v_max_f32_e64 v4, -v4, 0
	v_add_f32_e32 v5, 1.0, v5
	v_lshlrev_b32_e32 v18, 16, v18
	v_mul_f32_e32 v106, 0x3f317217, v20
	v_fma_f32 v106, v20, s33, -v106
	v_fmac_f32_e32 v106, 0x3377d1cf, v20
	v_fmac_f32_e32 v106, 0x3f317217, v20
	v_cmp_lt_f32_e64 s[0:1], |v20|, s14
	v_sub_f32_e32 v18, v18, v19
	v_fmac_f32_e32 v19, v127, v18
	v_cndmask_b32_e64 v20, v20, v106, s[0:1]
	v_cndmask_b32_e32 v106, 0, v219, vcc
	v_sub_f32_e32 v20, v20, v106
	v_add_f32_e32 v4, v4, v20
	v_sub_f32_e32 v4, -0.5, v4
	v_mul_f32_e32 v4, 0x3fb8aa3b, v4
	v_exp_f32_e32 v20, v4
	v_div_scale_f32 v106, s[0:1], v5, v5, 1.0
	v_rcp_f32_e32 v107, v106
	v_mul_f32_e32 v20, 0xbfb8aa3b, v20
	v_exp_f32_e32 v108, v20
	v_lshlrev_b64 v[2:3], 11, v[2:3]
	v_fma_f32 v20, -v106, v107, 1.0
	v_fmac_f32_e32 v107, v20, v107
	v_div_scale_f32 v20, vcc, 1.0, v5, 1.0
	v_mul_f32_e32 v109, v20, v107
	v_fma_f32 v145, -v106, v109, v20
	v_fmac_f32_e32 v109, v145, v107
	v_fma_f32 v20, -v106, v109, v20
	v_div_fmas_f32 v20, v20, v107, v109
	v_div_fixup_f32 v106, v20, v5, 1.0
	v_pk_mul_f32 v[102:103], v[102:103], v[102:103] op_sel:[0,1] op_sel_hi:[1,0]
	v_cvt_pk_bf16_f32 v5, v19, s0
	v_lshl_add_u64 v[2:3], v[96:97], 0, v[2:3]
	v_add_u32_e32 v4, 3, v92
	v_add_f32_e32 v20, -1.0, v106
	global_store_short v[104:105], v5, off nt
	v_cvt_pk_bf16_f32 v5, v102, s0
	global_store_short v[104:105], v5, off offset:128 nt
	global_store_short v[2:3], v21, off nt
	ds_read_u16 v2, v140 offset:17696
	ds_read_u16 v3, v140 offset:18096
	ds_read_u16 v5, v140 offset:17824
	ds_read_u16 v21, v140 offset:18224
	ds_read_u16 v107, v140 offset:18352
	ds_read_u16 v109, v140 offset:17952
	s_waitcnt lgkmcnt(4)
	v_lshlrev_b32_e32 v18, 16, v3
	v_lshlrev_b32_e32 v2, 16, v2
	v_sub_f32_e32 v2, v2, v18
	v_fmac_f32_e32 v18, v127, v2
	s_waitcnt lgkmcnt(3)
	v_lshlrev_b32_e32 v2, 16, v5
	s_waitcnt lgkmcnt(2)
	v_lshlrev_b32_e32 v3, 16, v21
	v_mov_b32_e32 v5, v2
	v_pk_add_f32 v[104:105], v[4:5], v[2:3] neg_lo:[0,1] neg_hi:[0,1]
	v_mov_b32_e32 v161, v3
	v_mov_b32_e32 v21, v105
	v_pk_fma_f32 v[2:3], v[94:95], v[20:21], v[160:161]
	v_ashrrev_i32_e32 v5, 31, v4
	v_pk_mul_f32 v[20:21], v[2:3], v[2:3] op_sel:[0,1] op_sel_hi:[1,0]
	s_waitcnt lgkmcnt(0)
	v_lshlrev_b32_e32 v2, 16, v109
	v_mov_b32_e32 v21, v102
	v_pk_mul_f32 v[102:103], v[18:19], v[20:21]
	v_lshlrev_b32_e32 v19, 16, v107
	v_sub_f32_e32 v2, v2, v19
	v_fmac_f32_e32 v19, v126, v2
	v_mul_f32_e32 v2, v125, v3
	v_mul_f32_e32 v21, v112, v2
	v_lshl_add_u64 v[2:3], v[4:5], 4, v[86:87]
	v_pk_fma_f32 v[78:79], v[0:1], v[102:103], v[78:79] op_sel_hi:[0,1,1]
	v_lshlrev_b64 v[102:103], 8, v[2:3]
	v_lshlrev_b64 v[2:3], 9, v[2:3]
	v_lshl_add_u64 v[2:3], v[98:99], 0, v[2:3]
	v_cvt_pk_bf16_f32 v18, v18, s0
	global_store_short v[2:3], v18, off nt
	v_cvt_pk_bf16_f32 v18, v20, s0
	v_mul_f32_e32 v104, v106, v21
	global_store_short v[2:3], v18, off offset:128 nt
	v_cvt_pk_bf16_f32 v18, v21, s0
	global_store_short v[2:3], v18, off offset:256 nt
	v_cvt_pk_bf16_f32 v18, v104, s0
	global_store_short v[2:3], v18, off offset:384 nt
	v_lshlrev_b64 v[2:3], 11, v[4:5]
	v_lshl_add_u64 v[102:103], v[100:101], 0, v[102:103]
	v_cvt_pk_bf16_f32 v18, v19, s0
	v_lshl_add_u64 v[2:3], v[96:97], 0, v[2:3]
	global_store_dword v[102:103], v108, off nt
	global_store_short v[2:3], v18, off nt
	ds_read_u16 v3, v140 offset:20096
	ds_read_u16 v4, v140 offset:19696
	ds_read_u16 v5, v140 offset:20224
	ds_read_u16 v18, v140 offset:20352
	ds_read_u16 v20, v140 offset:19952
	s_waitcnt lgkmcnt(4)
	v_lshlrev_b32_e32 v19, 16, v3
	s_waitcnt lgkmcnt(3)
	v_lshlrev_b32_e32 v4, 16, v4
	v_add_f32_e32 v22, v129, v22
	v_sub_f32_e32 v104, v4, v19
	v_mul_f32_e64 v4, |v22|, s3
	s_waitcnt lgkmcnt(0)
	v_lshlrev_b32_e32 v102, 16, v20
	v_exp_f32_e32 v20, v4
	ds_read_u16 v3, v140 offset:19824
	v_add_u32_e32 v2, 8, v92
	v_lshlrev_b32_e32 v5, 16, v5
	v_add_f32_e32 v20, 1.0, v20
	v_cmp_gt_f32_e32 vcc, s5, v20
	s_waitcnt lgkmcnt(0)
	v_lshlrev_b32_e32 v4, 16, v3
	v_mov_b32_e32 v3, v4
	v_cndmask_b32_e64 v21, 0, 32, vcc
	v_ldexp_f32 v20, v20, v21
	v_log_f32_e32 v103, v20
	v_pk_add_f32 v[20:21], v[2:3], v[4:5] neg_lo:[0,1] neg_hi:[0,1]
	v_add_f32_e32 v6, v6, v128
	v_mul_f32_e32 v6, 0xbfb8aa3b, v6
	v_mul_f32_e32 v20, 0x3f317217, v103
	v_fma_f32 v20, v103, s33, -v20
	v_fmac_f32_e32 v20, 0x3377d1cf, v103
	v_fmac_f32_e32 v20, 0x3f317217, v103
	v_cmp_lt_f32_e64 s[0:1], |v103|, s14
	v_max_f32_e64 v4, -v22, 0
	v_cndmask_b32_e32 v22, 0, v219, vcc
	v_cndmask_b32_e64 v20, v103, v20, s[0:1]
	v_exp_f32_e32 v6, v6
	v_sub_f32_e32 v20, v20, v22
	v_add_f32_e32 v4, v4, v20
	v_sub_f32_e32 v4, -0.5, v4
	v_mul_f32_e32 v4, 0x3fb8aa3b, v4
	v_add_f32_e32 v6, 1.0, v6
	v_exp_f32_e32 v4, v4
	v_div_scale_f32 v20, s[0:1], v6, v6, 1.0
	v_rcp_f32_e32 v22, v20
	v_lshlrev_b32_e32 v18, 16, v18
	v_sub_f32_e32 v3, v102, v18
	v_fmac_f32_e32 v18, v126, v3
	v_mul_f32_e32 v3, 0xbfb8aa3b, v4
	v_exp_f32_e32 v105, v3
	v_fma_f32 v3, -v20, v22, 1.0
	v_fmac_f32_e32 v22, v3, v22
	v_div_scale_f32 v3, vcc, 1.0, v6, 1.0
	v_mul_f32_e32 v4, v3, v22
	v_fma_f32 v102, -v20, v4, v3
	v_fmac_f32_e32 v4, v102, v22
	v_fma_f32 v3, -v20, v4, v3
	v_div_fmas_f32 v3, v3, v22, v4
	v_div_fixup_f32 v3, v3, v6, 1.0
	v_add_f32_e32 v20, -1.0, v3
	v_mov_b32_e32 v161, v5
	v_pk_fma_f32 v[20:21], v[94:95], v[20:21], v[160:161]
	v_cvt_pk_bf16_f32 v18, v18, s0
	v_mul_f32_e32 v4, v125, v21
	v_mul_f32_e32 v6, v113, v4
	v_mul_f32_e32 v22, v3, v6
	v_ashrrev_i32_e32 v3, 31, v2
	v_lshl_add_u64 v[4:5], v[2:3], 4, v[86:87]
	v_lshlrev_b64 v[102:103], 8, v[4:5]
	v_lshl_add_u64 v[102:103], v[100:101], 0, v[102:103]
	v_lshlrev_b64 v[4:5], 9, v[4:5]
	global_store_dword v[102:103], v105, off nt
	v_lshl_add_u64 v[102:103], v[98:99], 0, v[4:5]
	v_cvt_pk_bf16_f32 v4, v6, s0
	v_add_f32_e32 v6, v129, v23
	global_store_short v[102:103], v4, off offset:256 nt
	v_mul_f32_e64 v4, |v6|, s3
	v_exp_f32_e32 v4, v4
	v_cvt_pk_bf16_f32 v5, v22, s0
	global_store_short v[102:103], v5, off offset:384 nt
	v_fmac_f32_e32 v19, v127, v104
	v_add_f32_e32 v4, 1.0, v4
	v_cmp_gt_f32_e32 vcc, s5, v4
	v_pk_mul_f32 v[20:21], v[20:21], v[20:21] op_sel:[0,1] op_sel_hi:[1,0]
	s_nop 0
	v_cndmask_b32_e64 v5, 0, 32, vcc
	v_ldexp_f32 v4, v4, v5
	v_log_f32_e32 v105, v4
	v_lshlrev_b64 v[4:5], 11, v[2:3]
	v_lshl_add_u64 v[22:23], v[96:97], 0, v[4:5]
	v_max_f32_e64 v4, -v6, 0
	v_mul_f32_e32 v5, 0x3f317217, v105
	v_fma_f32 v5, v105, s33, -v5
	v_fmac_f32_e32 v5, 0x3377d1cf, v105
	v_fmac_f32_e32 v5, 0x3f317217, v105
	v_cmp_lt_f32_e64 s[0:1], |v105|, s14
	v_cndmask_b32_e32 v6, 0, v219, vcc
	s_nop 0
	v_cndmask_b32_e64 v5, v105, v5, s[0:1]
	v_sub_f32_e32 v5, v5, v6
	v_add_f32_e32 v4, v4, v5
	v_add_f32_e32 v5, v7, v128
	v_mul_f32_e32 v5, 0xbfb8aa3b, v5
	v_exp_f32_e32 v5, v5
	v_sub_f32_e32 v4, -0.5, v4
	v_mul_f32_e32 v4, 0x3fb8aa3b, v4
	v_exp_f32_e32 v6, v4
	v_add_f32_e32 v5, 1.0, v5
	v_div_scale_f32 v7, s[0:1], v5, v5, 1.0
	v_rcp_f32_e32 v105, v7
	v_mul_f32_e32 v6, 0xbfb8aa3b, v6
	v_exp_f32_e32 v106, v6
	v_add_u32_e32 v4, 9, v92
	v_fma_f32 v6, -v7, v105, 1.0
	v_fmac_f32_e32 v105, v6, v105
	v_div_scale_f32 v6, vcc, 1.0, v5, 1.0
	v_mul_f32_e32 v107, v6, v105
	v_fma_f32 v108, -v7, v107, v6
	v_fmac_f32_e32 v107, v108, v105
	v_fma_f32 v6, -v7, v107, v6
	v_div_fmas_f32 v6, v6, v105, v107
	v_div_fixup_f32 v105, v6, v5, 1.0
	v_cvt_pk_bf16_f32 v5, v19, s0
	v_add_f32_e32 v6, -1.0, v105
	global_store_short v[102:103], v5, off nt
	v_cvt_pk_bf16_f32 v5, v20, s0
	global_store_short v[102:103], v5, off offset:128 nt
	global_store_short v[22:23], v18, off nt
	ds_read_u16 v5, v140 offset:20096
	ds_read_u16 v7, v140 offset:20496
	ds_read_u16 v21, v140 offset:20224
	ds_read_u16 v22, v140 offset:20624
	ds_read_u16 v104, v140 offset:20752
	ds_read_u16 v107, v140 offset:20352
	s_waitcnt lgkmcnt(4)
	v_lshlrev_b32_e32 v18, 16, v7
	v_lshlrev_b32_e32 v5, 16, v5
	v_sub_f32_e32 v5, v5, v18
	s_waitcnt lgkmcnt(2)
	v_lshlrev_b32_e32 v23, 16, v22
	v_lshlrev_b32_e32 v22, 16, v21
	v_fmac_f32_e32 v18, v127, v5
	v_mov_b32_e32 v5, v22
	v_pk_add_f32 v[102:103], v[4:5], v[22:23] neg_lo:[0,1] neg_hi:[0,1]
	v_mov_b32_e32 v161, v23
	v_mov_b32_e32 v7, v103
	v_pk_fma_f32 v[6:7], v[94:95], v[6:7], v[160:161]
	s_waitcnt lgkmcnt(0)
	v_lshlrev_b32_e32 v5, 16, v107
	v_pk_mul_f32 v[22:23], v[6:7], v[6:7] op_sel:[0,1] op_sel_hi:[1,0]
	s_nop 0
	v_mov_b32_e32 v23, v20
	v_pk_mul_f32 v[20:21], v[18:19], v[22:23]
	v_lshlrev_b32_e32 v19, 16, v104
	v_sub_f32_e32 v5, v5, v19
	v_fmac_f32_e32 v19, v126, v5
	v_mul_f32_e32 v5, v125, v7
	v_mul_f32_e32 v23, v114, v5
	v_ashrrev_i32_e32 v5, 31, v4
	v_lshl_add_u64 v[6:7], v[4:5], 4, v[86:87]
	v_pk_fma_f32 v[76:77], v[0:1], v[20:21], v[76:77] op_sel_hi:[0,1,1]
	v_lshlrev_b64 v[20:21], 8, v[6:7]
	v_lshlrev_b64 v[6:7], 9, v[6:7]
	v_lshl_add_u64 v[6:7], v[98:99], 0, v[6:7]
	v_cvt_pk_bf16_f32 v18, v18, s0
	global_store_short v[6:7], v18, off nt
	v_cvt_pk_bf16_f32 v18, v22, s0
	v_mul_f32_e32 v102, v105, v23
	global_store_short v[6:7], v18, off offset:128 nt
	v_cvt_pk_bf16_f32 v18, v23, s0
	global_store_short v[6:7], v18, off offset:256 nt
	v_cvt_pk_bf16_f32 v18, v102, s0
	global_store_short v[6:7], v18, off offset:384 nt
	v_lshlrev_b64 v[6:7], 11, v[4:5]
	v_lshl_add_u64 v[20:21], v[100:101], 0, v[20:21]
	v_cvt_pk_bf16_f32 v18, v19, s0
	v_lshl_add_u64 v[6:7], v[96:97], 0, v[6:7]
	global_store_dword v[20:21], v106, off nt
	global_store_short v[6:7], v18, off nt
	ds_read_u16 v7, v140 offset:20896
	ds_read_u16 v18, v140 offset:20496
	ds_read_u16 v20, v140 offset:21024
	ds_read_u16 v21, v140 offset:21152
	ds_read_u16 v22, v140 offset:20752
	v_add_f32_e32 v24, v129, v24
	s_waitcnt lgkmcnt(4)
	v_lshlrev_b32_e32 v19, 16, v7
	ds_read_u16 v7, v140 offset:20624
	s_waitcnt lgkmcnt(2)
	v_lshlrev_b32_e32 v104, 16, v21
	v_mul_f32_e64 v21, |v24|, s3
	s_waitcnt lgkmcnt(1)
	v_lshlrev_b32_e32 v102, 16, v22
	v_exp_f32_e32 v22, v21
	v_lshlrev_b32_e32 v21, 16, v20
	s_waitcnt lgkmcnt(0)
	v_lshlrev_b32_e32 v20, 16, v7
	v_add_u32_e32 v6, 10, v92
	v_add_f32_e32 v22, 1.0, v22
	v_cmp_gt_f32_e32 vcc, s5, v22
	v_mov_b32_e32 v7, v20
	v_add_f32_e32 v8, v8, v128
	v_cndmask_b32_e64 v23, 0, 32, vcc
	v_ldexp_f32 v22, v22, v23
	v_log_f32_e32 v103, v22
	v_pk_add_f32 v[22:23], v[6:7], v[20:21] neg_lo:[0,1] neg_hi:[0,1]
	v_mul_f32_e32 v8, 0xbfb8aa3b, v8
	v_max_f32_e64 v20, -v24, 0
	v_mul_f32_e32 v22, 0x3f317217, v103
	v_fma_f32 v22, v103, s33, -v22
	v_fmac_f32_e32 v22, 0x3377d1cf, v103
	v_fmac_f32_e32 v22, 0x3f317217, v103
	v_cmp_lt_f32_e64 s[0:1], |v103|, s14
	v_cndmask_b32_e32 v24, 0, v219, vcc
	v_exp_f32_e32 v8, v8
	v_cndmask_b32_e64 v22, v103, v22, s[0:1]
	v_sub_f32_e32 v22, v22, v24
	v_add_f32_e32 v20, v20, v22
	v_sub_f32_e32 v20, -0.5, v20
	v_mul_f32_e32 v20, 0x3fb8aa3b, v20
	v_add_f32_e32 v8, 1.0, v8
	v_exp_f32_e32 v20, v20
	v_div_scale_f32 v22, s[0:1], v8, v8, 1.0
	v_rcp_f32_e32 v24, v22
	v_sub_f32_e32 v7, v102, v104
	v_fmac_f32_e32 v104, v126, v7
	v_mul_f32_e32 v7, 0xbfb8aa3b, v20
	v_exp_f32_e32 v105, v7
	v_fma_f32 v7, -v22, v24, 1.0
	v_fmac_f32_e32 v24, v7, v24
	v_div_scale_f32 v7, vcc, 1.0, v8, 1.0
	v_mul_f32_e32 v20, v7, v24
	v_fma_f32 v102, -v22, v20, v7
	v_fmac_f32_e32 v20, v102, v24
	v_fma_f32 v7, -v22, v20, v7
	v_div_fmas_f32 v7, v7, v24, v20
	v_div_fixup_f32 v7, v7, v8, 1.0
	v_add_f32_e32 v22, -1.0, v7
	v_mov_b32_e32 v161, v21
	v_pk_fma_f32 v[20:21], v[94:95], v[22:23], v[160:161]
	v_add_f32_e32 v9, v9, v128
	v_mul_f32_e32 v8, v125, v21
	v_mul_f32_e32 v8, v115, v8
	v_mul_f32_e32 v24, v7, v8
	v_ashrrev_i32_e32 v7, 31, v6
	v_lshl_add_u64 v[22:23], v[6:7], 4, v[86:87]
	v_lshlrev_b64 v[102:103], 8, v[22:23]
	v_lshlrev_b64 v[22:23], 9, v[22:23]
	v_lshl_add_u64 v[22:23], v[98:99], 0, v[22:23]
	v_cvt_pk_bf16_f32 v8, v8, s0
	global_store_short v[22:23], v8, off offset:256 nt
	v_add_f32_e32 v8, v129, v25
	v_mul_f32_e64 v25, |v8|, s3
	v_exp_f32_e32 v25, v25
	v_cvt_pk_bf16_f32 v24, v24, s0
	global_store_short v[22:23], v24, off offset:384 nt
	v_lshl_add_u64 v[102:103], v[100:101], 0, v[102:103]
	v_add_f32_e32 v24, 1.0, v25
	v_cmp_gt_f32_e32 vcc, s5, v24
	global_store_dword v[102:103], v105, off nt
	v_cvt_pk_bf16_f32 v103, v104, s0
	v_cndmask_b32_e64 v25, 0, 32, vcc
	v_ldexp_f32 v24, v24, v25
	v_log_f32_e32 v102, v24
	v_mul_f32_e32 v9, 0xbfb8aa3b, v9
	v_exp_f32_e32 v9, v9
	v_max_f32_e64 v8, -v8, 0
	v_mul_f32_e32 v104, 0x3f317217, v102
	v_fma_f32 v104, v102, s33, -v104
	v_fmac_f32_e32 v104, 0x3377d1cf, v102
	v_fmac_f32_e32 v104, 0x3f317217, v102
	v_cmp_lt_f32_e64 s[0:1], |v102|, s14
	v_add_f32_e32 v9, 1.0, v9
	v_lshlrev_b32_e32 v18, 16, v18
	v_cndmask_b32_e64 v102, v102, v104, s[0:1]
	v_cndmask_b32_e32 v104, 0, v219, vcc
	v_sub_f32_e32 v102, v102, v104
	v_add_f32_e32 v8, v8, v102
	v_sub_f32_e32 v8, -0.5, v8
	v_mul_f32_e32 v8, 0x3fb8aa3b, v8
	v_exp_f32_e32 v102, v8
	v_div_scale_f32 v104, s[0:1], v9, v9, 1.0
	v_rcp_f32_e32 v105, v104
	v_mul_f32_e32 v102, 0xbfb8aa3b, v102
	v_exp_f32_e32 v106, v102
	v_sub_f32_e32 v18, v18, v19
	v_fma_f32 v102, -v104, v105, 1.0
	v_fmac_f32_e32 v105, v102, v105
	v_div_scale_f32 v102, vcc, 1.0, v9, 1.0
	v_mul_f32_e32 v107, v102, v105
	v_fma_f32 v108, -v104, v107, v102
	v_fmac_f32_e32 v107, v108, v105
	v_fma_f32 v102, -v104, v107, v102
	v_div_fmas_f32 v102, v102, v105, v107
	v_fmac_f32_e32 v19, v127, v18
	v_lshlrev_b64 v[24:25], 11, v[6:7]
	v_div_fixup_f32 v104, v102, v9, 1.0
	v_pk_mul_f32 v[20:21], v[20:21], v[20:21] op_sel:[0,1] op_sel_hi:[1,0]
	v_cvt_pk_bf16_f32 v9, v19, s0
	v_lshl_add_u64 v[24:25], v[96:97], 0, v[24:25]
	v_add_u32_e32 v8, 11, v92
	global_store_short v[22:23], v9, off nt
	v_cvt_pk_bf16_f32 v9, v20, s0
	v_add_f32_e32 v102, -1.0, v104
	global_store_short v[22:23], v9, off offset:128 nt
	global_store_short v[24:25], v103, off nt
	ds_read_u16 v9, v140 offset:20896
	ds_read_u16 v18, v140 offset:21296
	ds_read_u16 v21, v140 offset:21024
	ds_read_u16 v22, v140 offset:21424
	ds_read_u16 v105, v140 offset:21552
	ds_read_u16 v107, v140 offset:21152
	s_waitcnt lgkmcnt(4)
	v_lshlrev_b32_e32 v18, 16, v18
	v_lshlrev_b32_e32 v9, 16, v9
	v_sub_f32_e32 v9, v9, v18
	s_waitcnt lgkmcnt(2)
	v_lshlrev_b32_e32 v23, 16, v22
	v_lshlrev_b32_e32 v22, 16, v21
	v_fmac_f32_e32 v18, v127, v9
	v_mov_b32_e32 v9, v22
	v_pk_add_f32 v[24:25], v[8:9], v[22:23] neg_lo:[0,1] neg_hi:[0,1]
	v_mov_b32_e32 v161, v23
	v_mov_b32_e32 v103, v25
	v_pk_fma_f32 v[22:23], v[94:95], v[102:103], v[160:161]
	s_waitcnt lgkmcnt(0)
	v_lshlrev_b32_e32 v9, 16, v107
	v_pk_mul_f32 v[24:25], v[22:23], v[22:23] op_sel:[0,1] op_sel_hi:[1,0]
	s_nop 0
	v_mov_b32_e32 v25, v20
	v_pk_mul_f32 v[20:21], v[18:19], v[24:25]
	v_lshlrev_b32_e32 v19, 16, v105
	v_sub_f32_e32 v9, v9, v19
	v_fmac_f32_e32 v19, v126, v9
	v_mul_f32_e32 v9, v125, v23
	v_mul_f32_e32 v25, v116, v9
	v_ashrrev_i32_e32 v9, 31, v8
	v_pk_fma_f32 v[74:75], v[0:1], v[20:21], v[74:75] op_sel_hi:[0,1,1]
	v_lshl_add_u64 v[20:21], v[8:9], 4, v[86:87]
	v_lshlrev_b64 v[22:23], 8, v[20:21]
	v_lshlrev_b64 v[20:21], 9, v[20:21]
	v_lshl_add_u64 v[20:21], v[98:99], 0, v[20:21]
	v_cvt_pk_bf16_f32 v18, v18, s0
	global_store_short v[20:21], v18, off nt
	v_cvt_pk_bf16_f32 v18, v24, s0
	v_mul_f32_e32 v102, v104, v25
	global_store_short v[20:21], v18, off offset:128 nt
	v_cvt_pk_bf16_f32 v18, v25, s0
	global_store_short v[20:21], v18, off offset:256 nt
	v_cvt_pk_bf16_f32 v18, v102, s0
	global_store_short v[20:21], v18, off offset:384 nt
	v_cvt_pk_bf16_f32 v20, v19, s0
	v_lshlrev_b64 v[18:19], 11, v[8:9]
	v_lshl_add_u64 v[22:23], v[100:101], 0, v[22:23]
	v_lshl_add_u64 v[18:19], v[96:97], 0, v[18:19]
	global_store_dword v[22:23], v106, off nt
	global_store_short v[18:19], v20, off nt
	v_add_u32_e32 v18, 16, v92
	ds_read_u16 v19, v140 offset:23296
	ds_read_u16 v20, v140 offset:22896
	ds_read_u16 v22, v140 offset:23424
	ds_read_u16 v23, v140 offset:23024
	ds_read_u16 v24, v140 offset:23552
	ds_read_u16 v25, v140 offset:23152
	s_waitcnt lgkmcnt(5)
	v_lshlrev_b32_e32 v21, 16, v19
	v_and_b32_e32 v19, 0x7fc, v18
	v_cndmask_b32_e64 v19, v19, v144, s[44:45]
	v_cndmask_b32_e64 v102, 0, v143, s[44:45]
	s_waitcnt lgkmcnt(4)
	v_lshlrev_b32_e32 v20, 16, v20
	v_cmp_eq_u32_e32 vcc, 0, v19
	s_waitcnt lgkmcnt(3)
	v_lshlrev_b32_e32 v161, 16, v22
	s_waitcnt lgkmcnt(2)
	v_lshlrev_b32_e32 v22, 16, v23
	v_cndmask_b32_e32 v19, v20, v102, vcc
	v_sub_f32_e32 v20, v19, v21
	v_cndmask_b32_e64 v19, 0, v142, s[44:45]
	v_cndmask_b32_e32 v19, v22, v19, vcc
	v_sub_f32_e32 v23, v19, v161
	v_add_f32_e32 v19, v129, v26
	v_mul_f32_e64 v22, |v19|, s3
	v_exp_f32_e32 v22, v22
	s_waitcnt lgkmcnt(1)
	v_lshlrev_b32_e32 v26, 16, v24
	v_cndmask_b32_e64 v24, 0, v141, s[44:45]
	s_waitcnt lgkmcnt(0)
	v_lshlrev_b32_e32 v25, 16, v25
	v_add_f32_e32 v22, 1.0, v22
	v_cmp_gt_f32_e64 s[0:1], s5, v22
	v_cndmask_b32_e32 v24, v25, v24, vcc
	v_add_f32_e32 v10, v10, v128
	v_cndmask_b32_e64 v102, 0, 32, s[0:1]
	v_ldexp_f32 v22, v22, v102
	v_log_f32_e32 v22, v22
	v_mul_f32_e32 v10, 0xbfb8aa3b, v10
	v_exp_f32_e32 v10, v10
	v_max_f32_e64 v19, -v19, 0
	v_mul_f32_e32 v25, 0x3f317217, v22
	v_fma_f32 v25, v22, s33, -v25
	v_fmac_f32_e32 v25, 0x3377d1cf, v22
	v_fmac_f32_e32 v25, 0x3f317217, v22
	v_cmp_lt_f32_e64 vcc, |v22|, s14
	v_add_f32_e32 v10, 1.0, v10
	v_sub_f32_e32 v24, v24, v26
	v_cndmask_b32_e32 v22, v22, v25, vcc
	v_cndmask_b32_e64 v25, 0, v219, s[0:1]
	v_sub_f32_e32 v22, v22, v25
	v_add_f32_e32 v19, v19, v22
	v_sub_f32_e32 v19, -0.5, v19
	v_mul_f32_e32 v19, 0x3fb8aa3b, v19
	v_exp_f32_e32 v19, v19
	v_div_scale_f32 v22, s[0:1], v10, v10, 1.0
	v_rcp_f32_e32 v25, v22
	v_mul_f32_e32 v19, 0xbfb8aa3b, v19
	v_exp_f32_e32 v104, v19
	v_fmac_f32_e32 v26, v126, v24
	v_fma_f32 v19, -v22, v25, 1.0
	v_fmac_f32_e32 v25, v19, v25
	v_div_scale_f32 v19, vcc, 1.0, v10, 1.0
	v_mul_f32_e32 v24, v19, v25
	v_fma_f32 v102, -v22, v24, v19
	v_fmac_f32_e32 v24, v102, v25
	v_fma_f32 v19, -v22, v24, v19
	v_div_fmas_f32 v19, v19, v25, v24
	v_div_fixup_f32 v10, v19, v10, 1.0
	v_add_f32_e32 v22, -1.0, v10
	v_pk_fma_f32 v[22:23], v[94:95], v[22:23], v[160:161]
	v_add_f32_e32 v11, v11, v128
	v_mul_f32_e32 v19, v125, v23
	v_mul_f32_e32 v105, v117, v19
	v_ashrrev_i32_e32 v19, 31, v18
	v_lshl_add_u64 v[24:25], v[18:19], 4, v[86:87]
	v_lshlrev_b64 v[102:103], 8, v[24:25]
	v_lshl_add_u64 v[102:103], v[100:101], 0, v[102:103]
	v_lshlrev_b64 v[24:25], 9, v[24:25]
	global_store_dword v[102:103], v104, off nt
	v_lshl_add_u64 v[24:25], v[98:99], 0, v[24:25]
	v_cvt_pk_bf16_f32 v102, v105, s0
	global_store_short v[24:25], v102, off offset:256 nt
	v_add_f32_e32 v102, v129, v27
	v_mul_f32_e64 v27, |v102|, s3
	v_exp_f32_e32 v27, v27
	v_mul_f32_e32 v10, v10, v105
	v_cvt_pk_bf16_f32 v10, v10, s0
	global_store_short v[24:25], v10, off offset:384 nt
	v_add_f32_e32 v10, 1.0, v27
	v_cmp_gt_f32_e32 vcc, s5, v10
	v_cvt_pk_bf16_f32 v103, v26, s0
	v_mul_f32_e32 v11, 0xbfb8aa3b, v11
	v_cndmask_b32_e64 v26, 0, 32, vcc
	v_ldexp_f32 v10, v10, v26
	v_log_f32_e32 v10, v10
	v_exp_f32_e32 v11, v11
	v_max_f32_e64 v102, -v102, 0
	v_fmac_f32_e32 v21, v127, v20
	v_mul_f32_e32 v104, 0x3f317217, v10
	v_fma_f32 v104, v10, s33, -v104
	v_fmac_f32_e32 v104, 0x3377d1cf, v10
	v_fmac_f32_e32 v104, 0x3f317217, v10
	v_cmp_lt_f32_e64 s[0:1], |v10|, s14
	v_add_f32_e32 v11, 1.0, v11
	v_pk_mul_f32 v[22:23], v[22:23], v[22:23] op_sel:[0,1] op_sel_hi:[1,0]
	v_cndmask_b32_e64 v10, v10, v104, s[0:1]
	v_cndmask_b32_e32 v104, 0, v219, vcc
	v_sub_f32_e32 v10, v10, v104
	v_add_f32_e32 v10, v102, v10
	v_sub_f32_e32 v10, -0.5, v10
	v_mul_f32_e32 v10, 0x3fb8aa3b, v10
	v_exp_f32_e32 v102, v10
	v_div_scale_f32 v104, s[0:1], v11, v11, 1.0
	v_rcp_f32_e32 v105, v104
	v_mul_f32_e32 v102, 0xbfb8aa3b, v102
	v_exp_f32_e32 v106, v102
	v_lshlrev_b64 v[26:27], 11, v[18:19]
	v_fma_f32 v102, -v104, v105, 1.0
	v_fmac_f32_e32 v105, v102, v105
	v_div_scale_f32 v102, vcc, 1.0, v11, 1.0
	v_mul_f32_e32 v107, v102, v105
	v_fma_f32 v108, -v104, v107, v102
	v_fmac_f32_e32 v107, v108, v105
	v_fma_f32 v102, -v104, v107, v102
	v_div_fmas_f32 v102, v102, v105, v107
	v_div_fixup_f32 v104, v102, v11, 1.0
	v_cvt_pk_bf16_f32 v11, v21, s0
	v_add_u32_e32 v10, 17, v92
	global_store_short v[24:25], v11, off nt
	v_cvt_pk_bf16_f32 v11, v22, s0
	v_lshl_add_u64 v[26:27], v[96:97], 0, v[26:27]
	v_add_f32_e32 v102, -1.0, v104
	global_store_short v[24:25], v11, off offset:128 nt
	global_store_short v[26:27], v103, off nt
	ds_read_u16 v11, v140 offset:23296
	ds_read_u16 v20, v140 offset:23696
	ds_read_u16 v23, v140 offset:23424
	ds_read_u16 v24, v140 offset:23824
	ds_read_u16 v105, v140 offset:23952
	ds_read_u16 v107, v140 offset:23552
	s_waitcnt lgkmcnt(4)
	v_lshlrev_b32_e32 v20, 16, v20
	v_lshlrev_b32_e32 v11, 16, v11
	v_sub_f32_e32 v11, v11, v20
	s_waitcnt lgkmcnt(2)
	v_lshlrev_b32_e32 v25, 16, v24
	v_lshlrev_b32_e32 v24, 16, v23
	v_fmac_f32_e32 v20, v127, v11
	v_mov_b32_e32 v11, v24
	v_pk_add_f32 v[26:27], v[10:11], v[24:25] neg_lo:[0,1] neg_hi:[0,1]
	v_mov_b32_e32 v161, v25
	v_mov_b32_e32 v103, v27
	v_pk_fma_f32 v[24:25], v[94:95], v[102:103], v[160:161]
	s_waitcnt lgkmcnt(0)
	v_lshlrev_b32_e32 v11, 16, v107
	v_pk_mul_f32 v[26:27], v[24:25], v[24:25] op_sel:[0,1] op_sel_hi:[1,0]
	s_nop 0
	v_mov_b32_e32 v27, v22
	v_pk_mul_f32 v[22:23], v[20:21], v[26:27]
	v_lshlrev_b32_e32 v21, 16, v105
	v_sub_f32_e32 v11, v11, v21
	v_fmac_f32_e32 v21, v126, v11
	v_mul_f32_e32 v11, v125, v25
	v_mul_f32_e32 v27, v118, v11
	v_ashrrev_i32_e32 v11, 31, v10
	v_pk_fma_f32 v[72:73], v[0:1], v[22:23], v[72:73] op_sel_hi:[0,1,1]
	v_lshl_add_u64 v[22:23], v[10:11], 4, v[86:87]
	v_lshlrev_b64 v[24:25], 8, v[22:23]
	v_lshlrev_b64 v[22:23], 9, v[22:23]
	v_lshl_add_u64 v[22:23], v[98:99], 0, v[22:23]
	v_cvt_pk_bf16_f32 v20, v20, s0
	global_store_short v[22:23], v20, off nt
	v_cvt_pk_bf16_f32 v20, v26, s0
	v_mul_f32_e32 v102, v104, v27
	global_store_short v[22:23], v20, off offset:128 nt
	v_cvt_pk_bf16_f32 v20, v27, s0
	global_store_short v[22:23], v20, off offset:256 nt
	v_cvt_pk_bf16_f32 v20, v102, s0
	global_store_short v[22:23], v20, off offset:384 nt
	v_cvt_pk_bf16_f32 v22, v21, s0
	v_lshlrev_b64 v[20:21], 11, v[10:11]
	v_lshl_add_u64 v[24:25], v[100:101], 0, v[24:25]
	v_lshl_add_u64 v[20:21], v[96:97], 0, v[20:21]
	global_store_dword v[24:25], v106, off nt
	global_store_short v[20:21], v22, off nt
	ds_read_u16 v21, v140 offset:24096
	ds_read_u16 v22, v140 offset:23696
	ds_read_u16 v24, v140 offset:24224
	ds_read_u16 v25, v140 offset:24352
	ds_read_u16 v26, v140 offset:23952
	v_add_f32_e32 v28, v129, v28
	s_waitcnt lgkmcnt(4)
	v_lshlrev_b32_e32 v23, 16, v21
	ds_read_u16 v21, v140 offset:23824
	s_waitcnt lgkmcnt(2)
	v_lshlrev_b32_e32 v104, 16, v25
	v_mul_f32_e64 v25, |v28|, s3
	s_waitcnt lgkmcnt(1)
	v_lshlrev_b32_e32 v102, 16, v26
	v_exp_f32_e32 v26, v25
	v_lshlrev_b32_e32 v25, 16, v24
	s_waitcnt lgkmcnt(0)
	v_lshlrev_b32_e32 v24, 16, v21
	v_add_u32_e32 v20, 18, v92
	v_add_f32_e32 v26, 1.0, v26
	v_cmp_gt_f32_e32 vcc, s5, v26
	v_mov_b32_e32 v21, v24
	v_add_f32_e32 v12, v12, v128
	v_cndmask_b32_e64 v27, 0, 32, vcc
	v_ldexp_f32 v26, v26, v27
	v_log_f32_e32 v103, v26
	v_pk_add_f32 v[26:27], v[20:21], v[24:25] neg_lo:[0,1] neg_hi:[0,1]
	v_mul_f32_e32 v12, 0xbfb8aa3b, v12
	v_max_f32_e64 v24, -v28, 0
	v_mul_f32_e32 v26, 0x3f317217, v103
	v_fma_f32 v26, v103, s33, -v26
	v_fmac_f32_e32 v26, 0x3377d1cf, v103
	v_fmac_f32_e32 v26, 0x3f317217, v103
	v_cmp_lt_f32_e64 s[0:1], |v103|, s14
	v_cndmask_b32_e32 v28, 0, v219, vcc
	v_exp_f32_e32 v12, v12
	v_cndmask_b32_e64 v26, v103, v26, s[0:1]
	v_sub_f32_e32 v26, v26, v28
	v_add_f32_e32 v24, v24, v26
	v_sub_f32_e32 v24, -0.5, v24
	v_mul_f32_e32 v24, 0x3fb8aa3b, v24
	v_add_f32_e32 v12, 1.0, v12
	v_exp_f32_e32 v24, v24
	v_div_scale_f32 v26, s[0:1], v12, v12, 1.0
	v_rcp_f32_e32 v28, v26
	v_sub_f32_e32 v21, v102, v104
	v_fmac_f32_e32 v104, v126, v21
	v_mul_f32_e32 v21, 0xbfb8aa3b, v24
	v_exp_f32_e32 v105, v21
	v_fma_f32 v21, -v26, v28, 1.0
	v_fmac_f32_e32 v28, v21, v28
	v_div_scale_f32 v21, vcc, 1.0, v12, 1.0
	v_mul_f32_e32 v24, v21, v28
	v_fma_f32 v102, -v26, v24, v21
	v_fmac_f32_e32 v24, v102, v28
	v_fma_f32 v21, -v26, v24, v21
	v_div_fmas_f32 v21, v21, v28, v24
	v_div_fixup_f32 v12, v21, v12, 1.0
	v_add_f32_e32 v26, -1.0, v12
	v_mov_b32_e32 v161, v25
	v_pk_fma_f32 v[24:25], v[94:95], v[26:27], v[160:161]
	v_add_f32_e32 v13, v13, v128
	v_mul_f32_e32 v21, v125, v25
	v_mul_f32_e32 v28, v119, v21
	v_ashrrev_i32_e32 v21, 31, v20
	v_lshl_add_u64 v[26:27], v[20:21], 4, v[86:87]
	v_lshlrev_b64 v[102:103], 8, v[26:27]
	v_lshl_add_u64 v[102:103], v[100:101], 0, v[102:103]
	v_lshlrev_b64 v[26:27], 9, v[26:27]
	v_mul_f32_e32 v12, v12, v28
	global_store_dword v[102:103], v105, off nt
	v_lshl_add_u64 v[26:27], v[98:99], 0, v[26:27]
	v_cvt_pk_bf16_f32 v28, v28, s0
	v_add_f32_e32 v102, v129, v29
	global_store_short v[26:27], v28, off offset:256 nt
	v_mul_f32_e64 v28, |v102|, s3
	v_exp_f32_e32 v28, v28
	v_cvt_pk_bf16_f32 v12, v12, s0
	global_store_short v[26:27], v12, off offset:384 nt
	v_cvt_pk_bf16_f32 v103, v104, s0
	v_add_f32_e32 v12, 1.0, v28
	v_cmp_gt_f32_e32 vcc, s5, v12
	v_mul_f32_e32 v13, 0xbfb8aa3b, v13
	v_exp_f32_e32 v13, v13
	v_cndmask_b32_e64 v28, 0, 32, vcc
	v_ldexp_f32 v12, v12, v28
	v_log_f32_e32 v12, v12
	v_max_f32_e64 v102, -v102, 0
	v_add_f32_e32 v13, 1.0, v13
	v_lshlrev_b32_e32 v22, 16, v22
	v_mul_f32_e32 v104, 0x3f317217, v12
	v_fma_f32 v104, v12, s33, -v104
	v_fmac_f32_e32 v104, 0x3377d1cf, v12
	v_fmac_f32_e32 v104, 0x3f317217, v12
	v_cmp_lt_f32_e64 s[0:1], |v12|, s14
	v_sub_f32_e32 v22, v22, v23
	v_fmac_f32_e32 v23, v127, v22
	v_cndmask_b32_e64 v12, v12, v104, s[0:1]
	v_cndmask_b32_e32 v104, 0, v219, vcc
	v_sub_f32_e32 v12, v12, v104
	v_add_f32_e32 v12, v102, v12
	v_sub_f32_e32 v12, -0.5, v12
	v_mul_f32_e32 v12, 0x3fb8aa3b, v12
	v_exp_f32_e32 v102, v12
	v_div_scale_f32 v104, s[0:1], v13, v13, 1.0
	v_rcp_f32_e32 v105, v104
	v_mul_f32_e32 v102, 0xbfb8aa3b, v102
	v_exp_f32_e32 v106, v102
	v_pk_mul_f32 v[24:25], v[24:25], v[24:25] op_sel:[0,1] op_sel_hi:[1,0]
	v_fma_f32 v102, -v104, v105, 1.0
	v_fmac_f32_e32 v105, v102, v105
	v_div_scale_f32 v102, vcc, 1.0, v13, 1.0
	v_mul_f32_e32 v107, v102, v105
	v_fma_f32 v108, -v104, v107, v102
	v_fmac_f32_e32 v107, v108, v105
	v_fma_f32 v102, -v104, v107, v102
	v_div_fmas_f32 v102, v102, v105, v107
	v_div_fixup_f32 v104, v102, v13, 1.0
	v_cvt_pk_bf16_f32 v13, v23, s0
	v_lshlrev_b64 v[28:29], 11, v[20:21]
	v_add_u32_e32 v12, 19, v92
	global_store_short v[26:27], v13, off nt
	v_cvt_pk_bf16_f32 v13, v24, s0
	v_lshl_add_u64 v[28:29], v[96:97], 0, v[28:29]
	v_add_f32_e32 v102, -1.0, v104
	global_store_short v[26:27], v13, off offset:128 nt
	global_store_short v[28:29], v103, off nt
	ds_read_u16 v13, v140 offset:24096
	ds_read_u16 v22, v140 offset:24496
	ds_read_u16 v25, v140 offset:24224
	ds_read_u16 v26, v140 offset:24624
	ds_read_u16 v105, v140 offset:24752
	ds_read_u16 v107, v140 offset:24352
	s_waitcnt lgkmcnt(4)
	v_lshlrev_b32_e32 v22, 16, v22
	v_lshlrev_b32_e32 v13, 16, v13
	v_sub_f32_e32 v13, v13, v22
	s_waitcnt lgkmcnt(2)
	v_lshlrev_b32_e32 v27, 16, v26
	v_lshlrev_b32_e32 v26, 16, v25
	v_fmac_f32_e32 v22, v127, v13
	v_mov_b32_e32 v13, v26
	v_pk_add_f32 v[28:29], v[12:13], v[26:27] neg_lo:[0,1] neg_hi:[0,1]
	v_mov_b32_e32 v161, v27
	v_mov_b32_e32 v103, v29
	v_pk_fma_f32 v[26:27], v[94:95], v[102:103], v[160:161]
	s_waitcnt lgkmcnt(0)
	v_lshlrev_b32_e32 v13, 16, v107
	v_pk_mul_f32 v[28:29], v[26:27], v[26:27] op_sel:[0,1] op_sel_hi:[1,0]
	s_nop 0
	v_mov_b32_e32 v29, v24
	v_pk_mul_f32 v[24:25], v[22:23], v[28:29]
	v_lshlrev_b32_e32 v23, 16, v105
	v_sub_f32_e32 v13, v13, v23
	v_fmac_f32_e32 v23, v126, v13
	v_mul_f32_e32 v13, v125, v27
	v_mul_f32_e32 v29, v120, v13
	v_ashrrev_i32_e32 v13, 31, v12
	v_pk_fma_f32 v[70:71], v[0:1], v[24:25], v[70:71] op_sel_hi:[0,1,1]
	v_lshl_add_u64 v[24:25], v[12:13], 4, v[86:87]
	v_lshlrev_b64 v[26:27], 8, v[24:25]
	v_lshlrev_b64 v[24:25], 9, v[24:25]
	v_lshl_add_u64 v[24:25], v[98:99], 0, v[24:25]
	v_cvt_pk_bf16_f32 v22, v22, s0
	global_store_short v[24:25], v22, off nt
	v_cvt_pk_bf16_f32 v22, v28, s0
	v_mul_f32_e32 v102, v104, v29
	global_store_short v[24:25], v22, off offset:128 nt
	v_cvt_pk_bf16_f32 v22, v29, s0
	global_store_short v[24:25], v22, off offset:256 nt
	v_cvt_pk_bf16_f32 v22, v102, s0
	global_store_short v[24:25], v22, off offset:384 nt
	v_cvt_pk_bf16_f32 v24, v23, s0
	v_lshlrev_b64 v[22:23], 11, v[12:13]
	v_lshl_add_u64 v[26:27], v[100:101], 0, v[26:27]
	v_lshl_add_u64 v[22:23], v[96:97], 0, v[22:23]
	global_store_dword v[26:27], v106, off nt
	global_store_short v[22:23], v24, off nt
	ds_read_u16 v23, v140 offset:26496
	ds_read_u16 v24, v140 offset:26096
	ds_read_u16 v26, v140 offset:26624
	ds_read_u16 v27, v140 offset:26752
	ds_read_u16 v28, v140 offset:26352
	v_add_f32_e32 v30, v129, v30
	s_waitcnt lgkmcnt(4)
	v_lshlrev_b32_e32 v25, 16, v23
	ds_read_u16 v23, v140 offset:26224
	s_waitcnt lgkmcnt(2)
	v_lshlrev_b32_e32 v104, 16, v27
	v_mul_f32_e64 v27, |v30|, s3
	s_waitcnt lgkmcnt(1)
	v_lshlrev_b32_e32 v102, 16, v28
	v_exp_f32_e32 v28, v27
	v_lshlrev_b32_e32 v27, 16, v26
	s_waitcnt lgkmcnt(0)
	v_lshlrev_b32_e32 v26, 16, v23
	v_add_u32_e32 v22, 24, v92
	v_add_f32_e32 v28, 1.0, v28
	v_cmp_gt_f32_e32 vcc, s5, v28
	v_mov_b32_e32 v23, v26
	v_add_f32_e32 v14, v14, v128
	v_cndmask_b32_e64 v29, 0, 32, vcc
	v_ldexp_f32 v28, v28, v29
	v_log_f32_e32 v103, v28
	v_pk_add_f32 v[28:29], v[22:23], v[26:27] neg_lo:[0,1] neg_hi:[0,1]
	v_mul_f32_e32 v14, 0xbfb8aa3b, v14
	v_max_f32_e64 v26, -v30, 0
	v_mul_f32_e32 v28, 0x3f317217, v103
	v_fma_f32 v28, v103, s33, -v28
	v_fmac_f32_e32 v28, 0x3377d1cf, v103
	v_fmac_f32_e32 v28, 0x3f317217, v103
	v_cmp_lt_f32_e64 s[0:1], |v103|, s14
	v_cndmask_b32_e32 v30, 0, v219, vcc
	v_exp_f32_e32 v14, v14
	v_cndmask_b32_e64 v28, v103, v28, s[0:1]
	v_sub_f32_e32 v28, v28, v30
	v_add_f32_e32 v26, v26, v28
	v_sub_f32_e32 v26, -0.5, v26
	v_mul_f32_e32 v26, 0x3fb8aa3b, v26
	v_add_f32_e32 v14, 1.0, v14
	v_exp_f32_e32 v26, v26
	v_div_scale_f32 v28, s[0:1], v14, v14, 1.0
	v_rcp_f32_e32 v30, v28
	v_sub_f32_e32 v23, v102, v104
	v_fmac_f32_e32 v104, v126, v23
	v_mul_f32_e32 v23, 0xbfb8aa3b, v26
	v_exp_f32_e32 v105, v23
	v_fma_f32 v23, -v28, v30, 1.0
	v_fmac_f32_e32 v30, v23, v30
	v_div_scale_f32 v23, vcc, 1.0, v14, 1.0
	v_mul_f32_e32 v26, v23, v30
	v_fma_f32 v102, -v28, v26, v23
	v_fmac_f32_e32 v26, v102, v30
	v_fma_f32 v23, -v28, v26, v23
	v_div_fmas_f32 v23, v23, v30, v26
	v_div_fixup_f32 v14, v23, v14, 1.0
	v_add_f32_e32 v28, -1.0, v14
	v_mov_b32_e32 v161, v27
	v_pk_fma_f32 v[26:27], v[94:95], v[28:29], v[160:161]
	v_add_f32_e32 v15, v15, v128
	v_mul_f32_e32 v23, v125, v27
	v_mul_f32_e32 v30, v121, v23
	v_ashrrev_i32_e32 v23, 31, v22
	v_lshl_add_u64 v[28:29], v[22:23], 4, v[86:87]
	v_lshlrev_b64 v[102:103], 8, v[28:29]
	v_lshl_add_u64 v[102:103], v[100:101], 0, v[102:103]
	v_lshlrev_b64 v[28:29], 9, v[28:29]
	v_mul_f32_e32 v14, v14, v30
	global_store_dword v[102:103], v105, off nt
	v_lshl_add_u64 v[28:29], v[98:99], 0, v[28:29]
	v_cvt_pk_bf16_f32 v30, v30, s0
	v_add_f32_e32 v102, v129, v31
	global_store_short v[28:29], v30, off offset:256 nt
	v_mul_f32_e64 v30, |v102|, s3
	v_exp_f32_e32 v30, v30
	v_cvt_pk_bf16_f32 v14, v14, s0
	global_store_short v[28:29], v14, off offset:384 nt
	v_cvt_pk_bf16_f32 v103, v104, s0
	v_add_f32_e32 v14, 1.0, v30
	v_cmp_gt_f32_e32 vcc, s5, v14
	v_mul_f32_e32 v15, 0xbfb8aa3b, v15
	v_exp_f32_e32 v15, v15
	v_cndmask_b32_e64 v30, 0, 32, vcc
	v_ldexp_f32 v14, v14, v30
	v_log_f32_e32 v14, v14
	v_max_f32_e64 v102, -v102, 0
	v_add_f32_e32 v15, 1.0, v15
	v_lshlrev_b32_e32 v24, 16, v24
	v_mul_f32_e32 v104, 0x3f317217, v14
	v_fma_f32 v104, v14, s33, -v104
	v_fmac_f32_e32 v104, 0x3377d1cf, v14
	v_fmac_f32_e32 v104, 0x3f317217, v14
	v_cmp_lt_f32_e64 s[0:1], |v14|, s14
	v_sub_f32_e32 v24, v24, v25
	v_fmac_f32_e32 v25, v127, v24
	v_cndmask_b32_e64 v14, v14, v104, s[0:1]
	v_cndmask_b32_e32 v104, 0, v219, vcc
	v_sub_f32_e32 v14, v14, v104
	v_add_f32_e32 v14, v102, v14
	v_sub_f32_e32 v14, -0.5, v14
	v_mul_f32_e32 v14, 0x3fb8aa3b, v14
	v_exp_f32_e32 v102, v14
	v_div_scale_f32 v104, s[0:1], v15, v15, 1.0
	v_rcp_f32_e32 v105, v104
	v_mul_f32_e32 v102, 0xbfb8aa3b, v102
	v_exp_f32_e32 v106, v102
	v_pk_mul_f32 v[26:27], v[26:27], v[26:27] op_sel:[0,1] op_sel_hi:[1,0]
	v_fma_f32 v102, -v104, v105, 1.0
	v_fmac_f32_e32 v105, v102, v105
	v_div_scale_f32 v102, vcc, 1.0, v15, 1.0
	v_mul_f32_e32 v107, v102, v105
	v_fma_f32 v108, -v104, v107, v102
	v_fmac_f32_e32 v107, v108, v105
	v_fma_f32 v102, -v104, v107, v102
	v_div_fmas_f32 v102, v102, v105, v107
	v_div_fixup_f32 v104, v102, v15, 1.0
	v_cvt_pk_bf16_f32 v15, v25, s0
	v_lshlrev_b64 v[30:31], 11, v[22:23]
	v_add_u32_e32 v14, 25, v92
	global_store_short v[28:29], v15, off nt
	v_cvt_pk_bf16_f32 v15, v26, s0
	v_lshl_add_u64 v[30:31], v[96:97], 0, v[30:31]
	v_add_f32_e32 v102, -1.0, v104
	global_store_short v[28:29], v15, off offset:128 nt
	global_store_short v[30:31], v103, off nt
	ds_read_u16 v15, v140 offset:26496
	ds_read_u16 v24, v140 offset:26896
	ds_read_u16 v27, v140 offset:26624
	ds_read_u16 v28, v140 offset:27024
	ds_read_u16 v105, v140 offset:27152
	ds_read_u16 v107, v140 offset:26752
	s_waitcnt lgkmcnt(4)
	v_lshlrev_b32_e32 v24, 16, v24
	v_lshlrev_b32_e32 v15, 16, v15
	v_sub_f32_e32 v15, v15, v24
	s_waitcnt lgkmcnt(2)
	v_lshlrev_b32_e32 v29, 16, v28
	v_lshlrev_b32_e32 v28, 16, v27
	v_fmac_f32_e32 v24, v127, v15
	v_mov_b32_e32 v15, v28
	v_pk_add_f32 v[30:31], v[14:15], v[28:29] neg_lo:[0,1] neg_hi:[0,1]
	v_mov_b32_e32 v161, v29
	v_mov_b32_e32 v103, v31
	v_pk_fma_f32 v[28:29], v[94:95], v[102:103], v[160:161]
	s_waitcnt lgkmcnt(0)
	v_lshlrev_b32_e32 v15, 16, v107
	v_pk_mul_f32 v[30:31], v[28:29], v[28:29] op_sel:[0,1] op_sel_hi:[1,0]
	s_nop 0
	v_mov_b32_e32 v31, v26
	v_pk_mul_f32 v[26:27], v[24:25], v[30:31]
	v_lshlrev_b32_e32 v25, 16, v105
	v_sub_f32_e32 v15, v15, v25
	v_fmac_f32_e32 v25, v126, v15
	v_mul_f32_e32 v15, v125, v29
	v_mul_f32_e32 v31, v122, v15
	v_ashrrev_i32_e32 v15, 31, v14
	v_pk_fma_f32 v[68:69], v[0:1], v[26:27], v[68:69] op_sel_hi:[0,1,1]
	v_lshl_add_u64 v[26:27], v[14:15], 4, v[86:87]
	v_lshlrev_b64 v[28:29], 8, v[26:27]
	v_lshlrev_b64 v[26:27], 9, v[26:27]
	v_lshl_add_u64 v[26:27], v[98:99], 0, v[26:27]
	v_cvt_pk_bf16_f32 v24, v24, s0
	global_store_short v[26:27], v24, off nt
	v_cvt_pk_bf16_f32 v24, v30, s0
	v_mul_f32_e32 v102, v104, v31
	global_store_short v[26:27], v24, off offset:128 nt
	v_cvt_pk_bf16_f32 v24, v31, s0
	global_store_short v[26:27], v24, off offset:256 nt
	v_cvt_pk_bf16_f32 v24, v102, s0
	global_store_short v[26:27], v24, off offset:384 nt
	v_cvt_pk_bf16_f32 v26, v25, s0
	v_lshlrev_b64 v[24:25], 11, v[14:15]
	v_lshl_add_u64 v[28:29], v[100:101], 0, v[28:29]
	v_lshl_add_u64 v[24:25], v[96:97], 0, v[24:25]
	global_store_dword v[28:29], v106, off nt
	global_store_short v[24:25], v26, off nt
	ds_read_u16 v25, v140 offset:27296
	ds_read_u16 v26, v140 offset:26896
	ds_read_u16 v28, v140 offset:27424
	ds_read_u16 v29, v140 offset:27552
	ds_read_u16 v30, v140 offset:27152
	v_add_f32_e32 v32, v129, v32
	s_waitcnt lgkmcnt(4)
	v_lshlrev_b32_e32 v27, 16, v25
	ds_read_u16 v25, v140 offset:27024
	s_waitcnt lgkmcnt(2)
	v_lshlrev_b32_e32 v104, 16, v29
	v_mul_f32_e64 v29, |v32|, s3
	s_waitcnt lgkmcnt(1)
	v_lshlrev_b32_e32 v102, 16, v30
	v_exp_f32_e32 v30, v29
	v_lshlrev_b32_e32 v29, 16, v28
	s_waitcnt lgkmcnt(0)
	v_lshlrev_b32_e32 v28, 16, v25
	v_add_u32_e32 v24, 26, v92
	v_add_f32_e32 v30, 1.0, v30
	v_cmp_gt_f32_e32 vcc, s5, v30
	v_mov_b32_e32 v25, v28
	v_add_f32_e32 v16, v16, v128
	v_cndmask_b32_e64 v31, 0, 32, vcc
	v_ldexp_f32 v30, v30, v31
	v_log_f32_e32 v103, v30
	v_pk_add_f32 v[30:31], v[24:25], v[28:29] neg_lo:[0,1] neg_hi:[0,1]
	v_mul_f32_e32 v16, 0xbfb8aa3b, v16
	v_max_f32_e64 v28, -v32, 0
	v_mul_f32_e32 v30, 0x3f317217, v103
	v_fma_f32 v30, v103, s33, -v30
	v_fmac_f32_e32 v30, 0x3377d1cf, v103
	v_fmac_f32_e32 v30, 0x3f317217, v103
	v_cmp_lt_f32_e64 s[0:1], |v103|, s14
	v_cndmask_b32_e32 v32, 0, v219, vcc
	v_exp_f32_e32 v16, v16
	v_cndmask_b32_e64 v30, v103, v30, s[0:1]
	v_sub_f32_e32 v30, v30, v32
	v_add_f32_e32 v28, v28, v30
	v_sub_f32_e32 v28, -0.5, v28
	v_mul_f32_e32 v28, 0x3fb8aa3b, v28
	v_add_f32_e32 v16, 1.0, v16
	v_exp_f32_e32 v28, v28
	v_div_scale_f32 v30, s[0:1], v16, v16, 1.0
	v_rcp_f32_e32 v32, v30
	v_sub_f32_e32 v25, v102, v104
	v_fmac_f32_e32 v104, v126, v25
	v_mul_f32_e32 v25, 0xbfb8aa3b, v28
	v_exp_f32_e32 v105, v25
	v_fma_f32 v25, -v30, v32, 1.0
	v_fmac_f32_e32 v32, v25, v32
	v_div_scale_f32 v25, vcc, 1.0, v16, 1.0
	v_mul_f32_e32 v28, v25, v32
	v_fma_f32 v102, -v30, v28, v25
	v_fmac_f32_e32 v28, v102, v32
	v_fma_f32 v25, -v30, v28, v25
	v_div_fmas_f32 v25, v25, v32, v28
	v_div_fixup_f32 v16, v25, v16, 1.0
	v_add_f32_e32 v30, -1.0, v16
	v_mov_b32_e32 v161, v29
	v_pk_fma_f32 v[28:29], v[94:95], v[30:31], v[160:161]
	v_add_f32_e32 v17, v17, v128
	v_mul_f32_e32 v25, v125, v29
	v_mul_f32_e32 v32, v123, v25
	v_ashrrev_i32_e32 v25, 31, v24
	v_lshl_add_u64 v[30:31], v[24:25], 4, v[86:87]
	v_lshlrev_b64 v[102:103], 8, v[30:31]
	v_lshl_add_u64 v[102:103], v[100:101], 0, v[102:103]
	v_lshlrev_b64 v[30:31], 9, v[30:31]
	v_mul_f32_e32 v16, v16, v32
	global_store_dword v[102:103], v105, off nt
	v_lshl_add_u64 v[30:31], v[98:99], 0, v[30:31]
	v_cvt_pk_bf16_f32 v32, v32, s0
	v_add_f32_e32 v102, v129, v33
	global_store_short v[30:31], v32, off offset:256 nt
	v_mul_f32_e64 v32, |v102|, s3
	v_exp_f32_e32 v32, v32
	v_cvt_pk_bf16_f32 v16, v16, s0
	global_store_short v[30:31], v16, off offset:384 nt
	v_cvt_pk_bf16_f32 v103, v104, s0
	v_add_f32_e32 v16, 1.0, v32
	v_cmp_gt_f32_e32 vcc, s5, v16
	v_mul_f32_e32 v17, 0xbfb8aa3b, v17
	v_exp_f32_e32 v17, v17
	v_cndmask_b32_e64 v32, 0, 32, vcc
	v_ldexp_f32 v16, v16, v32
	v_log_f32_e32 v16, v16
	v_max_f32_e64 v102, -v102, 0
	v_add_f32_e32 v17, 1.0, v17
	v_lshlrev_b32_e32 v26, 16, v26
	v_mul_f32_e32 v104, 0x3f317217, v16
	v_fma_f32 v104, v16, s33, -v104
	v_fmac_f32_e32 v104, 0x3377d1cf, v16
	v_fmac_f32_e32 v104, 0x3f317217, v16
	v_cmp_lt_f32_e64 s[0:1], |v16|, s14
	v_sub_f32_e32 v26, v26, v27
	v_fmac_f32_e32 v27, v127, v26
	v_cndmask_b32_e64 v16, v16, v104, s[0:1]
	v_cndmask_b32_e32 v104, 0, v219, vcc
	v_sub_f32_e32 v16, v16, v104
	v_add_f32_e32 v16, v102, v16
	v_sub_f32_e32 v16, -0.5, v16
	v_mul_f32_e32 v16, 0x3fb8aa3b, v16
	v_exp_f32_e32 v102, v16
	v_div_scale_f32 v104, s[0:1], v17, v17, 1.0
	v_rcp_f32_e32 v105, v104
	v_mul_f32_e32 v102, 0xbfb8aa3b, v102
	v_exp_f32_e32 v106, v102
	v_pk_mul_f32 v[28:29], v[28:29], v[28:29] op_sel:[0,1] op_sel_hi:[1,0]
	v_fma_f32 v102, -v104, v105, 1.0
	v_fmac_f32_e32 v105, v102, v105
	v_div_scale_f32 v102, vcc, 1.0, v17, 1.0
	v_mul_f32_e32 v107, v102, v105
	v_fma_f32 v108, -v104, v107, v102
	v_fmac_f32_e32 v107, v108, v105
	v_fma_f32 v102, -v104, v107, v102
	v_div_fmas_f32 v102, v102, v105, v107
	v_div_fixup_f32 v104, v102, v17, 1.0
	v_cvt_pk_bf16_f32 v17, v27, s0
	v_lshlrev_b64 v[32:33], 11, v[24:25]
	v_add_u32_e32 v16, 27, v92
	global_store_short v[30:31], v17, off nt
	v_cvt_pk_bf16_f32 v17, v28, s0
	v_lshl_add_u64 v[32:33], v[96:97], 0, v[32:33]
	v_add_f32_e32 v102, -1.0, v104
	global_store_short v[30:31], v17, off offset:128 nt
	global_store_short v[32:33], v103, off nt
	ds_read_u16 v17, v140 offset:27296
	ds_read_u16 v26, v140 offset:27696
	s_waitcnt lgkmcnt(1)
	v_lshlrev_b32_e32 v17, 16, v17
	s_waitcnt lgkmcnt(0)
	v_lshlrev_b32_e32 v26, 16, v26
	v_sub_f32_e32 v17, v17, v26
	v_fmac_f32_e32 v26, v127, v17
	ds_read_u16 v17, v140 offset:27424
	ds_read_u16 v29, v140 offset:27824
	s_waitcnt lgkmcnt(1)
	v_lshlrev_b32_e32 v30, 16, v17
	s_waitcnt lgkmcnt(0)
	v_lshlrev_b32_e32 v31, 16, v29
	v_mov_b32_e32 v17, v30
	v_pk_add_f32 v[32:33], v[16:17], v[30:31] neg_lo:[0,1] neg_hi:[0,1]
	v_mov_b32_e32 v161, v31
	v_mov_b32_e32 v103, v33
	v_pk_fma_f32 v[30:31], v[94:95], v[102:103], v[160:161]
	ds_read_u16 v17, v140 offset:27552
	v_pk_mul_f32 v[32:33], v[30:31], v[30:31] op_sel:[0,1] op_sel_hi:[1,0]
	s_nop 0
	v_mov_b32_e32 v33, v28
	v_pk_mul_f32 v[28:29], v[26:27], v[32:33]
	ds_read_u16 v27, v140 offset:27952
	s_waitcnt lgkmcnt(1)
	v_lshlrev_b32_e32 v17, 16, v17
	v_pk_fma_f32 v[66:67], v[0:1], v[28:29], v[66:67] op_sel_hi:[0,1,1]
	v_cvt_pk_bf16_f32 v0, v26, s0
	s_waitcnt lgkmcnt(0)
	v_lshlrev_b32_e32 v27, 16, v27
	v_sub_f32_e32 v17, v17, v27
	v_fmac_f32_e32 v27, v126, v17
	v_mul_f32_e32 v17, v125, v31
	v_mul_f32_e32 v33, v124, v17
	v_ashrrev_i32_e32 v17, 31, v16
	v_lshl_add_u64 v[28:29], v[16:17], 4, v[86:87]
	v_lshlrev_b64 v[30:31], 8, v[28:29]
	v_lshlrev_b64 v[28:29], 9, v[28:29]
	v_lshl_add_u64 v[28:29], v[98:99], 0, v[28:29]
	global_store_short v[28:29], v0, off nt
	v_cvt_pk_bf16_f32 v0, v32, s0
	v_mul_f32_e32 v94, v104, v33
	global_store_short v[28:29], v0, off offset:128 nt
	v_cvt_pk_bf16_f32 v0, v33, s0
	global_store_short v[28:29], v0, off offset:256 nt
	v_cvt_pk_bf16_f32 v0, v94, s0
	global_store_short v[28:29], v0, off offset:384 nt
	v_cvt_pk_bf16_f32 v0, v27, s0
	v_lshlrev_b64 v[26:27], 11, v[16:17]
	v_lshl_add_u64 v[30:31], v[100:101], 0, v[30:31]
	v_lshl_add_u64 v[26:27], v[96:97], 0, v[26:27]
	global_store_dword v[30:31], v106, off nt
	global_store_short v[26:27], v0, off nt
	s_andn2_b64 vcc, exec, s[46:47]
	s_mov_b64 s[46:47], 0
	s_cbranch_vccz .LBB0_732
	v_add_f32_dpp v0, v81, v81 row_ror:8 row_mask:0xf bank_mask:0xf bound_ctrl:1
	v_readlane_b32 s0, v250, 26
	v_readlane_b32 s1, v250, 27
	v_add_f32_dpp v0, v0, v0 row_ror:4 row_mask:0xf bank_mask:0xf bound_ctrl:1
	v_cmp_eq_u32_e32 vcc, 0, v88
	v_lshl_add_u64 v[26:27], v[86:87], 2, s[0:1]
	v_add_f32_dpp v0, v0, v0 row_ror:2 row_mask:0xf bank_mask:0xf bound_ctrl:1
	s_nop 1
	v_add_f32_dpp v0, v0, v0 row_ror:1 row_mask:0xf bank_mask:0xf bound_ctrl:1
	ds_bpermute_b32 v28, v89, v0
	s_and_saveexec_b64 s[0:1], vcc
	s_mov_b32 s88, s18
	s_mov_b64 s[90:91], s[38:39]
	v_readlane_b32 s18, v255, 21
	v_readlane_b32 s19, v255, 22
	s_cbranch_execz .LBB0_735
	v_lshlrev_b64 v[30:31], 6, v[92:93]
	v_lshl_add_u64 v[30:31], v[26:27], 0, v[30:31]
	s_waitcnt lgkmcnt(0)
	v_add_f32_e32 v0, v0, v28
	global_store_dword v[30:31], v0, off

.Lp0_skip:
	v_readlane_b32 s0, v254, 32
	v_add_u32_e32 v54, s56, v54
	v_add_u32_e32 v70, s56, v70
	v_add_u32_e32 v20, s0, v20
	v_add_u32_e32 v24, s0, v24
	v_add_u32_e32 v69, s0, v69
	s_movk_i32 s0, 0x637f
	v_cmp_lt_i32_e32 vcc, s0, v54
	s_or_b64 s[40:41], vcc, s[40:41]
	v_add_u32_e32 v71, s56, v71
	s_andn2_b64 exec, exec, s[40:41]
	s_cbranch_execz .LBB0_886
.LBB0_848:
	v_readfirstlane_b32 s0, v54
	s_sub_u32 s0, s0, 0x1900
	s_cmp_lt_u32 s0, 0x4a00
	s_cbranch_scc1 .Lp0_skip
	s_movk_i32 s0, 0x18ff
	v_cmp_lt_i32_e32 vcc, s0, v54
	s_and_saveexec_b64 s[0:1], vcc
	s_xor_b64 s[42:43], exec, s[0:1]
	s_cbranch_execz .LBB0_882
	v_lshlrev_b32_e32 v0, 2, v69
	s_movk_i32 s0, 0x20ff
	v_and_b32_e32 v21, 0x1f80, v0
	v_cmp_lt_u32_e32 vcc, s0, v54
	s_and_saveexec_b64 s[0:1], vcc
	s_xor_b64 s[44:45], exec, s[0:1]
	s_cbranch_execz .LBB0_877
	s_movk_i32 s0, 0x4cff
	v_cmp_lt_u32_e32 vcc, s0, v54
	s_and_saveexec_b64 s[0:1], vcc
	s_xor_b64 s[46:47], exec, s[0:1]
	s_cbranch_execz .LBB0_872
	s_movk_i32 s0, 0x62ff
	v_cmp_lt_u32_e32 vcc, s0, v54
	s_and_saveexec_b64 s[0:1], vcc
	s_xor_b64 s[48:49], exec, s[0:1]
	s_cbranch_execz .LBB0_867
	s_movk_i32 s0, 0x631f
	v_cmp_lt_u32_e32 vcc, s0, v54
	s_and_saveexec_b64 s[0:1], vcc
	s_xor_b64 s[50:51], exec, s[0:1]
	s_cbranch_execz .LBB0_862
	s_movk_i32 s0, 0x633f
	v_cmp_lt_u32_e32 vcc, s0, v54
	s_and_saveexec_b64 s[0:1], vcc
	s_xor_b64 s[0:1], exec, s[0:1]
	s_cbranch_execz .LBB0_857
	v_add_u32_e32 v0, 0xffff9cc0, v54
	v_add_u32_e32 v21, 0xffff9ca0, v54
	v_cmp_gt_u32_e32 vcc, 32, v0
	s_mov_b64 s[12:13], 0
	s_nop 0
	v_cndmask_b32_e32 v25, v21, v0, vcc
	v_cmp_lt_u32_e32 vcc, 31, v0
	v_lshlrev_b32_e32 v34, 5, v25
	v_ashrrev_i32_e32 v35, 31, v34
	v_cndmask_b32_e64 v21, 0, 64, vcc
	v_or_b32_e32 v0, v62, v21
	v_lshlrev_b64 v[50:51], 2, v[34:35]
	v_lshlrev_b32_e32 v0, 12, v0
	v_lshl_add_u64 v[36:37], v[50:51], 0, v[0:1]
	v_or_b32_e32 v0, v63, v21
	v_lshlrev_b32_e32 v0, 12, v0
	v_lshl_add_u64 v[38:39], v[50:51], 0, v[0:1]
	v_or_b32_e32 v0, v64, v21
	v_lshlrev_b32_e32 v0, 12, v0
	v_lshl_add_u64 v[40:41], v[50:51], 0, v[0:1]
	v_or_b32_e32 v0, v65, v21
	v_lshlrev_b32_e32 v0, 12, v0
	v_lshl_add_u64 v[42:43], v[50:51], 0, v[0:1]
	v_or_b32_e32 v0, v66, v21
	v_lshlrev_b32_e32 v0, 12, v0
	v_lshl_add_u64 v[44:45], v[50:51], 0, v[0:1]
	v_or_b32_e32 v0, v67, v21
	v_lshlrev_b32_e32 v0, 12, v0
	v_lshl_add_u64 v[46:47], v[50:51], 0, v[0:1]
	v_or_b32_e32 v0, v68, v21
	v_lshlrev_b32_e32 v0, 12, v0
	v_lshl_add_u64 v[48:49], v[50:51], 0, v[0:1]
	v_or_b32_e32 v0, v55, v21
	v_lshlrev_b32_e32 v0, 12, v0
	v_lshl_add_u64 v[50:51], v[0:1], 0, v[50:51]
	v_lshl_add_u64 v[36:37], v[16:17], 0, v[36:37]
	v_lshl_add_u64 v[38:39], v[16:17], 0, v[38:39]
	v_lshl_add_u64 v[40:41], v[16:17], 0, v[40:41]
	v_lshl_add_u64 v[42:43], v[16:17], 0, v[42:43]
	v_lshl_add_u64 v[44:45], v[16:17], 0, v[44:45]
	v_lshl_add_u64 v[46:47], v[16:17], 0, v[46:47]
	v_lshl_add_u64 v[48:49], v[16:17], 0, v[48:49]
	v_lshl_add_u64 v[50:51], v[16:17], 0, v[50:51]
	v_mov_b32_e32 v0, v61
